# GEMM K-loops: two K-halves of each accumulator issued back to back (accumulate chain), plus P3 q-GEMM rebalance
# speedup vs baseline: 1.0669x; 1.0077x over previous
; #define PG8_STAGE(bufoff, gbase, voff) do { _Pragma("unroll") for (int _i = 0; _i < 2; ++_i) \
;         __builtin_amdgcn_global_load_lds((const unsigned*)((const char*)(gbase) + (voff)[_i]), (LAS unsigned*)(lds + (bufoff) + ldsw + _i * 8192), 16, 0, 0); } while (0)
; #define PG8_LDA(dst, b, h) do { _Pragma("unroll") for (int m = 0; m < 4; ++m) _Pragma("unroll") for (int k = 0; k < 2; ++k) dst[m][k] = *(const LAS bf16x8*)(lds + PG8_SA(b, h) + aoff + m * 2048 + k * 1024); } while (0)
; #define PG8_LDB(dst, b, h) do { _Pragma("unroll") for (int n = 0; n < 2; ++n) _Pragma("unroll") for (int k = 0; k < 2; ++k) dst[n][k] = *(const LAS bf16x8*)(lds + PG8_SB(b, h) + boff + n * 2048 + k * 1024); } while (0)
; #define PG8_MMA(ai, bj, At, Bt) do { __builtin_amdgcn_s_setprio(1); _Pragma("unroll") for (int m = 0; m < 4; ++m) _Pragma("unroll") for (int n = 0; n < 2; ++n) _Pragma("unroll") for (int k = 0; k < 2; ++k) \
;         acc[ai][bj][m][n] = __builtin_amdgcn_mfma_f32_16x16x32_bf16(Bt[n][k], At[m][k], acc[ai][bj][m][n], 0, 0, 0); __builtin_amdgcn_s_setprio(0); } while (0)
; #define PG8_WAIT_V(n) asm volatile("s_waitcnt vmcnt(" #n ")" ::: "memory")
; #define PG8_WAIT_L(n) asm volatile("s_waitcnt lgkmcnt(" #n ")" ::: "memory")
; #define PG8_BAR __builtin_amdgcn_s_barrier()
; #define PG8_SCHED __builtin_amdgcn_sched_barrier(0)
; template <class Epi, bool ALIGN_EPI>
; __device__ __forceinline__ void gemm_phase(LAS unsigned char* lds, const Gemm g, const StaticOrder& S, const Epi& E) {
;     ...
;         for (int t = 0; t < nt; t += 2) {
;             const bool last = (t == nt - 2);
;             const char* a1 = cA + (size_t)(t + 1) * kstep;
;             const char* a2 = last ? nA : cA + (size_t)(t + 2) * kstep; const char* b2 = last ? nB : cB + (size_t)(t + 2) * kstep;
;             const char* a3 = a2 + kstep; const char* b3 = b2 + kstep;
;             PG8_LDB(B0, 0, 0); PG8_LDB(B1, 0, 1); PG8_SCHED; PG8_LDA(At, 0, 0); PG8_STAGE(PG8_SA(1, 1), a1 + hA, voffA);
;             PG8_WAIT_V(8); PG8_WAIT_L(0); PG8_BAR; PG8_MMA(0, 0, At, B0); PG8_MMA(0, 1, At, B1); PG8_BAR; PG8_SCHED;
;             PG8_LDA(At, 0, 1); PG8_STAGE(PG8_SB(0, 0), b2, voffB); PG8_STAGE(PG8_SB(0, 1), b2 + hB, voffB); PG8_STAGE(PG8_SA(0, 0), a2, voffA);
;             PG8_WAIT_V(8); PG8_WAIT_L(0); PG8_BAR; PG8_MMA(1, 0, At, B0); PG8_MMA(1, 1, At, B1); PG8_BAR; PG8_SCHED;
.LBB0_252:
	ds_read_b128 v[168:171], v153
	ds_read_b128 v[172:175], v153 offset:1024
	ds_read_b128 v[176:179], v153 offset:2048
	ds_read_b128 v[180:183], v153 offset:3072
	ds_read_b128 v[184:187], v154
	ds_read_b128 v[188:191], v154 offset:1024
	ds_read_b128 v[194:197], v154 offset:2048
	ds_read_b128 v[198:201], v154 offset:3072
	s_add_u32 s8, s6, 0xfff80080
	s_addc_u32 s9, s7, -1
	s_cmp_eq_u32 s71, 28
	s_cselect_b32 s55, s47, s9
	s_cselect_b32 s54, s67, s8
	s_cselect_b32 s9, s45, s70
	s_cselect_b32 s8, s68, s69
	v_lshl_add_u64 v[234:235], s[6:7], 0, v[136:137]
	s_add_i32 m0, s39, 0xc000
	ds_read_b128 v[202:205], v155
	ds_read_b128 v[206:209], v155 offset:1024
	ds_read_b128 v[210:213], v155 offset:2048
	ds_read_b128 v[214:217], v155 offset:3072
	ds_read_b128 v[218:221], v155 offset:4096
	ds_read_b128 v[222:225], v155 offset:5120
	ds_read_b128 v[226:229], v155 offset:6144
	ds_read_b128 v[230:233], v155 offset:7168
	global_load_lds_dwordx4 v[234:235], off
	v_lshl_add_u64 v[234:235], s[6:7], 0, v[138:139]
	s_add_i32 m0, s39, 0xe000
	s_nop 0
	global_load_lds_dwordx4 v[234:235], off
	s_waitcnt vmcnt(8)
	s_waitcnt lgkmcnt(0)
	s_barrier
	s_setprio 1
	s_waitcnt lgkmcnt(0)
	v_mfma_f32_16x16x32_bf16 v[124:127], v[168:171], v[202:205], v[124:127]
	v_mfma_f32_16x16x32_bf16 v[124:127], v[172:175], v[206:209], v[124:127]
	v_mfma_f32_16x16x32_bf16 v[120:123], v[176:179], v[202:205], v[120:123]
	v_mfma_f32_16x16x32_bf16 v[120:123], v[180:183], v[206:209], v[120:123]
	v_mfma_f32_16x16x32_bf16 v[108:111], v[168:171], v[210:213], v[108:111]
	v_mfma_f32_16x16x32_bf16 v[108:111], v[172:175], v[214:217], v[108:111]
	v_mfma_f32_16x16x32_bf16 v[104:107], v[176:179], v[210:213], v[104:107]
	v_mfma_f32_16x16x32_bf16 v[104:107], v[180:183], v[214:217], v[104:107]
	v_mfma_f32_16x16x32_bf16 v[92:95], v[168:171], v[218:221], v[92:95]
	v_mfma_f32_16x16x32_bf16 v[92:95], v[172:175], v[222:225], v[92:95]
	v_mfma_f32_16x16x32_bf16 v[88:91], v[176:179], v[218:221], v[88:91]
	v_mfma_f32_16x16x32_bf16 v[88:91], v[180:183], v[222:225], v[88:91]
	v_mfma_f32_16x16x32_bf16 v[76:79], v[168:171], v[226:229], v[76:79]
	v_mfma_f32_16x16x32_bf16 v[76:79], v[172:175], v[230:233], v[76:79]
	v_mfma_f32_16x16x32_bf16 v[72:75], v[176:179], v[226:229], v[72:75]
	v_mfma_f32_16x16x32_bf16 v[72:75], v[180:183], v[230:233], v[72:75]
	s_setprio 0
	s_setprio 1
	v_mfma_f32_16x16x32_bf16 v[116:119], v[184:187], v[202:205], v[116:119]
	v_mfma_f32_16x16x32_bf16 v[116:119], v[188:191], v[206:209], v[116:119]
	v_mfma_f32_16x16x32_bf16 v[112:115], v[194:197], v[202:205], v[112:115]
	v_mfma_f32_16x16x32_bf16 v[112:115], v[198:201], v[206:209], v[112:115]
	v_mfma_f32_16x16x32_bf16 v[100:103], v[184:187], v[210:213], v[100:103]
	v_mfma_f32_16x16x32_bf16 v[100:103], v[188:191], v[214:217], v[100:103]
	v_mfma_f32_16x16x32_bf16 v[96:99], v[194:197], v[210:213], v[96:99]
	v_mfma_f32_16x16x32_bf16 v[96:99], v[198:201], v[214:217], v[96:99]
	v_mfma_f32_16x16x32_bf16 v[84:87], v[184:187], v[218:221], v[84:87]
	v_mfma_f32_16x16x32_bf16 v[84:87], v[188:191], v[222:225], v[84:87]
	v_mfma_f32_16x16x32_bf16 v[80:83], v[194:197], v[218:221], v[80:83]
	v_mfma_f32_16x16x32_bf16 v[80:83], v[198:201], v[222:225], v[80:83]
	v_mfma_f32_16x16x32_bf16 v[68:71], v[184:187], v[226:229], v[68:71]
	v_mfma_f32_16x16x32_bf16 v[68:71], v[188:191], v[230:233], v[68:71]
	v_mfma_f32_16x16x32_bf16 v[64:67], v[194:197], v[226:229], v[64:67]
	v_mfma_f32_16x16x32_bf16 v[64:67], v[198:201], v[230:233], v[64:67]
	s_setprio 0
	s_barrier
	s_add_i32 s72, s63, s33
	v_lshl_add_u64 v[234:235], s[8:9], 0, v[132:133]
	s_mov_b32 m0, s72
	ds_read_b128 v[202:205], v155 offset:16384
	ds_read_b128 v[206:209], v155 offset:17408
	ds_read_b128 v[210:213], v155 offset:18432
	ds_read_b128 v[214:217], v155 offset:19456
	ds_read_b128 v[218:221], v155 offset:20480
	ds_read_b128 v[222:225], v155 offset:21504
	ds_read_b128 v[226:229], v155 offset:22528
	ds_read_b128 v[230:233], v155 offset:23552
	global_load_lds_dwordx4 v[234:235], off
	s_add_i32 m0, s72, 0x2000
	s_add_u32 s72, s8, 0x80000
	v_lshl_add_u64 v[236:237], s[8:9], 0, v[128:129]
	s_addc_u32 s73, s9, 0
	s_add_i32 s74, s64, s33
	global_load_lds_dwordx4 v[236:237], off
	v_lshl_add_u64 v[238:239], s[72:73], 0, v[132:133]
	s_mov_b32 m0, s74
	v_lshl_add_u64 v[240:241], s[54:55], 0, v[130:131]
	global_load_lds_dwordx4 v[238:239], off
	v_lshl_add_u64 v[238:239], s[72:73], 0, v[128:129]
	s_add_i32 m0, s74, 0x2000
	s_nop 0
	global_load_lds_dwordx4 v[238:239], off
	v_lshl_add_u64 v[238:239], s[54:55], 0, v[134:135]
	s_mov_b32 m0, s39
	s_nop 0
	global_load_lds_dwordx4 v[238:239], off
	s_mov_b32 m0, s53
	s_nop 0
	global_load_lds_dwordx4 v[240:241], off
	s_waitcnt vmcnt(8)
	s_waitcnt lgkmcnt(0)
	s_barrier
; #define PG8_STAGE(bufoff, gbase, voff) do { _Pragma("unroll") for (int _i = 0; _i < 2; ++_i) \
;         __builtin_amdgcn_global_load_lds((const unsigned*)((const char*)(gbase) + (voff)[_i]), (LAS unsigned*)(lds + (bufoff) + ldsw + _i * 8192), 16, 0, 0); } while (0)
; #define PG8_LDA(dst, b, h) do { _Pragma("unroll") for (int m = 0; m < 4; ++m) _Pragma("unroll") for (int k = 0; k < 2; ++k) dst[m][k] = *(const LAS bf16x8*)(lds + PG8_SA(b, h) + aoff + m * 2048 + k * 1024); } while (0)
; #define PG8_LDB(dst, b, h) do { _Pragma("unroll") for (int n = 0; n < 2; ++n) _Pragma("unroll") for (int k = 0; k < 2; ++k) dst[n][k] = *(const LAS bf16x8*)(lds + PG8_SB(b, h) + boff + n * 2048 + k * 1024); } while (0)
; #define PG8_MMA(ai, bj, At, Bt) do { __builtin_amdgcn_s_setprio(1); _Pragma("unroll") for (int m = 0; m < 4; ++m) _Pragma("unroll") for (int n = 0; n < 2; ++n) _Pragma("unroll") for (int k = 0; k < 2; ++k) \
;         acc[ai][bj][m][n] = __builtin_amdgcn_mfma_f32_16x16x32_bf16(Bt[n][k], At[m][k], acc[ai][bj][m][n], 0, 0, 0); __builtin_amdgcn_s_setprio(0); } while (0)
; #define PG8_WAIT_V(n) asm volatile("s_waitcnt vmcnt(" #n ")" ::: "memory")
; #define PG8_WAIT_L(n) asm volatile("s_waitcnt lgkmcnt(" #n ")" ::: "memory")
; #define PG8_BAR __builtin_amdgcn_s_barrier()
; #define PG8_SCHED __builtin_amdgcn_sched_barrier(0)
; template <class Epi, bool ALIGN_EPI>
; __device__ __forceinline__ void gemm_phase(LAS unsigned char* lds, const Gemm g, const StaticOrder& S, const Epi& E) {
;     ...
;             PG8_WAIT_V(8); PG8_WAIT_L(0); PG8_BAR; PG8_MMA(1, 0, At, B0); PG8_MMA(1, 1, At, B1); PG8_BAR; PG8_SCHED;
;             PG8_LDB(B0, 1, 0); PG8_LDB(B1, 1, 1); PG8_SCHED; PG8_LDA(At, 1, 0); PG8_STAGE(PG8_SA(0, 1), a2 + hA, voffA);
;             PG8_WAIT_V(8); PG8_WAIT_L(0); PG8_BAR; PG8_MMA(0, 0, At, B0); PG8_MMA(0, 1, At, B1); PG8_BAR; PG8_SCHED;
	s_setprio 1
	s_waitcnt lgkmcnt(0)
	v_mfma_f32_16x16x32_bf16 v[60:63], v[168:171], v[202:205], v[60:63]
	v_mfma_f32_16x16x32_bf16 v[60:63], v[172:175], v[206:209], v[60:63]
	v_mfma_f32_16x16x32_bf16 v[56:59], v[176:179], v[202:205], v[56:59]
	v_mfma_f32_16x16x32_bf16 v[56:59], v[180:183], v[206:209], v[56:59]
	v_mfma_f32_16x16x32_bf16 v[48:51], v[168:171], v[210:213], v[48:51]
	v_mfma_f32_16x16x32_bf16 v[48:51], v[172:175], v[214:217], v[48:51]
	v_mfma_f32_16x16x32_bf16 v[40:43], v[176:179], v[210:213], v[40:43]
	v_mfma_f32_16x16x32_bf16 v[40:43], v[180:183], v[214:217], v[40:43]
	v_mfma_f32_16x16x32_bf16 v[32:35], v[168:171], v[218:221], v[32:35]
	v_mfma_f32_16x16x32_bf16 v[32:35], v[172:175], v[222:225], v[32:35]
	v_mfma_f32_16x16x32_bf16 v[24:27], v[176:179], v[218:221], v[24:27]
	v_mfma_f32_16x16x32_bf16 v[24:27], v[180:183], v[222:225], v[24:27]
	v_mfma_f32_16x16x32_bf16 v[16:19], v[168:171], v[226:229], v[16:19]
	v_mfma_f32_16x16x32_bf16 v[16:19], v[172:175], v[230:233], v[16:19]
	v_mfma_f32_16x16x32_bf16 v[8:11], v[176:179], v[226:229], v[8:11]
	v_mfma_f32_16x16x32_bf16 v[8:11], v[180:183], v[230:233], v[8:11]
	s_setprio 0
	s_setprio 1
	v_mfma_f32_16x16x32_bf16 v[52:55], v[184:187], v[202:205], v[52:55]
	v_mfma_f32_16x16x32_bf16 v[52:55], v[188:191], v[206:209], v[52:55]
	v_mfma_f32_16x16x32_bf16 v[44:47], v[194:197], v[202:205], v[44:47]
	v_mfma_f32_16x16x32_bf16 v[44:47], v[198:201], v[206:209], v[44:47]
	v_mfma_f32_16x16x32_bf16 v[36:39], v[184:187], v[210:213], v[36:39]
	v_mfma_f32_16x16x32_bf16 v[36:39], v[188:191], v[214:217], v[36:39]
	v_mfma_f32_16x16x32_bf16 v[28:31], v[194:197], v[210:213], v[28:31]
	v_mfma_f32_16x16x32_bf16 v[28:31], v[198:201], v[214:217], v[28:31]
	v_mfma_f32_16x16x32_bf16 v[20:23], v[184:187], v[218:221], v[20:23]
	v_mfma_f32_16x16x32_bf16 v[20:23], v[188:191], v[222:225], v[20:23]
	v_mfma_f32_16x16x32_bf16 v[12:15], v[194:197], v[218:221], v[12:15]
	v_mfma_f32_16x16x32_bf16 v[12:15], v[198:201], v[222:225], v[12:15]
	v_mfma_f32_16x16x32_bf16 v[4:7], v[184:187], v[226:229], v[4:7]
	v_mfma_f32_16x16x32_bf16 v[4:7], v[188:191], v[230:233], v[4:7]
	v_mfma_f32_16x16x32_bf16 v[0:3], v[194:197], v[226:229], v[0:3]
	v_mfma_f32_16x16x32_bf16 v[0:3], v[198:201], v[230:233], v[0:3]
	s_setprio 0
	s_barrier
	s_add_i32 s72, 0, 0x18000
	v_add_u32_e32 v167, s72, v149
	s_add_i32 s73, 0, 0x1c000
	ds_read_b128 v[168:171], v167
	ds_read_b128 v[172:175], v167 offset:1024
	ds_read_b128 v[176:179], v167 offset:2048
	ds_read_b128 v[180:183], v167 offset:3072
	v_add_u32_e32 v167, s73, v149
	ds_read_b128 v[184:187], v167
	ds_read_b128 v[188:191], v167 offset:1024
	ds_read_b128 v[194:197], v167 offset:2048
	ds_read_b128 v[198:201], v167 offset:3072
	s_add_u32 s54, s54, 0x80000
	s_addc_u32 s55, s55, 0
	s_mov_b32 m0, s56
	v_lshl_add_u64 v[242:243], s[54:55], 0, v[134:135]
	ds_read_b128 v[202:205], v155 offset:32768
	ds_read_b128 v[206:209], v155 offset:33792
	ds_read_b128 v[210:213], v155 offset:34816
	ds_read_b128 v[214:217], v155 offset:35840
	ds_read_b128 v[218:221], v155 offset:36864
	ds_read_b128 v[222:225], v155 offset:37888
	ds_read_b128 v[226:229], v155 offset:38912
	ds_read_b128 v[230:233], v155 offset:39936
	global_load_lds_dwordx4 v[242:243], off
	v_lshl_add_u64 v[242:243], s[54:55], 0, v[130:131]
	s_mov_b32 m0, s57
	s_nop 0
	global_load_lds_dwordx4 v[242:243], off
	s_waitcnt vmcnt(8)
	s_waitcnt lgkmcnt(0)
	s_barrier
	s_setprio 1
	s_waitcnt lgkmcnt(0)
	v_mfma_f32_16x16x32_bf16 v[124:127], v[168:171], v[202:205], v[124:127]
	v_mfma_f32_16x16x32_bf16 v[124:127], v[172:175], v[206:209], v[124:127]
	v_mfma_f32_16x16x32_bf16 v[120:123], v[176:179], v[202:205], v[120:123]
	v_mfma_f32_16x16x32_bf16 v[120:123], v[180:183], v[206:209], v[120:123]
	v_mfma_f32_16x16x32_bf16 v[108:111], v[168:171], v[210:213], v[108:111]
	v_mfma_f32_16x16x32_bf16 v[108:111], v[172:175], v[214:217], v[108:111]
	v_mfma_f32_16x16x32_bf16 v[104:107], v[176:179], v[210:213], v[104:107]
	v_mfma_f32_16x16x32_bf16 v[104:107], v[180:183], v[214:217], v[104:107]
	v_mfma_f32_16x16x32_bf16 v[92:95], v[168:171], v[218:221], v[92:95]
	v_mfma_f32_16x16x32_bf16 v[92:95], v[172:175], v[222:225], v[92:95]
	v_mfma_f32_16x16x32_bf16 v[88:91], v[176:179], v[218:221], v[88:91]
	v_mfma_f32_16x16x32_bf16 v[88:91], v[180:183], v[222:225], v[88:91]
	v_mfma_f32_16x16x32_bf16 v[76:79], v[168:171], v[226:229], v[76:79]
	v_mfma_f32_16x16x32_bf16 v[76:79], v[172:175], v[230:233], v[76:79]
	v_mfma_f32_16x16x32_bf16 v[72:75], v[176:179], v[226:229], v[72:75]
	v_mfma_f32_16x16x32_bf16 v[72:75], v[180:183], v[230:233], v[72:75]
	s_setprio 0
	s_setprio 1
	v_mfma_f32_16x16x32_bf16 v[116:119], v[184:187], v[202:205], v[116:119]
	v_mfma_f32_16x16x32_bf16 v[116:119], v[188:191], v[206:209], v[116:119]
	v_mfma_f32_16x16x32_bf16 v[112:115], v[194:197], v[202:205], v[112:115]
	v_mfma_f32_16x16x32_bf16 v[112:115], v[198:201], v[206:209], v[112:115]
	v_mfma_f32_16x16x32_bf16 v[100:103], v[184:187], v[210:213], v[100:103]
	v_mfma_f32_16x16x32_bf16 v[100:103], v[188:191], v[214:217], v[100:103]
	v_mfma_f32_16x16x32_bf16 v[96:99], v[194:197], v[210:213], v[96:99]
	v_mfma_f32_16x16x32_bf16 v[96:99], v[198:201], v[214:217], v[96:99]
	v_mfma_f32_16x16x32_bf16 v[84:87], v[184:187], v[218:221], v[84:87]
	v_mfma_f32_16x16x32_bf16 v[84:87], v[188:191], v[222:225], v[84:87]
	v_mfma_f32_16x16x32_bf16 v[80:83], v[194:197], v[218:221], v[80:83]
	v_mfma_f32_16x16x32_bf16 v[80:83], v[198:201], v[222:225], v[80:83]
	v_mfma_f32_16x16x32_bf16 v[68:71], v[184:187], v[226:229], v[68:71]
	v_mfma_f32_16x16x32_bf16 v[68:71], v[188:191], v[230:233], v[68:71]
	v_mfma_f32_16x16x32_bf16 v[64:67], v[194:197], v[226:229], v[64:67]
	v_mfma_f32_16x16x32_bf16 v[64:67], v[198:201], v[230:233], v[64:67]
	s_setprio 0
	s_barrier
; #define PG8_STAGE(bufoff, gbase, voff) do { _Pragma("unroll") for (int _i = 0; _i < 2; ++_i) \
;         __builtin_amdgcn_global_load_lds((const unsigned*)((const char*)(gbase) + (voff)[_i]), (LAS unsigned*)(lds + (bufoff) + ldsw + _i * 8192), 16, 0, 0); } while (0)
; #define PG8_LDA(dst, b, h) do { _Pragma("unroll") for (int m = 0; m < 4; ++m) _Pragma("unroll") for (int k = 0; k < 2; ++k) dst[m][k] = *(const LAS bf16x8*)(lds + PG8_SA(b, h) + aoff + m * 2048 + k * 1024); } while (0)
; #define PG8_MMA(ai, bj, At, Bt) do { __builtin_amdgcn_s_setprio(1); _Pragma("unroll") for (int m = 0; m < 4; ++m) _Pragma("unroll") for (int n = 0; n < 2; ++n) _Pragma("unroll") for (int k = 0; k < 2; ++k) \
;         acc[ai][bj][m][n] = __builtin_amdgcn_mfma_f32_16x16x32_bf16(Bt[n][k], At[m][k], acc[ai][bj][m][n], 0, 0, 0); __builtin_amdgcn_s_setprio(0); } while (0)
; #define PG8_WAIT_V(n) asm volatile("s_waitcnt vmcnt(" #n ")" ::: "memory")
; #define PG8_WAIT_L(n) asm volatile("s_waitcnt lgkmcnt(" #n ")" ::: "memory")
; #define PG8_BAR __builtin_amdgcn_s_barrier()
; #define PG8_SCHED __builtin_amdgcn_sched_barrier(0)
; template <class Epi, bool ALIGN_EPI>
; __device__ __forceinline__ void gemm_phase(LAS unsigned char* lds, const Gemm g, const StaticOrder& S, const Epi& E) {
;     ...
;             PG8_LDA(At, 1, 1); PG8_STAGE(PG8_SB(1, 0), b3, voffB); PG8_STAGE(PG8_SB(1, 1), b3 + hB, voffB); PG8_STAGE(PG8_SA(1, 0), a3, voffA);
;             PG8_WAIT_V(8); PG8_WAIT_L(0); PG8_BAR; PG8_MMA(1, 0, At, B0); PG8_MMA(1, 1, At, B1); PG8_BAR; PG8_SCHED;
;         }
;         if constexpr (ALIGN_EPI) { if (wr == 0) PG8_BAR; }
	s_add_i32 s54, s72, s33
	v_lshl_add_u64 v[234:235], v[234:235], 0, s[20:21]
	s_mov_b32 m0, s54
	ds_read_b128 v[202:205], v155 offset:49152
	ds_read_b128 v[206:209], v155 offset:50176
	ds_read_b128 v[210:213], v155 offset:51200
	ds_read_b128 v[214:217], v155 offset:52224
	ds_read_b128 v[218:221], v155 offset:53248
	ds_read_b128 v[222:225], v155 offset:54272
	ds_read_b128 v[226:229], v155 offset:55296
	ds_read_b128 v[230:233], v155 offset:56320
	global_load_lds_dwordx4 v[234:235], off
	s_add_i32 m0, s54, 0x2000
	s_add_u32 s8, s8, 0x80080
	v_lshl_add_u64 v[234:235], v[236:237], 0, s[20:21]
	s_addc_u32 s9, s9, 0
	s_add_i32 s54, s73, s33
	global_load_lds_dwordx4 v[234:235], off
	v_lshl_add_u64 v[234:235], s[8:9], 0, v[132:133]
	s_mov_b32 m0, s54
	s_nop 0
	global_load_lds_dwordx4 v[234:235], off
	v_lshl_add_u64 v[234:235], s[8:9], 0, v[128:129]
	s_add_i32 m0, s54, 0x2000
	s_nop 0
	global_load_lds_dwordx4 v[234:235], off
	v_lshl_add_u64 v[234:235], v[238:239], 0, s[20:21]
	s_mov_b32 m0, s60
	s_nop 0
	global_load_lds_dwordx4 v[234:235], off
	v_lshl_add_u64 v[234:235], v[240:241], 0, s[20:21]
	s_mov_b32 m0, s61
	s_nop 0
	global_load_lds_dwordx4 v[234:235], off
	s_waitcnt vmcnt(8)
	s_waitcnt lgkmcnt(0)
	s_barrier
	s_setprio 1
	s_waitcnt lgkmcnt(0)
	v_mfma_f32_16x16x32_bf16 v[60:63], v[168:171], v[202:205], v[60:63]
	v_mfma_f32_16x16x32_bf16 v[60:63], v[172:175], v[206:209], v[60:63]
	v_mfma_f32_16x16x32_bf16 v[56:59], v[176:179], v[202:205], v[56:59]
	v_mfma_f32_16x16x32_bf16 v[56:59], v[180:183], v[206:209], v[56:59]
	v_mfma_f32_16x16x32_bf16 v[48:51], v[168:171], v[210:213], v[48:51]
	v_mfma_f32_16x16x32_bf16 v[48:51], v[172:175], v[214:217], v[48:51]
	v_mfma_f32_16x16x32_bf16 v[40:43], v[176:179], v[210:213], v[40:43]
	v_mfma_f32_16x16x32_bf16 v[40:43], v[180:183], v[214:217], v[40:43]
	v_mfma_f32_16x16x32_bf16 v[32:35], v[168:171], v[218:221], v[32:35]
	v_mfma_f32_16x16x32_bf16 v[32:35], v[172:175], v[222:225], v[32:35]
	v_mfma_f32_16x16x32_bf16 v[24:27], v[176:179], v[218:221], v[24:27]
	v_mfma_f32_16x16x32_bf16 v[24:27], v[180:183], v[222:225], v[24:27]
	v_mfma_f32_16x16x32_bf16 v[16:19], v[168:171], v[226:229], v[16:19]
	v_mfma_f32_16x16x32_bf16 v[16:19], v[172:175], v[230:233], v[16:19]
	v_mfma_f32_16x16x32_bf16 v[8:11], v[176:179], v[226:229], v[8:11]
	v_mfma_f32_16x16x32_bf16 v[8:11], v[180:183], v[230:233], v[8:11]
	s_setprio 0
	s_setprio 1
	v_mfma_f32_16x16x32_bf16 v[52:55], v[184:187], v[202:205], v[52:55]
	v_mfma_f32_16x16x32_bf16 v[52:55], v[188:191], v[206:209], v[52:55]
	v_mfma_f32_16x16x32_bf16 v[44:47], v[194:197], v[202:205], v[44:47]
	v_mfma_f32_16x16x32_bf16 v[44:47], v[198:201], v[206:209], v[44:47]
	v_mfma_f32_16x16x32_bf16 v[36:39], v[184:187], v[210:213], v[36:39]
	v_mfma_f32_16x16x32_bf16 v[36:39], v[188:191], v[214:217], v[36:39]
	v_mfma_f32_16x16x32_bf16 v[28:31], v[194:197], v[210:213], v[28:31]
	v_mfma_f32_16x16x32_bf16 v[28:31], v[198:201], v[214:217], v[28:31]
	v_mfma_f32_16x16x32_bf16 v[20:23], v[184:187], v[218:221], v[20:23]
	v_mfma_f32_16x16x32_bf16 v[20:23], v[188:191], v[222:225], v[20:23]
	v_mfma_f32_16x16x32_bf16 v[12:15], v[194:197], v[218:221], v[12:15]
	v_mfma_f32_16x16x32_bf16 v[12:15], v[198:201], v[222:225], v[12:15]
	v_mfma_f32_16x16x32_bf16 v[4:7], v[184:187], v[226:229], v[4:7]
	v_mfma_f32_16x16x32_bf16 v[4:7], v[188:191], v[230:233], v[4:7]
	v_mfma_f32_16x16x32_bf16 v[0:3], v[194:197], v[226:229], v[0:3]
	v_mfma_f32_16x16x32_bf16 v[0:3], v[198:201], v[230:233], v[0:3]
	s_setprio 0
	s_barrier
	s_add_i32 s71, s71, 2
	s_add_u32 s6, s6, 0x100
	s_addc_u32 s7, s7, 0
	s_add_u32 s69, s69, 0x100
	s_addc_u32 s70, s70, 0
	s_cmp_gt_u32 s71, 29
	s_cbranch_scc0 .LBB0_252
	s_and_b64 vcc, exec, s[22:23]
	s_cbranch_vccz .LBB0_255
	s_barrier

; #define PG8_STAGE(bufoff, gbase, voff) do { _Pragma("unroll") for (int _i = 0; _i < 2; ++_i) \
;         __builtin_amdgcn_global_load_lds((const unsigned*)((const char*)(gbase) + (voff)[_i]), (LAS unsigned*)(lds + (bufoff) + ldsw + _i * 8192), 16, 0, 0); } while (0)
; #define PG8_LDA(dst, b, h) do { _Pragma("unroll") for (int m = 0; m < 4; ++m) _Pragma("unroll") for (int k = 0; k < 2; ++k) dst[m][k] = *(const LAS bf16x8*)(lds + PG8_SA(b, h) + aoff + m * 2048 + k * 1024); } while (0)
; #define PG8_LDB(dst, b, h) do { _Pragma("unroll") for (int n = 0; n < 2; ++n) _Pragma("unroll") for (int k = 0; k < 2; ++k) dst[n][k] = *(const LAS bf16x8*)(lds + PG8_SB(b, h) + boff + n * 2048 + k * 1024); } while (0)
; #define PG8_MMA(ai, bj, At, Bt) do { __builtin_amdgcn_s_setprio(1); _Pragma("unroll") for (int m = 0; m < 4; ++m) _Pragma("unroll") for (int n = 0; n < 2; ++n) _Pragma("unroll") for (int k = 0; k < 2; ++k) \
;         acc[ai][bj][m][n] = __builtin_amdgcn_mfma_f32_16x16x32_bf16(Bt[n][k], At[m][k], acc[ai][bj][m][n], 0, 0, 0); __builtin_amdgcn_s_setprio(0); } while (0)
; #define PG8_WAIT_V(n) asm volatile("s_waitcnt vmcnt(" #n ")" ::: "memory")
; #define PG8_WAIT_L(n) asm volatile("s_waitcnt lgkmcnt(" #n ")" ::: "memory")
; #define PG8_BAR __builtin_amdgcn_s_barrier()
; #define PG8_SCHED __builtin_amdgcn_sched_barrier(0)
; template <class Epi, bool ALIGN_EPI>
; __device__ __forceinline__ void gemm_phase(LAS unsigned char* lds, const Gemm g, const StaticOrder& S, const Epi& E) {
;     ...
;         for (int t = 0; t < nt; t += 2) {
;             const bool last = (t == nt - 2);
;             const char* a1 = cA + (size_t)(t + 1) * kstep;
;             const char* a2 = last ? nA : cA + (size_t)(t + 2) * kstep; const char* b2 = last ? nB : cB + (size_t)(t + 2) * kstep;
;             const char* a3 = a2 + kstep; const char* b3 = b2 + kstep;
;             PG8_LDB(B0, 0, 0); PG8_LDB(B1, 0, 1); PG8_SCHED; PG8_LDA(At, 0, 0); PG8_STAGE(PG8_SA(1, 1), a1 + hA, voffA);
;             PG8_WAIT_V(8); PG8_WAIT_L(0); PG8_BAR; PG8_MMA(0, 0, At, B0); PG8_MMA(0, 1, At, B1); PG8_BAR; PG8_SCHED;
;             PG8_LDA(At, 0, 1); PG8_STAGE(PG8_SB(0, 0), b2, voffB); PG8_STAGE(PG8_SB(0, 1), b2 + hB, voffB); PG8_STAGE(PG8_SA(0, 0), a2, voffA);
;             PG8_WAIT_V(8); PG8_WAIT_L(0); PG8_BAR; PG8_MMA(1, 0, At, B0); PG8_MMA(1, 1, At, B1); PG8_BAR; PG8_SCHED;
.LBB0_385:
	ds_read_b128 v[152:155], v149
	ds_read_b128 v[156:159], v149 offset:1024
	ds_read_b128 v[160:163], v149 offset:2048
	ds_read_b128 v[164:167], v149 offset:3072
	ds_read_b128 v[168:171], v150
	ds_read_b128 v[172:175], v150 offset:1024
	ds_read_b128 v[176:179], v150 offset:2048
	ds_read_b128 v[180:183], v150 offset:3072
	s_add_u32 s40, s36, 0xfff80080
	s_addc_u32 s41, s37, -1
	s_cmp_eq_u32 s61, 4
	s_cselect_b32 s43, s27, s41
	s_cselect_b32 s42, s57, s40
	s_cselect_b32 s41, s25, s60
	s_cselect_b32 s40, s58, s59
	v_lshl_add_u64 v[144:145], s[36:37], 0, v[136:137]
	s_add_i32 m0, s35, 0xc000
	ds_read_b128 v[184:187], v151
	ds_read_b128 v[188:191], v151 offset:1024
	ds_read_b128 v[194:197], v151 offset:2048
	ds_read_b128 v[198:201], v151 offset:3072
	ds_read_b128 v[202:205], v151 offset:4096
	ds_read_b128 v[206:209], v151 offset:5120
	ds_read_b128 v[210:213], v151 offset:6144
	ds_read_b128 v[214:217], v151 offset:7168
	global_load_lds_dwordx4 v[144:145], off
	v_lshl_add_u64 v[144:145], s[36:37], 0, v[138:139]
	s_add_i32 m0, s35, 0xe000
	s_nop 0
	global_load_lds_dwordx4 v[144:145], off
	s_waitcnt vmcnt(8)
	s_waitcnt lgkmcnt(0)
	s_barrier
	s_setprio 1
	s_waitcnt lgkmcnt(0)
	v_mfma_f32_16x16x32_bf16 v[124:127], v[152:155], v[184:187], v[124:127]
	v_mfma_f32_16x16x32_bf16 v[124:127], v[156:159], v[188:191], v[124:127]
	v_mfma_f32_16x16x32_bf16 v[120:123], v[160:163], v[184:187], v[120:123]
	v_mfma_f32_16x16x32_bf16 v[120:123], v[164:167], v[188:191], v[120:123]
	v_mfma_f32_16x16x32_bf16 v[116:119], v[152:155], v[194:197], v[116:119]
	v_mfma_f32_16x16x32_bf16 v[116:119], v[156:159], v[198:201], v[116:119]
	v_mfma_f32_16x16x32_bf16 v[108:111], v[160:163], v[194:197], v[108:111]
	v_mfma_f32_16x16x32_bf16 v[108:111], v[164:167], v[198:201], v[108:111]
	v_mfma_f32_16x16x32_bf16 v[100:103], v[152:155], v[202:205], v[100:103]
	v_mfma_f32_16x16x32_bf16 v[100:103], v[156:159], v[206:209], v[100:103]
	v_mfma_f32_16x16x32_bf16 v[92:95], v[160:163], v[202:205], v[92:95]
	v_mfma_f32_16x16x32_bf16 v[92:95], v[164:167], v[206:209], v[92:95]
	v_mfma_f32_16x16x32_bf16 v[84:87], v[152:155], v[210:213], v[84:87]
	v_mfma_f32_16x16x32_bf16 v[84:87], v[156:159], v[214:217], v[84:87]
	v_mfma_f32_16x16x32_bf16 v[76:79], v[160:163], v[210:213], v[76:79]
	v_mfma_f32_16x16x32_bf16 v[76:79], v[164:167], v[214:217], v[76:79]
	s_setprio 0
	s_setprio 1
	v_mfma_f32_16x16x32_bf16 v[112:115], v[168:171], v[184:187], v[112:115]
	v_mfma_f32_16x16x32_bf16 v[112:115], v[172:175], v[188:191], v[112:115]
	v_mfma_f32_16x16x32_bf16 v[104:107], v[176:179], v[184:187], v[104:107]
	v_mfma_f32_16x16x32_bf16 v[104:107], v[180:183], v[188:191], v[104:107]
	v_mfma_f32_16x16x32_bf16 v[96:99], v[168:171], v[194:197], v[96:99]
	v_mfma_f32_16x16x32_bf16 v[96:99], v[172:175], v[198:201], v[96:99]
	v_mfma_f32_16x16x32_bf16 v[88:91], v[176:179], v[194:197], v[88:91]
	v_mfma_f32_16x16x32_bf16 v[88:91], v[180:183], v[198:201], v[88:91]
	v_mfma_f32_16x16x32_bf16 v[80:83], v[168:171], v[202:205], v[80:83]
	v_mfma_f32_16x16x32_bf16 v[80:83], v[172:175], v[206:209], v[80:83]
	v_mfma_f32_16x16x32_bf16 v[72:75], v[176:179], v[202:205], v[72:75]
	v_mfma_f32_16x16x32_bf16 v[72:75], v[180:183], v[206:209], v[72:75]
	v_mfma_f32_16x16x32_bf16 v[68:71], v[168:171], v[210:213], v[68:71]
	v_mfma_f32_16x16x32_bf16 v[68:71], v[172:175], v[214:217], v[68:71]
	v_mfma_f32_16x16x32_bf16 v[64:67], v[176:179], v[210:213], v[64:67]
	v_mfma_f32_16x16x32_bf16 v[64:67], v[180:183], v[214:217], v[64:67]
	s_setprio 0
	s_barrier
	s_add_i32 s62, s53, s45
	v_lshl_add_u64 v[144:145], s[40:41], 0, v[132:133]
	s_mov_b32 m0, s62
	ds_read_b128 v[184:187], v151 offset:16384
	ds_read_b128 v[188:191], v151 offset:17408
	ds_read_b128 v[194:197], v151 offset:18432
	ds_read_b128 v[198:201], v151 offset:19456
	ds_read_b128 v[202:205], v151 offset:20480
	ds_read_b128 v[206:209], v151 offset:21504
	ds_read_b128 v[210:213], v151 offset:22528
	ds_read_b128 v[214:217], v151 offset:23552
	global_load_lds_dwordx4 v[144:145], off
	s_add_i32 m0, s62, 0x2000
	s_add_u32 s62, s40, 0x20000
	v_lshl_add_u64 v[218:219], s[40:41], 0, v[128:129]
	s_addc_u32 s63, s41, 0
	s_add_i32 s64, s54, s45
	global_load_lds_dwordx4 v[218:219], off
	v_lshl_add_u64 v[220:221], s[62:63], 0, v[132:133]
	s_mov_b32 m0, s64
	v_lshl_add_u64 v[222:223], s[42:43], 0, v[130:131]
	global_load_lds_dwordx4 v[220:221], off
	v_lshl_add_u64 v[220:221], s[62:63], 0, v[128:129]
	s_add_i32 m0, s64, 0x2000
	s_nop 0
	global_load_lds_dwordx4 v[220:221], off
	v_lshl_add_u64 v[220:221], s[42:43], 0, v[134:135]
	s_mov_b32 m0, s35
	s_nop 0
	global_load_lds_dwordx4 v[220:221], off
	s_mov_b32 m0, s47
	s_nop 0
	global_load_lds_dwordx4 v[222:223], off
	s_waitcnt vmcnt(8)
	s_waitcnt lgkmcnt(0)
	s_barrier
; #define PG8_STAGE(bufoff, gbase, voff) do { _Pragma("unroll") for (int _i = 0; _i < 2; ++_i) \
;         __builtin_amdgcn_global_load_lds((const unsigned*)((const char*)(gbase) + (voff)[_i]), (LAS unsigned*)(lds + (bufoff) + ldsw + _i * 8192), 16, 0, 0); } while (0)
; #define PG8_LDA(dst, b, h) do { _Pragma("unroll") for (int m = 0; m < 4; ++m) _Pragma("unroll") for (int k = 0; k < 2; ++k) dst[m][k] = *(const LAS bf16x8*)(lds + PG8_SA(b, h) + aoff + m * 2048 + k * 1024); } while (0)
; #define PG8_LDB(dst, b, h) do { _Pragma("unroll") for (int n = 0; n < 2; ++n) _Pragma("unroll") for (int k = 0; k < 2; ++k) dst[n][k] = *(const LAS bf16x8*)(lds + PG8_SB(b, h) + boff + n * 2048 + k * 1024); } while (0)
; #define PG8_MMA(ai, bj, At, Bt) do { __builtin_amdgcn_s_setprio(1); _Pragma("unroll") for (int m = 0; m < 4; ++m) _Pragma("unroll") for (int n = 0; n < 2; ++n) _Pragma("unroll") for (int k = 0; k < 2; ++k) \
;         acc[ai][bj][m][n] = __builtin_amdgcn_mfma_f32_16x16x32_bf16(Bt[n][k], At[m][k], acc[ai][bj][m][n], 0, 0, 0); __builtin_amdgcn_s_setprio(0); } while (0)
; #define PG8_WAIT_V(n) asm volatile("s_waitcnt vmcnt(" #n ")" ::: "memory")
; #define PG8_WAIT_L(n) asm volatile("s_waitcnt lgkmcnt(" #n ")" ::: "memory")
; #define PG8_BAR __builtin_amdgcn_s_barrier()
; #define PG8_SCHED __builtin_amdgcn_sched_barrier(0)
; template <class Epi, bool ALIGN_EPI>
; __device__ __forceinline__ void gemm_phase(LAS unsigned char* lds, const Gemm g, const StaticOrder& S, const Epi& E) {
;     ...
;             PG8_WAIT_V(8); PG8_WAIT_L(0); PG8_BAR; PG8_MMA(1, 0, At, B0); PG8_MMA(1, 1, At, B1); PG8_BAR; PG8_SCHED;
;             PG8_LDB(B0, 1, 0); PG8_LDB(B1, 1, 1); PG8_SCHED; PG8_LDA(At, 1, 0); PG8_STAGE(PG8_SA(0, 1), a2 + hA, voffA);
;             PG8_WAIT_V(8); PG8_WAIT_L(0); PG8_BAR; PG8_MMA(0, 0, At, B0); PG8_MMA(0, 1, At, B1); PG8_BAR; PG8_SCHED;
	s_setprio 1
	s_waitcnt lgkmcnt(0)
	v_mfma_f32_16x16x32_bf16 v[60:63], v[152:155], v[184:187], v[60:63]
	v_mfma_f32_16x16x32_bf16 v[60:63], v[156:159], v[188:191], v[60:63]
	v_mfma_f32_16x16x32_bf16 v[56:59], v[160:163], v[184:187], v[56:59]
	v_mfma_f32_16x16x32_bf16 v[56:59], v[164:167], v[188:191], v[56:59]
	v_mfma_f32_16x16x32_bf16 v[52:55], v[152:155], v[194:197], v[52:55]
	v_mfma_f32_16x16x32_bf16 v[52:55], v[156:159], v[198:201], v[52:55]
	v_mfma_f32_16x16x32_bf16 v[44:47], v[160:163], v[194:197], v[44:47]
	v_mfma_f32_16x16x32_bf16 v[44:47], v[164:167], v[198:201], v[44:47]
	v_mfma_f32_16x16x32_bf16 v[36:39], v[152:155], v[202:205], v[36:39]
	v_mfma_f32_16x16x32_bf16 v[36:39], v[156:159], v[206:209], v[36:39]
	v_mfma_f32_16x16x32_bf16 v[28:31], v[160:163], v[202:205], v[28:31]
	v_mfma_f32_16x16x32_bf16 v[28:31], v[164:167], v[206:209], v[28:31]
	v_mfma_f32_16x16x32_bf16 v[20:23], v[152:155], v[210:213], v[20:23]
	v_mfma_f32_16x16x32_bf16 v[20:23], v[156:159], v[214:217], v[20:23]
	v_mfma_f32_16x16x32_bf16 v[12:15], v[160:163], v[210:213], v[12:15]
	v_mfma_f32_16x16x32_bf16 v[12:15], v[164:167], v[214:217], v[12:15]
	s_setprio 0
	s_setprio 1
	v_mfma_f32_16x16x32_bf16 v[48:51], v[168:171], v[184:187], v[48:51]
	v_mfma_f32_16x16x32_bf16 v[48:51], v[172:175], v[188:191], v[48:51]
	v_mfma_f32_16x16x32_bf16 v[40:43], v[176:179], v[184:187], v[40:43]
	v_mfma_f32_16x16x32_bf16 v[40:43], v[180:183], v[188:191], v[40:43]
	v_mfma_f32_16x16x32_bf16 v[32:35], v[168:171], v[194:197], v[32:35]
	v_mfma_f32_16x16x32_bf16 v[32:35], v[172:175], v[198:201], v[32:35]
	v_mfma_f32_16x16x32_bf16 v[24:27], v[176:179], v[194:197], v[24:27]
	v_mfma_f32_16x16x32_bf16 v[24:27], v[180:183], v[198:201], v[24:27]
	v_mfma_f32_16x16x32_bf16 v[16:19], v[168:171], v[202:205], v[16:19]
	v_mfma_f32_16x16x32_bf16 v[16:19], v[172:175], v[206:209], v[16:19]
	v_mfma_f32_16x16x32_bf16 v[8:11], v[176:179], v[202:205], v[8:11]
	v_mfma_f32_16x16x32_bf16 v[8:11], v[180:183], v[206:209], v[8:11]
	v_mfma_f32_16x16x32_bf16 v[4:7], v[168:171], v[210:213], v[4:7]
	v_mfma_f32_16x16x32_bf16 v[4:7], v[172:175], v[214:217], v[4:7]
	v_mfma_f32_16x16x32_bf16 v[0:3], v[176:179], v[210:213], v[0:3]
	v_mfma_f32_16x16x32_bf16 v[0:3], v[180:183], v[214:217], v[0:3]
	s_setprio 0
	s_barrier
	s_add_i32 s62, 0, 0x18000
	s_add_i32 s63, 0, 0x1c000
	v_add_u32_e32 v164, s62, v147
	v_add_u32_e32 v180, s63, v147
	ds_read_b128 v[152:155], v164
	ds_read_b128 v[156:159], v164 offset:1024
	ds_read_b128 v[160:163], v164 offset:2048
	ds_read_b128 v[164:167], v164 offset:3072
	ds_read_b128 v[168:171], v180
	ds_read_b128 v[172:175], v180 offset:1024
	ds_read_b128 v[176:179], v180 offset:2048
	ds_read_b128 v[180:183], v180 offset:3072
	s_add_u32 s42, s42, 0x80000
	s_addc_u32 s43, s43, 0
	s_mov_b32 m0, s48
	v_lshl_add_u64 v[224:225], s[42:43], 0, v[134:135]
	ds_read_b128 v[184:187], v151 offset:32768
	ds_read_b128 v[188:191], v151 offset:33792
	ds_read_b128 v[194:197], v151 offset:34816
	ds_read_b128 v[198:201], v151 offset:35840
	ds_read_b128 v[202:205], v151 offset:36864
	ds_read_b128 v[206:209], v151 offset:37888
	ds_read_b128 v[210:213], v151 offset:38912
	ds_read_b128 v[214:217], v151 offset:39936
	global_load_lds_dwordx4 v[224:225], off
	v_lshl_add_u64 v[224:225], s[42:43], 0, v[130:131]
	s_mov_b32 m0, s49
	s_nop 0
	global_load_lds_dwordx4 v[224:225], off
	s_waitcnt vmcnt(8)
	s_waitcnt lgkmcnt(0)
	s_barrier
	s_setprio 1
	s_waitcnt lgkmcnt(0)
	v_mfma_f32_16x16x32_bf16 v[124:127], v[152:155], v[184:187], v[124:127]
	v_mfma_f32_16x16x32_bf16 v[124:127], v[156:159], v[188:191], v[124:127]
	v_mfma_f32_16x16x32_bf16 v[120:123], v[160:163], v[184:187], v[120:123]
	v_mfma_f32_16x16x32_bf16 v[120:123], v[164:167], v[188:191], v[120:123]
	v_mfma_f32_16x16x32_bf16 v[116:119], v[152:155], v[194:197], v[116:119]
	v_mfma_f32_16x16x32_bf16 v[116:119], v[156:159], v[198:201], v[116:119]
	v_mfma_f32_16x16x32_bf16 v[108:111], v[160:163], v[194:197], v[108:111]
	v_mfma_f32_16x16x32_bf16 v[108:111], v[164:167], v[198:201], v[108:111]
	v_mfma_f32_16x16x32_bf16 v[100:103], v[152:155], v[202:205], v[100:103]
	v_mfma_f32_16x16x32_bf16 v[100:103], v[156:159], v[206:209], v[100:103]
	v_mfma_f32_16x16x32_bf16 v[92:95], v[160:163], v[202:205], v[92:95]
	v_mfma_f32_16x16x32_bf16 v[92:95], v[164:167], v[206:209], v[92:95]
	v_mfma_f32_16x16x32_bf16 v[84:87], v[152:155], v[210:213], v[84:87]
	v_mfma_f32_16x16x32_bf16 v[84:87], v[156:159], v[214:217], v[84:87]
	v_mfma_f32_16x16x32_bf16 v[76:79], v[160:163], v[210:213], v[76:79]
	v_mfma_f32_16x16x32_bf16 v[76:79], v[164:167], v[214:217], v[76:79]
	s_setprio 0
	s_setprio 1
	v_mfma_f32_16x16x32_bf16 v[112:115], v[168:171], v[184:187], v[112:115]
	v_mfma_f32_16x16x32_bf16 v[112:115], v[172:175], v[188:191], v[112:115]
	v_mfma_f32_16x16x32_bf16 v[104:107], v[176:179], v[184:187], v[104:107]
	v_mfma_f32_16x16x32_bf16 v[104:107], v[180:183], v[188:191], v[104:107]
	v_mfma_f32_16x16x32_bf16 v[96:99], v[168:171], v[194:197], v[96:99]
	v_mfma_f32_16x16x32_bf16 v[96:99], v[172:175], v[198:201], v[96:99]
	v_mfma_f32_16x16x32_bf16 v[88:91], v[176:179], v[194:197], v[88:91]
	v_mfma_f32_16x16x32_bf16 v[88:91], v[180:183], v[198:201], v[88:91]
	v_mfma_f32_16x16x32_bf16 v[80:83], v[168:171], v[202:205], v[80:83]
	v_mfma_f32_16x16x32_bf16 v[80:83], v[172:175], v[206:209], v[80:83]
	v_mfma_f32_16x16x32_bf16 v[72:75], v[176:179], v[202:205], v[72:75]
	v_mfma_f32_16x16x32_bf16 v[72:75], v[180:183], v[206:209], v[72:75]
	v_mfma_f32_16x16x32_bf16 v[68:71], v[168:171], v[210:213], v[68:71]
	v_mfma_f32_16x16x32_bf16 v[68:71], v[172:175], v[214:217], v[68:71]
	v_mfma_f32_16x16x32_bf16 v[64:67], v[176:179], v[210:213], v[64:67]
	v_mfma_f32_16x16x32_bf16 v[64:67], v[180:183], v[214:217], v[64:67]
	s_setprio 0
	s_barrier
; #define PG8_STAGE(bufoff, gbase, voff) do { _Pragma("unroll") for (int _i = 0; _i < 2; ++_i) \
;         __builtin_amdgcn_global_load_lds((const unsigned*)((const char*)(gbase) + (voff)[_i]), (LAS unsigned*)(lds + (bufoff) + ldsw + _i * 8192), 16, 0, 0); } while (0)
; #define PG8_LDA(dst, b, h) do { _Pragma("unroll") for (int m = 0; m < 4; ++m) _Pragma("unroll") for (int k = 0; k < 2; ++k) dst[m][k] = *(const LAS bf16x8*)(lds + PG8_SA(b, h) + aoff + m * 2048 + k * 1024); } while (0)
; #define PG8_MMA(ai, bj, At, Bt) do { __builtin_amdgcn_s_setprio(1); _Pragma("unroll") for (int m = 0; m < 4; ++m) _Pragma("unroll") for (int n = 0; n < 2; ++n) _Pragma("unroll") for (int k = 0; k < 2; ++k) \
;         acc[ai][bj][m][n] = __builtin_amdgcn_mfma_f32_16x16x32_bf16(Bt[n][k], At[m][k], acc[ai][bj][m][n], 0, 0, 0); __builtin_amdgcn_s_setprio(0); } while (0)
; #define PG8_WAIT_V(n) asm volatile("s_waitcnt vmcnt(" #n ")" ::: "memory")
; #define PG8_WAIT_L(n) asm volatile("s_waitcnt lgkmcnt(" #n ")" ::: "memory")
; #define PG8_BAR __builtin_amdgcn_s_barrier()
; #define PG8_SCHED __builtin_amdgcn_sched_barrier(0)
; template <class Epi, bool ALIGN_EPI>
; __device__ __forceinline__ void gemm_phase(LAS unsigned char* lds, const Gemm g, const StaticOrder& S, const Epi& E) {
;     ...
;             PG8_LDA(At, 1, 1); PG8_STAGE(PG8_SB(1, 0), b3, voffB); PG8_STAGE(PG8_SB(1, 1), b3 + hB, voffB); PG8_STAGE(PG8_SA(1, 0), a3, voffA);
;             PG8_WAIT_V(8); PG8_WAIT_L(0); PG8_BAR; PG8_MMA(1, 0, At, B0); PG8_MMA(1, 1, At, B1); PG8_BAR; PG8_SCHED;
;         }
;         if constexpr (ALIGN_EPI) { if (wr == 0) PG8_BAR; }
	s_add_i32 s42, s62, s45
	v_lshl_add_u64 v[144:145], v[144:145], 0, s[18:19]
	s_mov_b32 m0, s42
	ds_read_b128 v[184:187], v151 offset:49152
	ds_read_b128 v[188:191], v151 offset:50176
	ds_read_b128 v[194:197], v151 offset:51200
	ds_read_b128 v[198:201], v151 offset:52224
	ds_read_b128 v[202:205], v151 offset:53248
	ds_read_b128 v[206:209], v151 offset:54272
	ds_read_b128 v[210:213], v151 offset:55296
	ds_read_b128 v[214:217], v151 offset:56320
	global_load_lds_dwordx4 v[144:145], off
	s_add_i32 m0, s42, 0x2000
	s_add_u32 s40, s40, 0x20080
	v_lshl_add_u64 v[144:145], v[218:219], 0, s[18:19]
	s_addc_u32 s41, s41, 0
	s_add_i32 s42, s63, s45
	global_load_lds_dwordx4 v[144:145], off
	v_lshl_add_u64 v[144:145], s[40:41], 0, v[132:133]
	s_mov_b32 m0, s42
	s_nop 0
	global_load_lds_dwordx4 v[144:145], off
	v_lshl_add_u64 v[144:145], s[40:41], 0, v[128:129]
	s_add_i32 m0, s42, 0x2000
	s_nop 0
	global_load_lds_dwordx4 v[144:145], off
	v_lshl_add_u64 v[144:145], v[220:221], 0, s[18:19]
	s_mov_b32 m0, s50
	s_nop 0
	global_load_lds_dwordx4 v[144:145], off
	v_lshl_add_u64 v[144:145], v[222:223], 0, s[18:19]
	s_mov_b32 m0, s51
	s_nop 0
	global_load_lds_dwordx4 v[144:145], off
	s_waitcnt vmcnt(8)
	s_waitcnt lgkmcnt(0)
	s_barrier
	s_setprio 1
	s_waitcnt lgkmcnt(0)
	v_mfma_f32_16x16x32_bf16 v[60:63], v[152:155], v[184:187], v[60:63]
	v_mfma_f32_16x16x32_bf16 v[60:63], v[156:159], v[188:191], v[60:63]
	v_mfma_f32_16x16x32_bf16 v[56:59], v[160:163], v[184:187], v[56:59]
	v_mfma_f32_16x16x32_bf16 v[56:59], v[164:167], v[188:191], v[56:59]
	v_mfma_f32_16x16x32_bf16 v[52:55], v[152:155], v[194:197], v[52:55]
	v_mfma_f32_16x16x32_bf16 v[52:55], v[156:159], v[198:201], v[52:55]
	v_mfma_f32_16x16x32_bf16 v[44:47], v[160:163], v[194:197], v[44:47]
	v_mfma_f32_16x16x32_bf16 v[44:47], v[164:167], v[198:201], v[44:47]
	v_mfma_f32_16x16x32_bf16 v[36:39], v[152:155], v[202:205], v[36:39]
	v_mfma_f32_16x16x32_bf16 v[36:39], v[156:159], v[206:209], v[36:39]
	v_mfma_f32_16x16x32_bf16 v[28:31], v[160:163], v[202:205], v[28:31]
	v_mfma_f32_16x16x32_bf16 v[28:31], v[164:167], v[206:209], v[28:31]
	v_mfma_f32_16x16x32_bf16 v[20:23], v[152:155], v[210:213], v[20:23]
	v_mfma_f32_16x16x32_bf16 v[20:23], v[156:159], v[214:217], v[20:23]
	v_mfma_f32_16x16x32_bf16 v[12:15], v[160:163], v[210:213], v[12:15]
	v_mfma_f32_16x16x32_bf16 v[12:15], v[164:167], v[214:217], v[12:15]
	s_setprio 0
	s_setprio 1
	v_mfma_f32_16x16x32_bf16 v[48:51], v[168:171], v[184:187], v[48:51]
	v_mfma_f32_16x16x32_bf16 v[48:51], v[172:175], v[188:191], v[48:51]
	v_mfma_f32_16x16x32_bf16 v[40:43], v[176:179], v[184:187], v[40:43]
	v_mfma_f32_16x16x32_bf16 v[40:43], v[180:183], v[188:191], v[40:43]
	v_mfma_f32_16x16x32_bf16 v[32:35], v[168:171], v[194:197], v[32:35]
	v_mfma_f32_16x16x32_bf16 v[32:35], v[172:175], v[198:201], v[32:35]
	v_mfma_f32_16x16x32_bf16 v[24:27], v[176:179], v[194:197], v[24:27]
	v_mfma_f32_16x16x32_bf16 v[24:27], v[180:183], v[198:201], v[24:27]
	v_mfma_f32_16x16x32_bf16 v[16:19], v[168:171], v[202:205], v[16:19]
	v_mfma_f32_16x16x32_bf16 v[16:19], v[172:175], v[206:209], v[16:19]
	v_mfma_f32_16x16x32_bf16 v[8:11], v[176:179], v[202:205], v[8:11]
	v_mfma_f32_16x16x32_bf16 v[8:11], v[180:183], v[206:209], v[8:11]
	v_mfma_f32_16x16x32_bf16 v[4:7], v[168:171], v[210:213], v[4:7]
	v_mfma_f32_16x16x32_bf16 v[4:7], v[172:175], v[214:217], v[4:7]
	v_mfma_f32_16x16x32_bf16 v[0:3], v[176:179], v[210:213], v[0:3]
	v_mfma_f32_16x16x32_bf16 v[0:3], v[180:183], v[214:217], v[0:3]
	s_setprio 0
	s_barrier
	s_add_i32 s61, s61, 2
	s_add_u32 s36, s36, 0x100
	s_addc_u32 s37, s37, 0
	s_add_u32 s59, s59, 0x100
	s_addc_u32 s60, s60, 0
	s_cmp_gt_u32 s61, 5
	s_cbranch_scc0 .LBB0_385
	s_and_b64 vcc, exec, s[20:21]
	s_cbranch_vccz .LBB0_388
	s_barrier

; #define PG8_STAGE(bufoff, gbase, voff) do { _Pragma("unroll") for (int _i = 0; _i < 2; ++_i) \
;         __builtin_amdgcn_global_load_lds((const unsigned*)((const char*)(gbase) + (voff)[_i]), (LAS unsigned*)(lds + (bufoff) + ldsw + _i * 8192), 16, 0, 0); } while (0)
; #define PG8_LDA(dst, b, h) do { _Pragma("unroll") for (int m = 0; m < 4; ++m) _Pragma("unroll") for (int k = 0; k < 2; ++k) dst[m][k] = *(const LAS bf16x8*)(lds + PG8_SA(b, h) + aoff + m * 2048 + k * 1024); } while (0)
; #define PG8_LDB(dst, b, h) do { _Pragma("unroll") for (int n = 0; n < 2; ++n) _Pragma("unroll") for (int k = 0; k < 2; ++k) dst[n][k] = *(const LAS bf16x8*)(lds + PG8_SB(b, h) + boff + n * 2048 + k * 1024); } while (0)
; #define PG8_MMA(ai, bj, At, Bt) do { __builtin_amdgcn_s_setprio(1); _Pragma("unroll") for (int m = 0; m < 4; ++m) _Pragma("unroll") for (int n = 0; n < 2; ++n) _Pragma("unroll") for (int k = 0; k < 2; ++k) \
;         acc[ai][bj][m][n] = __builtin_amdgcn_mfma_f32_16x16x32_bf16(Bt[n][k], At[m][k], acc[ai][bj][m][n], 0, 0, 0); __builtin_amdgcn_s_setprio(0); } while (0)
; #define PG8_WAIT_V(n) asm volatile("s_waitcnt vmcnt(" #n ")" ::: "memory")
; #define PG8_WAIT_L(n) asm volatile("s_waitcnt lgkmcnt(" #n ")" ::: "memory")
; #define PG8_BAR __builtin_amdgcn_s_barrier()
; #define PG8_SCHED __builtin_amdgcn_sched_barrier(0)
; template <class Epi, bool ALIGN_EPI>
; __device__ __forceinline__ void gemm_phase(LAS unsigned char* lds, const Gemm g, const StaticOrder& S, const Epi& E) {
;     ...
;         for (int t = 0; t < nt; t += 2) {
;             const bool last = (t == nt - 2);
;             const char* a1 = cA + (size_t)(t + 1) * kstep;
;             const char* a2 = last ? nA : cA + (size_t)(t + 2) * kstep; const char* b2 = last ? nB : cB + (size_t)(t + 2) * kstep;
;             const char* a3 = a2 + kstep; const char* b3 = b2 + kstep;
;             PG8_LDB(B0, 0, 0); PG8_LDB(B1, 0, 1); PG8_SCHED; PG8_LDA(At, 0, 0); PG8_STAGE(PG8_SA(1, 1), a1 + hA, voffA);
;             PG8_WAIT_V(8); PG8_WAIT_L(0); PG8_BAR; PG8_MMA(0, 0, At, B0); PG8_MMA(0, 1, At, B1); PG8_BAR; PG8_SCHED;
;             PG8_LDA(At, 0, 1); PG8_STAGE(PG8_SB(0, 0), b2, voffB); PG8_STAGE(PG8_SB(0, 1), b2 + hB, voffB); PG8_STAGE(PG8_SA(0, 0), a2, voffA);
;             PG8_WAIT_V(8); PG8_WAIT_L(0); PG8_BAR; PG8_MMA(1, 0, At, B0); PG8_MMA(1, 1, At, B1); PG8_BAR; PG8_SCHED;
.LBB0_403:
	ds_read_b128 v[152:155], v149
	ds_read_b128 v[156:159], v149 offset:1024
	ds_read_b128 v[160:163], v149 offset:2048
	ds_read_b128 v[164:167], v149 offset:3072
	ds_read_b128 v[168:171], v150
	ds_read_b128 v[172:175], v150 offset:1024
	ds_read_b128 v[176:179], v150 offset:2048
	ds_read_b128 v[180:183], v150 offset:3072
	s_add_u32 s30, s6, 0xfff80080
	s_addc_u32 s31, s7, -1
	s_cmp_eq_u32 s53, 8
	s_cselect_b32 s35, s23, s31
	s_cselect_b32 s34, s50, s30
	s_cselect_b32 s31, s25, s52
	s_cselect_b32 s30, s24, s51
	v_lshl_add_u64 v[144:145], s[6:7], 0, v[136:137]
	s_add_i32 m0, s0, 0xc000
	ds_read_b128 v[184:187], v151
	ds_read_b128 v[188:191], v151 offset:1024
	ds_read_b128 v[194:197], v151 offset:2048
	ds_read_b128 v[198:201], v151 offset:3072
	ds_read_b128 v[202:205], v151 offset:4096
	ds_read_b128 v[206:209], v151 offset:5120
	ds_read_b128 v[210:213], v151 offset:6144
	ds_read_b128 v[214:217], v151 offset:7168
	global_load_lds_dwordx4 v[144:145], off
	v_lshl_add_u64 v[144:145], s[6:7], 0, v[138:139]
	s_add_i32 m0, s0, 0xe000
	s_nop 0
	global_load_lds_dwordx4 v[144:145], off
	s_waitcnt vmcnt(8)
	s_waitcnt lgkmcnt(0)
	s_barrier
	s_setprio 1
	s_waitcnt lgkmcnt(0)
	v_mfma_f32_16x16x32_bf16 v[124:127], v[152:155], v[184:187], v[124:127]
	v_mfma_f32_16x16x32_bf16 v[124:127], v[156:159], v[188:191], v[124:127]
	v_mfma_f32_16x16x32_bf16 v[120:123], v[160:163], v[184:187], v[120:123]
	v_mfma_f32_16x16x32_bf16 v[120:123], v[164:167], v[188:191], v[120:123]
	v_mfma_f32_16x16x32_bf16 v[116:119], v[152:155], v[194:197], v[116:119]
	v_mfma_f32_16x16x32_bf16 v[116:119], v[156:159], v[198:201], v[116:119]
	v_mfma_f32_16x16x32_bf16 v[108:111], v[160:163], v[194:197], v[108:111]
	v_mfma_f32_16x16x32_bf16 v[108:111], v[164:167], v[198:201], v[108:111]
	v_mfma_f32_16x16x32_bf16 v[100:103], v[152:155], v[202:205], v[100:103]
	v_mfma_f32_16x16x32_bf16 v[100:103], v[156:159], v[206:209], v[100:103]
	v_mfma_f32_16x16x32_bf16 v[92:95], v[160:163], v[202:205], v[92:95]
	v_mfma_f32_16x16x32_bf16 v[92:95], v[164:167], v[206:209], v[92:95]
	v_mfma_f32_16x16x32_bf16 v[84:87], v[152:155], v[210:213], v[84:87]
	v_mfma_f32_16x16x32_bf16 v[84:87], v[156:159], v[214:217], v[84:87]
	v_mfma_f32_16x16x32_bf16 v[76:79], v[160:163], v[210:213], v[76:79]
	v_mfma_f32_16x16x32_bf16 v[76:79], v[164:167], v[214:217], v[76:79]
	s_setprio 0
	s_setprio 1
	v_mfma_f32_16x16x32_bf16 v[112:115], v[168:171], v[184:187], v[112:115]
	v_mfma_f32_16x16x32_bf16 v[112:115], v[172:175], v[188:191], v[112:115]
	v_mfma_f32_16x16x32_bf16 v[104:107], v[176:179], v[184:187], v[104:107]
	v_mfma_f32_16x16x32_bf16 v[104:107], v[180:183], v[188:191], v[104:107]
	v_mfma_f32_16x16x32_bf16 v[96:99], v[168:171], v[194:197], v[96:99]
	v_mfma_f32_16x16x32_bf16 v[96:99], v[172:175], v[198:201], v[96:99]
	v_mfma_f32_16x16x32_bf16 v[88:91], v[176:179], v[194:197], v[88:91]
	v_mfma_f32_16x16x32_bf16 v[88:91], v[180:183], v[198:201], v[88:91]
	v_mfma_f32_16x16x32_bf16 v[80:83], v[168:171], v[202:205], v[80:83]
	v_mfma_f32_16x16x32_bf16 v[80:83], v[172:175], v[206:209], v[80:83]
	v_mfma_f32_16x16x32_bf16 v[72:75], v[176:179], v[202:205], v[72:75]
	v_mfma_f32_16x16x32_bf16 v[72:75], v[180:183], v[206:209], v[72:75]
	v_mfma_f32_16x16x32_bf16 v[68:71], v[168:171], v[210:213], v[68:71]
	v_mfma_f32_16x16x32_bf16 v[68:71], v[172:175], v[214:217], v[68:71]
	v_mfma_f32_16x16x32_bf16 v[64:67], v[176:179], v[210:213], v[64:67]
	v_mfma_f32_16x16x32_bf16 v[64:67], v[180:183], v[214:217], v[64:67]
	s_setprio 0
	s_barrier
	s_add_i32 s54, s45, s2
	v_lshl_add_u64 v[144:145], s[30:31], 0, v[132:133]
	s_mov_b32 m0, s54
	ds_read_b128 v[184:187], v151 offset:16384
	ds_read_b128 v[188:191], v151 offset:17408
	ds_read_b128 v[194:197], v151 offset:18432
	ds_read_b128 v[198:201], v151 offset:19456
	ds_read_b128 v[202:205], v151 offset:20480
	ds_read_b128 v[206:209], v151 offset:21504
	ds_read_b128 v[210:213], v151 offset:22528
	ds_read_b128 v[214:217], v151 offset:23552
	global_load_lds_dwordx4 v[144:145], off
	s_add_i32 m0, s54, 0x2000
	s_add_u32 s54, s30, 0x30000
	v_lshl_add_u64 v[218:219], s[30:31], 0, v[128:129]
	s_addc_u32 s55, s31, 0
	s_add_i32 s56, s46, s2
	global_load_lds_dwordx4 v[218:219], off
	v_lshl_add_u64 v[220:221], s[54:55], 0, v[132:133]
	s_mov_b32 m0, s56
	v_lshl_add_u64 v[222:223], s[34:35], 0, v[130:131]
	global_load_lds_dwordx4 v[220:221], off
	v_lshl_add_u64 v[220:221], s[54:55], 0, v[128:129]
	s_add_i32 m0, s56, 0x2000
	s_nop 0
	global_load_lds_dwordx4 v[220:221], off
	v_lshl_add_u64 v[220:221], s[34:35], 0, v[134:135]
	s_mov_b32 m0, s0
	s_nop 0
	global_load_lds_dwordx4 v[220:221], off
	s_mov_b32 m0, s1
	s_nop 0
	global_load_lds_dwordx4 v[222:223], off
	s_waitcnt vmcnt(8)
	s_waitcnt lgkmcnt(0)
	s_barrier
; #define PG8_STAGE(bufoff, gbase, voff) do { _Pragma("unroll") for (int _i = 0; _i < 2; ++_i) \
;         __builtin_amdgcn_global_load_lds((const unsigned*)((const char*)(gbase) + (voff)[_i]), (LAS unsigned*)(lds + (bufoff) + ldsw + _i * 8192), 16, 0, 0); } while (0)
; #define PG8_LDA(dst, b, h) do { _Pragma("unroll") for (int m = 0; m < 4; ++m) _Pragma("unroll") for (int k = 0; k < 2; ++k) dst[m][k] = *(const LAS bf16x8*)(lds + PG8_SA(b, h) + aoff + m * 2048 + k * 1024); } while (0)
; #define PG8_LDB(dst, b, h) do { _Pragma("unroll") for (int n = 0; n < 2; ++n) _Pragma("unroll") for (int k = 0; k < 2; ++k) dst[n][k] = *(const LAS bf16x8*)(lds + PG8_SB(b, h) + boff + n * 2048 + k * 1024); } while (0)
; #define PG8_MMA(ai, bj, At, Bt) do { __builtin_amdgcn_s_setprio(1); _Pragma("unroll") for (int m = 0; m < 4; ++m) _Pragma("unroll") for (int n = 0; n < 2; ++n) _Pragma("unroll") for (int k = 0; k < 2; ++k) \
;         acc[ai][bj][m][n] = __builtin_amdgcn_mfma_f32_16x16x32_bf16(Bt[n][k], At[m][k], acc[ai][bj][m][n], 0, 0, 0); __builtin_amdgcn_s_setprio(0); } while (0)
; #define PG8_WAIT_V(n) asm volatile("s_waitcnt vmcnt(" #n ")" ::: "memory")
; #define PG8_WAIT_L(n) asm volatile("s_waitcnt lgkmcnt(" #n ")" ::: "memory")
; #define PG8_BAR __builtin_amdgcn_s_barrier()
; #define PG8_SCHED __builtin_amdgcn_sched_barrier(0)
; template <class Epi, bool ALIGN_EPI>
; __device__ __forceinline__ void gemm_phase(LAS unsigned char* lds, const Gemm g, const StaticOrder& S, const Epi& E) {
;     ...
;             PG8_WAIT_V(8); PG8_WAIT_L(0); PG8_BAR; PG8_MMA(1, 0, At, B0); PG8_MMA(1, 1, At, B1); PG8_BAR; PG8_SCHED;
;             PG8_LDB(B0, 1, 0); PG8_LDB(B1, 1, 1); PG8_SCHED; PG8_LDA(At, 1, 0); PG8_STAGE(PG8_SA(0, 1), a2 + hA, voffA);
;             PG8_WAIT_V(8); PG8_WAIT_L(0); PG8_BAR; PG8_MMA(0, 0, At, B0); PG8_MMA(0, 1, At, B1); PG8_BAR; PG8_SCHED;
	s_setprio 1
	s_waitcnt lgkmcnt(0)
	v_mfma_f32_16x16x32_bf16 v[60:63], v[152:155], v[184:187], v[60:63]
	v_mfma_f32_16x16x32_bf16 v[60:63], v[156:159], v[188:191], v[60:63]
	v_mfma_f32_16x16x32_bf16 v[56:59], v[160:163], v[184:187], v[56:59]
	v_mfma_f32_16x16x32_bf16 v[56:59], v[164:167], v[188:191], v[56:59]
	v_mfma_f32_16x16x32_bf16 v[52:55], v[152:155], v[194:197], v[52:55]
	v_mfma_f32_16x16x32_bf16 v[52:55], v[156:159], v[198:201], v[52:55]
	v_mfma_f32_16x16x32_bf16 v[44:47], v[160:163], v[194:197], v[44:47]
	v_mfma_f32_16x16x32_bf16 v[44:47], v[164:167], v[198:201], v[44:47]
	v_mfma_f32_16x16x32_bf16 v[36:39], v[152:155], v[202:205], v[36:39]
	v_mfma_f32_16x16x32_bf16 v[36:39], v[156:159], v[206:209], v[36:39]
	v_mfma_f32_16x16x32_bf16 v[28:31], v[160:163], v[202:205], v[28:31]
	v_mfma_f32_16x16x32_bf16 v[28:31], v[164:167], v[206:209], v[28:31]
	v_mfma_f32_16x16x32_bf16 v[20:23], v[152:155], v[210:213], v[20:23]
	v_mfma_f32_16x16x32_bf16 v[20:23], v[156:159], v[214:217], v[20:23]
	v_mfma_f32_16x16x32_bf16 v[12:15], v[160:163], v[210:213], v[12:15]
	v_mfma_f32_16x16x32_bf16 v[12:15], v[164:167], v[214:217], v[12:15]
	s_setprio 0
	s_setprio 1
	v_mfma_f32_16x16x32_bf16 v[48:51], v[168:171], v[184:187], v[48:51]
	v_mfma_f32_16x16x32_bf16 v[48:51], v[172:175], v[188:191], v[48:51]
	v_mfma_f32_16x16x32_bf16 v[40:43], v[176:179], v[184:187], v[40:43]
	v_mfma_f32_16x16x32_bf16 v[40:43], v[180:183], v[188:191], v[40:43]
	v_mfma_f32_16x16x32_bf16 v[32:35], v[168:171], v[194:197], v[32:35]
	v_mfma_f32_16x16x32_bf16 v[32:35], v[172:175], v[198:201], v[32:35]
	v_mfma_f32_16x16x32_bf16 v[24:27], v[176:179], v[194:197], v[24:27]
	v_mfma_f32_16x16x32_bf16 v[24:27], v[180:183], v[198:201], v[24:27]
	v_mfma_f32_16x16x32_bf16 v[16:19], v[168:171], v[202:205], v[16:19]
	v_mfma_f32_16x16x32_bf16 v[16:19], v[172:175], v[206:209], v[16:19]
	v_mfma_f32_16x16x32_bf16 v[8:11], v[176:179], v[202:205], v[8:11]
	v_mfma_f32_16x16x32_bf16 v[8:11], v[180:183], v[206:209], v[8:11]
	v_mfma_f32_16x16x32_bf16 v[4:7], v[168:171], v[210:213], v[4:7]
	v_mfma_f32_16x16x32_bf16 v[4:7], v[172:175], v[214:217], v[4:7]
	v_mfma_f32_16x16x32_bf16 v[0:3], v[176:179], v[210:213], v[0:3]
	v_mfma_f32_16x16x32_bf16 v[0:3], v[180:183], v[214:217], v[0:3]
	s_setprio 0
	s_barrier
	s_add_i32 s54, 0, 0x18000
	s_add_i32 s55, 0, 0x1c000
	v_add_u32_e32 v164, s54, v147
	v_add_u32_e32 v180, s55, v147
	ds_read_b128 v[152:155], v164
	ds_read_b128 v[156:159], v164 offset:1024
	ds_read_b128 v[160:163], v164 offset:2048
	ds_read_b128 v[164:167], v164 offset:3072
	ds_read_b128 v[168:171], v180
	ds_read_b128 v[172:175], v180 offset:1024
	ds_read_b128 v[176:179], v180 offset:2048
	ds_read_b128 v[180:183], v180 offset:3072
	s_add_u32 s34, s34, 0x80000
	s_addc_u32 s35, s35, 0
	s_mov_b32 m0, s29
	v_lshl_add_u64 v[224:225], s[34:35], 0, v[134:135]
	ds_read_b128 v[184:187], v151 offset:32768
	ds_read_b128 v[188:191], v151 offset:33792
	ds_read_b128 v[194:197], v151 offset:34816
	ds_read_b128 v[198:201], v151 offset:35840
	ds_read_b128 v[202:205], v151 offset:36864
	ds_read_b128 v[206:209], v151 offset:37888
	ds_read_b128 v[210:213], v151 offset:38912
	ds_read_b128 v[214:217], v151 offset:39936
	global_load_lds_dwordx4 v[224:225], off
	v_lshl_add_u64 v[224:225], s[34:35], 0, v[130:131]
	s_mov_b32 m0, s40
	s_nop 0
	global_load_lds_dwordx4 v[224:225], off
	s_waitcnt vmcnt(8)
	s_waitcnt lgkmcnt(0)
	s_barrier
	s_setprio 1
	s_waitcnt lgkmcnt(0)
	v_mfma_f32_16x16x32_bf16 v[124:127], v[152:155], v[184:187], v[124:127]
	v_mfma_f32_16x16x32_bf16 v[124:127], v[156:159], v[188:191], v[124:127]
	v_mfma_f32_16x16x32_bf16 v[120:123], v[160:163], v[184:187], v[120:123]
	v_mfma_f32_16x16x32_bf16 v[120:123], v[164:167], v[188:191], v[120:123]
	v_mfma_f32_16x16x32_bf16 v[116:119], v[152:155], v[194:197], v[116:119]
	v_mfma_f32_16x16x32_bf16 v[116:119], v[156:159], v[198:201], v[116:119]
	v_mfma_f32_16x16x32_bf16 v[108:111], v[160:163], v[194:197], v[108:111]
	v_mfma_f32_16x16x32_bf16 v[108:111], v[164:167], v[198:201], v[108:111]
	v_mfma_f32_16x16x32_bf16 v[100:103], v[152:155], v[202:205], v[100:103]
	v_mfma_f32_16x16x32_bf16 v[100:103], v[156:159], v[206:209], v[100:103]
	v_mfma_f32_16x16x32_bf16 v[92:95], v[160:163], v[202:205], v[92:95]
	v_mfma_f32_16x16x32_bf16 v[92:95], v[164:167], v[206:209], v[92:95]
	v_mfma_f32_16x16x32_bf16 v[84:87], v[152:155], v[210:213], v[84:87]
	v_mfma_f32_16x16x32_bf16 v[84:87], v[156:159], v[214:217], v[84:87]
	v_mfma_f32_16x16x32_bf16 v[76:79], v[160:163], v[210:213], v[76:79]
	v_mfma_f32_16x16x32_bf16 v[76:79], v[164:167], v[214:217], v[76:79]
	s_setprio 0
	s_setprio 1
	v_mfma_f32_16x16x32_bf16 v[112:115], v[168:171], v[184:187], v[112:115]
	v_mfma_f32_16x16x32_bf16 v[112:115], v[172:175], v[188:191], v[112:115]
	v_mfma_f32_16x16x32_bf16 v[104:107], v[176:179], v[184:187], v[104:107]
	v_mfma_f32_16x16x32_bf16 v[104:107], v[180:183], v[188:191], v[104:107]
	v_mfma_f32_16x16x32_bf16 v[96:99], v[168:171], v[194:197], v[96:99]
	v_mfma_f32_16x16x32_bf16 v[96:99], v[172:175], v[198:201], v[96:99]
	v_mfma_f32_16x16x32_bf16 v[88:91], v[176:179], v[194:197], v[88:91]
	v_mfma_f32_16x16x32_bf16 v[88:91], v[180:183], v[198:201], v[88:91]
	v_mfma_f32_16x16x32_bf16 v[80:83], v[168:171], v[202:205], v[80:83]
	v_mfma_f32_16x16x32_bf16 v[80:83], v[172:175], v[206:209], v[80:83]
	v_mfma_f32_16x16x32_bf16 v[72:75], v[176:179], v[202:205], v[72:75]
	v_mfma_f32_16x16x32_bf16 v[72:75], v[180:183], v[206:209], v[72:75]
	v_mfma_f32_16x16x32_bf16 v[68:71], v[168:171], v[210:213], v[68:71]
	v_mfma_f32_16x16x32_bf16 v[68:71], v[172:175], v[214:217], v[68:71]
	v_mfma_f32_16x16x32_bf16 v[64:67], v[176:179], v[210:213], v[64:67]
	v_mfma_f32_16x16x32_bf16 v[64:67], v[180:183], v[214:217], v[64:67]
	s_setprio 0
	s_barrier
; #define PG8_STAGE(bufoff, gbase, voff) do { _Pragma("unroll") for (int _i = 0; _i < 2; ++_i) \
;         __builtin_amdgcn_global_load_lds((const unsigned*)((const char*)(gbase) + (voff)[_i]), (LAS unsigned*)(lds + (bufoff) + ldsw + _i * 8192), 16, 0, 0); } while (0)
; #define PG8_LDA(dst, b, h) do { _Pragma("unroll") for (int m = 0; m < 4; ++m) _Pragma("unroll") for (int k = 0; k < 2; ++k) dst[m][k] = *(const LAS bf16x8*)(lds + PG8_SA(b, h) + aoff + m * 2048 + k * 1024); } while (0)
; #define PG8_MMA(ai, bj, At, Bt) do { __builtin_amdgcn_s_setprio(1); _Pragma("unroll") for (int m = 0; m < 4; ++m) _Pragma("unroll") for (int n = 0; n < 2; ++n) _Pragma("unroll") for (int k = 0; k < 2; ++k) \
;         acc[ai][bj][m][n] = __builtin_amdgcn_mfma_f32_16x16x32_bf16(Bt[n][k], At[m][k], acc[ai][bj][m][n], 0, 0, 0); __builtin_amdgcn_s_setprio(0); } while (0)
; #define PG8_WAIT_V(n) asm volatile("s_waitcnt vmcnt(" #n ")" ::: "memory")
; #define PG8_WAIT_L(n) asm volatile("s_waitcnt lgkmcnt(" #n ")" ::: "memory")
; #define PG8_BAR __builtin_amdgcn_s_barrier()
; #define PG8_SCHED __builtin_amdgcn_sched_barrier(0)
; template <class Epi, bool ALIGN_EPI>
; __device__ __forceinline__ void gemm_phase(LAS unsigned char* lds, const Gemm g, const StaticOrder& S, const Epi& E) {
;     ...
;             PG8_LDA(At, 1, 1); PG8_STAGE(PG8_SB(1, 0), b3, voffB); PG8_STAGE(PG8_SB(1, 1), b3 + hB, voffB); PG8_STAGE(PG8_SA(1, 0), a3, voffA);
;             PG8_WAIT_V(8); PG8_WAIT_L(0); PG8_BAR; PG8_MMA(1, 0, At, B0); PG8_MMA(1, 1, At, B1); PG8_BAR; PG8_SCHED;
;         }
;         if constexpr (ALIGN_EPI) { if (wr == 0) PG8_BAR; }
	s_add_i32 s34, s54, s2
	v_lshl_add_u64 v[144:145], v[144:145], 0, s[16:17]
	s_mov_b32 m0, s34
	ds_read_b128 v[184:187], v151 offset:49152
	ds_read_b128 v[188:191], v151 offset:50176
	ds_read_b128 v[194:197], v151 offset:51200
	ds_read_b128 v[198:201], v151 offset:52224
	ds_read_b128 v[202:205], v151 offset:53248
	ds_read_b128 v[206:209], v151 offset:54272
	ds_read_b128 v[210:213], v151 offset:55296
	ds_read_b128 v[214:217], v151 offset:56320
	global_load_lds_dwordx4 v[144:145], off
	s_add_i32 m0, s34, 0x2000
	s_add_u32 s30, s30, 0x30080
	v_lshl_add_u64 v[144:145], v[218:219], 0, s[16:17]
	s_addc_u32 s31, s31, 0
	s_add_i32 s34, s55, s2
	global_load_lds_dwordx4 v[144:145], off
	v_lshl_add_u64 v[144:145], s[30:31], 0, v[132:133]
	s_mov_b32 m0, s34
	s_nop 0
	global_load_lds_dwordx4 v[144:145], off
	v_lshl_add_u64 v[144:145], s[30:31], 0, v[128:129]
	s_add_i32 m0, s34, 0x2000
	s_nop 0
	global_load_lds_dwordx4 v[144:145], off
	v_lshl_add_u64 v[144:145], v[220:221], 0, s[16:17]
	s_mov_b32 m0, s42
	s_nop 0
	global_load_lds_dwordx4 v[144:145], off
	v_lshl_add_u64 v[144:145], v[222:223], 0, s[16:17]
	s_mov_b32 m0, s43
	s_nop 0
	global_load_lds_dwordx4 v[144:145], off
	s_waitcnt vmcnt(8)
	s_waitcnt lgkmcnt(0)
	s_barrier
	s_setprio 1
	s_waitcnt lgkmcnt(0)
	v_mfma_f32_16x16x32_bf16 v[60:63], v[152:155], v[184:187], v[60:63]
	v_mfma_f32_16x16x32_bf16 v[60:63], v[156:159], v[188:191], v[60:63]
	v_mfma_f32_16x16x32_bf16 v[56:59], v[160:163], v[184:187], v[56:59]
	v_mfma_f32_16x16x32_bf16 v[56:59], v[164:167], v[188:191], v[56:59]
	v_mfma_f32_16x16x32_bf16 v[52:55], v[152:155], v[194:197], v[52:55]
	v_mfma_f32_16x16x32_bf16 v[52:55], v[156:159], v[198:201], v[52:55]
	v_mfma_f32_16x16x32_bf16 v[44:47], v[160:163], v[194:197], v[44:47]
	v_mfma_f32_16x16x32_bf16 v[44:47], v[164:167], v[198:201], v[44:47]
	v_mfma_f32_16x16x32_bf16 v[36:39], v[152:155], v[202:205], v[36:39]
	v_mfma_f32_16x16x32_bf16 v[36:39], v[156:159], v[206:209], v[36:39]
	v_mfma_f32_16x16x32_bf16 v[28:31], v[160:163], v[202:205], v[28:31]
	v_mfma_f32_16x16x32_bf16 v[28:31], v[164:167], v[206:209], v[28:31]
	v_mfma_f32_16x16x32_bf16 v[20:23], v[152:155], v[210:213], v[20:23]
	v_mfma_f32_16x16x32_bf16 v[20:23], v[156:159], v[214:217], v[20:23]
	v_mfma_f32_16x16x32_bf16 v[12:15], v[160:163], v[210:213], v[12:15]
	v_mfma_f32_16x16x32_bf16 v[12:15], v[164:167], v[214:217], v[12:15]
	s_setprio 0
	s_setprio 1
	v_mfma_f32_16x16x32_bf16 v[48:51], v[168:171], v[184:187], v[48:51]
	v_mfma_f32_16x16x32_bf16 v[48:51], v[172:175], v[188:191], v[48:51]
	v_mfma_f32_16x16x32_bf16 v[40:43], v[176:179], v[184:187], v[40:43]
	v_mfma_f32_16x16x32_bf16 v[40:43], v[180:183], v[188:191], v[40:43]
	v_mfma_f32_16x16x32_bf16 v[32:35], v[168:171], v[194:197], v[32:35]
	v_mfma_f32_16x16x32_bf16 v[32:35], v[172:175], v[198:201], v[32:35]
	v_mfma_f32_16x16x32_bf16 v[24:27], v[176:179], v[194:197], v[24:27]
	v_mfma_f32_16x16x32_bf16 v[24:27], v[180:183], v[198:201], v[24:27]
	v_mfma_f32_16x16x32_bf16 v[16:19], v[168:171], v[202:205], v[16:19]
	v_mfma_f32_16x16x32_bf16 v[16:19], v[172:175], v[206:209], v[16:19]
	v_mfma_f32_16x16x32_bf16 v[8:11], v[176:179], v[202:205], v[8:11]
	v_mfma_f32_16x16x32_bf16 v[8:11], v[180:183], v[206:209], v[8:11]
	v_mfma_f32_16x16x32_bf16 v[4:7], v[168:171], v[210:213], v[4:7]
	v_mfma_f32_16x16x32_bf16 v[4:7], v[172:175], v[214:217], v[4:7]
	v_mfma_f32_16x16x32_bf16 v[0:3], v[176:179], v[210:213], v[0:3]
	v_mfma_f32_16x16x32_bf16 v[0:3], v[180:183], v[214:217], v[0:3]
	s_setprio 0
	s_barrier
	s_add_i32 s53, s53, 2
	s_add_u32 s6, s6, 0x100
	s_addc_u32 s7, s7, 0
	s_add_u32 s51, s51, 0x100
	s_addc_u32 s52, s52, 0
	s_cmp_gt_u32 s53, 9
	s_cbranch_scc0 .LBB0_403
	s_and_b64 vcc, exec, s[18:19]
	s_cbranch_vccz .LBB0_406
	s_barrier

; #define PG8_STAGE(bufoff, gbase, voff) do { _Pragma("unroll") for (int _i = 0; _i < 2; ++_i) \
;         __builtin_amdgcn_global_load_lds((const unsigned*)((const char*)(gbase) + (voff)[_i]), (LAS unsigned*)(lds + (bufoff) + ldsw + _i * 8192), 16, 0, 0); } while (0)
; #define PG8_LDA(dst, b, h) do { _Pragma("unroll") for (int m = 0; m < 4; ++m) _Pragma("unroll") for (int k = 0; k < 2; ++k) dst[m][k] = *(const LAS bf16x8*)(lds + PG8_SA(b, h) + aoff + m * 2048 + k * 1024); } while (0)
; #define PG8_LDB(dst, b, h) do { _Pragma("unroll") for (int n = 0; n < 2; ++n) _Pragma("unroll") for (int k = 0; k < 2; ++k) dst[n][k] = *(const LAS bf16x8*)(lds + PG8_SB(b, h) + boff + n * 2048 + k * 1024); } while (0)
; #define PG8_MMA(ai, bj, At, Bt) do { __builtin_amdgcn_s_setprio(1); _Pragma("unroll") for (int m = 0; m < 4; ++m) _Pragma("unroll") for (int n = 0; n < 2; ++n) _Pragma("unroll") for (int k = 0; k < 2; ++k) \
;         acc[ai][bj][m][n] = __builtin_amdgcn_mfma_f32_16x16x32_bf16(Bt[n][k], At[m][k], acc[ai][bj][m][n], 0, 0, 0); __builtin_amdgcn_s_setprio(0); } while (0)
; #define PG8_WAIT_V(n) asm volatile("s_waitcnt vmcnt(" #n ")" ::: "memory")
; #define PG8_WAIT_L(n) asm volatile("s_waitcnt lgkmcnt(" #n ")" ::: "memory")
; #define PG8_BAR __builtin_amdgcn_s_barrier()
; #define PG8_SCHED __builtin_amdgcn_sched_barrier(0)
; template <class Epi, bool ALIGN_EPI>
; __device__ __forceinline__ void gemm_phase(LAS unsigned char* lds, const Gemm g, const StaticOrder& S, const Epi& E) {
;     ...
;         for (int t = 0; t < nt; t += 2) {
;             const bool last = (t == nt - 2);
;             const char* a1 = cA + (size_t)(t + 1) * kstep;
;             const char* a2 = last ? nA : cA + (size_t)(t + 2) * kstep; const char* b2 = last ? nB : cB + (size_t)(t + 2) * kstep;
;             const char* a3 = a2 + kstep; const char* b3 = b2 + kstep;
;             PG8_LDB(B0, 0, 0); PG8_LDB(B1, 0, 1); PG8_SCHED; PG8_LDA(At, 0, 0); PG8_STAGE(PG8_SA(1, 1), a1 + hA, voffA);
;             PG8_WAIT_V(8); PG8_WAIT_L(0); PG8_BAR; PG8_MMA(0, 0, At, B0); PG8_MMA(0, 1, At, B1); PG8_BAR; PG8_SCHED;
;             PG8_LDA(At, 0, 1); PG8_STAGE(PG8_SB(0, 0), b2, voffB); PG8_STAGE(PG8_SB(0, 1), b2 + hB, voffB); PG8_STAGE(PG8_SA(0, 0), a2, voffA);
;             PG8_WAIT_V(8); PG8_WAIT_L(0); PG8_BAR; PG8_MMA(1, 0, At, B0); PG8_MMA(1, 1, At, B1); PG8_BAR; PG8_SCHED;
.LBB0_419:
	ds_read_b128 v[148:151], v145
	ds_read_b128 v[152:155], v145 offset:1024
	ds_read_b128 v[156:159], v145 offset:2048
	ds_read_b128 v[160:163], v145 offset:3072
	ds_read_b128 v[164:167], v146
	ds_read_b128 v[168:171], v146 offset:1024
	ds_read_b128 v[172:175], v146 offset:2048
	ds_read_b128 v[176:179], v146 offset:3072
	s_add_u32 s30, s28, 0xfff80080
	s_addc_u32 s31, s29, -1
	s_cmp_eq_u32 s53, 28
	s_cselect_b32 s35, s19, s31
	s_cselect_b32 s34, s49, s30
	s_cselect_b32 s31, s17, s52
	s_cselect_b32 s30, s50, s51
	v_lshl_add_u64 v[140:141], s[28:29], 0, v[136:137]
	s_add_i32 m0, s27, 0xc000
	ds_read_b128 v[180:183], v147
	ds_read_b128 v[184:187], v147 offset:1024
	ds_read_b128 v[188:191], v147 offset:2048
	ds_read_b128 v[194:197], v147 offset:3072
	ds_read_b128 v[198:201], v147 offset:4096
	ds_read_b128 v[202:205], v147 offset:5120
	ds_read_b128 v[206:209], v147 offset:6144
	ds_read_b128 v[210:213], v147 offset:7168
	global_load_lds_dwordx4 v[140:141], off
	v_lshl_add_u64 v[140:141], s[28:29], 0, v[138:139]
	s_add_i32 m0, s27, 0xe000
	s_nop 0
	global_load_lds_dwordx4 v[140:141], off
	s_waitcnt vmcnt(8)
	s_waitcnt lgkmcnt(0)
	s_barrier
	s_setprio 1
	s_waitcnt lgkmcnt(0)
	v_mfma_f32_16x16x32_bf16 v[124:127], v[148:151], v[180:183], v[124:127]
	v_mfma_f32_16x16x32_bf16 v[124:127], v[152:155], v[184:187], v[124:127]
	v_mfma_f32_16x16x32_bf16 v[120:123], v[156:159], v[180:183], v[120:123]
	v_mfma_f32_16x16x32_bf16 v[120:123], v[160:163], v[184:187], v[120:123]
	v_mfma_f32_16x16x32_bf16 v[116:119], v[148:151], v[188:191], v[116:119]
	v_mfma_f32_16x16x32_bf16 v[116:119], v[152:155], v[194:197], v[116:119]
	v_mfma_f32_16x16x32_bf16 v[108:111], v[156:159], v[188:191], v[108:111]
	v_mfma_f32_16x16x32_bf16 v[108:111], v[160:163], v[194:197], v[108:111]
	v_mfma_f32_16x16x32_bf16 v[100:103], v[148:151], v[198:201], v[100:103]
	v_mfma_f32_16x16x32_bf16 v[100:103], v[152:155], v[202:205], v[100:103]
	v_mfma_f32_16x16x32_bf16 v[92:95], v[156:159], v[198:201], v[92:95]
	v_mfma_f32_16x16x32_bf16 v[92:95], v[160:163], v[202:205], v[92:95]
	v_mfma_f32_16x16x32_bf16 v[84:87], v[148:151], v[206:209], v[84:87]
	v_mfma_f32_16x16x32_bf16 v[84:87], v[152:155], v[210:213], v[84:87]
	v_mfma_f32_16x16x32_bf16 v[76:79], v[156:159], v[206:209], v[76:79]
	v_mfma_f32_16x16x32_bf16 v[76:79], v[160:163], v[210:213], v[76:79]
	s_setprio 0
	s_setprio 1
	v_mfma_f32_16x16x32_bf16 v[112:115], v[164:167], v[180:183], v[112:115]
	v_mfma_f32_16x16x32_bf16 v[112:115], v[168:171], v[184:187], v[112:115]
	v_mfma_f32_16x16x32_bf16 v[104:107], v[172:175], v[180:183], v[104:107]
	v_mfma_f32_16x16x32_bf16 v[104:107], v[176:179], v[184:187], v[104:107]
	v_mfma_f32_16x16x32_bf16 v[96:99], v[164:167], v[188:191], v[96:99]
	v_mfma_f32_16x16x32_bf16 v[96:99], v[168:171], v[194:197], v[96:99]
	v_mfma_f32_16x16x32_bf16 v[88:91], v[172:175], v[188:191], v[88:91]
	v_mfma_f32_16x16x32_bf16 v[88:91], v[176:179], v[194:197], v[88:91]
	v_mfma_f32_16x16x32_bf16 v[80:83], v[164:167], v[198:201], v[80:83]
	v_mfma_f32_16x16x32_bf16 v[80:83], v[168:171], v[202:205], v[80:83]
	v_mfma_f32_16x16x32_bf16 v[72:75], v[172:175], v[198:201], v[72:75]
	v_mfma_f32_16x16x32_bf16 v[72:75], v[176:179], v[202:205], v[72:75]
	v_mfma_f32_16x16x32_bf16 v[68:71], v[164:167], v[206:209], v[68:71]
	v_mfma_f32_16x16x32_bf16 v[68:71], v[168:171], v[210:213], v[68:71]
	v_mfma_f32_16x16x32_bf16 v[64:67], v[172:175], v[206:209], v[64:67]
	v_mfma_f32_16x16x32_bf16 v[64:67], v[176:179], v[210:213], v[64:67]
	s_setprio 0
	s_barrier
	s_add_i32 s54, s45, s1
	v_lshl_add_u64 v[140:141], s[30:31], 0, v[132:133]
	s_mov_b32 m0, s54
	ds_read_b128 v[180:183], v147 offset:16384
	ds_read_b128 v[184:187], v147 offset:17408
	ds_read_b128 v[188:191], v147 offset:18432
	ds_read_b128 v[194:197], v147 offset:19456
	ds_read_b128 v[198:201], v147 offset:20480
	ds_read_b128 v[202:205], v147 offset:21504
	ds_read_b128 v[206:209], v147 offset:22528
	ds_read_b128 v[210:213], v147 offset:23552
	global_load_lds_dwordx4 v[140:141], off
	s_add_i32 m0, s54, 0x2000
	s_add_u32 s54, s30, 0x80000
	v_lshl_add_u64 v[214:215], s[30:31], 0, v[128:129]
	s_addc_u32 s55, s31, 0
	s_add_i32 s56, s46, s1
	global_load_lds_dwordx4 v[214:215], off
	v_lshl_add_u64 v[216:217], s[54:55], 0, v[132:133]
	s_mov_b32 m0, s56
	v_lshl_add_u64 v[218:219], s[34:35], 0, v[130:131]
	global_load_lds_dwordx4 v[216:217], off
	v_lshl_add_u64 v[216:217], s[54:55], 0, v[128:129]
	s_add_i32 m0, s56, 0x2000
	s_nop 0
	global_load_lds_dwordx4 v[216:217], off
	v_lshl_add_u64 v[216:217], s[34:35], 0, v[134:135]
	s_mov_b32 m0, s27
	s_nop 0
	global_load_lds_dwordx4 v[216:217], off
	s_mov_b32 m0, s39
	s_nop 0
	global_load_lds_dwordx4 v[218:219], off
	s_waitcnt vmcnt(8)
	s_waitcnt lgkmcnt(0)
	s_barrier
; #define PG8_STAGE(bufoff, gbase, voff) do { _Pragma("unroll") for (int _i = 0; _i < 2; ++_i) \
;         __builtin_amdgcn_global_load_lds((const unsigned*)((const char*)(gbase) + (voff)[_i]), (LAS unsigned*)(lds + (bufoff) + ldsw + _i * 8192), 16, 0, 0); } while (0)
; #define PG8_LDA(dst, b, h) do { _Pragma("unroll") for (int m = 0; m < 4; ++m) _Pragma("unroll") for (int k = 0; k < 2; ++k) dst[m][k] = *(const LAS bf16x8*)(lds + PG8_SA(b, h) + aoff + m * 2048 + k * 1024); } while (0)
; #define PG8_LDB(dst, b, h) do { _Pragma("unroll") for (int n = 0; n < 2; ++n) _Pragma("unroll") for (int k = 0; k < 2; ++k) dst[n][k] = *(const LAS bf16x8*)(lds + PG8_SB(b, h) + boff + n * 2048 + k * 1024); } while (0)
; #define PG8_MMA(ai, bj, At, Bt) do { __builtin_amdgcn_s_setprio(1); _Pragma("unroll") for (int m = 0; m < 4; ++m) _Pragma("unroll") for (int n = 0; n < 2; ++n) _Pragma("unroll") for (int k = 0; k < 2; ++k) \
;         acc[ai][bj][m][n] = __builtin_amdgcn_mfma_f32_16x16x32_bf16(Bt[n][k], At[m][k], acc[ai][bj][m][n], 0, 0, 0); __builtin_amdgcn_s_setprio(0); } while (0)
; #define PG8_WAIT_V(n) asm volatile("s_waitcnt vmcnt(" #n ")" ::: "memory")
; #define PG8_WAIT_L(n) asm volatile("s_waitcnt lgkmcnt(" #n ")" ::: "memory")
; #define PG8_BAR __builtin_amdgcn_s_barrier()
; #define PG8_SCHED __builtin_amdgcn_sched_barrier(0)
; template <class Epi, bool ALIGN_EPI>
; __device__ __forceinline__ void gemm_phase(LAS unsigned char* lds, const Gemm g, const StaticOrder& S, const Epi& E) {
;     ...
;             PG8_WAIT_V(8); PG8_WAIT_L(0); PG8_BAR; PG8_MMA(1, 0, At, B0); PG8_MMA(1, 1, At, B1); PG8_BAR; PG8_SCHED;
;             PG8_LDB(B0, 1, 0); PG8_LDB(B1, 1, 1); PG8_SCHED; PG8_LDA(At, 1, 0); PG8_STAGE(PG8_SA(0, 1), a2 + hA, voffA);
;             PG8_WAIT_V(8); PG8_WAIT_L(0); PG8_BAR; PG8_MMA(0, 0, At, B0); PG8_MMA(0, 1, At, B1); PG8_BAR; PG8_SCHED;
	s_setprio 1
	s_waitcnt lgkmcnt(0)
	v_mfma_f32_16x16x32_bf16 v[60:63], v[148:151], v[180:183], v[60:63]
	v_mfma_f32_16x16x32_bf16 v[60:63], v[152:155], v[184:187], v[60:63]
	v_mfma_f32_16x16x32_bf16 v[56:59], v[156:159], v[180:183], v[56:59]
	v_mfma_f32_16x16x32_bf16 v[56:59], v[160:163], v[184:187], v[56:59]
	v_mfma_f32_16x16x32_bf16 v[52:55], v[148:151], v[188:191], v[52:55]
	v_mfma_f32_16x16x32_bf16 v[52:55], v[152:155], v[194:197], v[52:55]
	v_mfma_f32_16x16x32_bf16 v[44:47], v[156:159], v[188:191], v[44:47]
	v_mfma_f32_16x16x32_bf16 v[44:47], v[160:163], v[194:197], v[44:47]
	v_mfma_f32_16x16x32_bf16 v[36:39], v[148:151], v[198:201], v[36:39]
	v_mfma_f32_16x16x32_bf16 v[36:39], v[152:155], v[202:205], v[36:39]
	v_mfma_f32_16x16x32_bf16 v[28:31], v[156:159], v[198:201], v[28:31]
	v_mfma_f32_16x16x32_bf16 v[28:31], v[160:163], v[202:205], v[28:31]
	v_mfma_f32_16x16x32_bf16 v[20:23], v[148:151], v[206:209], v[20:23]
	v_mfma_f32_16x16x32_bf16 v[20:23], v[152:155], v[210:213], v[20:23]
	v_mfma_f32_16x16x32_bf16 v[12:15], v[156:159], v[206:209], v[12:15]
	v_mfma_f32_16x16x32_bf16 v[12:15], v[160:163], v[210:213], v[12:15]
	s_setprio 0
	s_setprio 1
	v_mfma_f32_16x16x32_bf16 v[48:51], v[164:167], v[180:183], v[48:51]
	v_mfma_f32_16x16x32_bf16 v[48:51], v[168:171], v[184:187], v[48:51]
	v_mfma_f32_16x16x32_bf16 v[40:43], v[172:175], v[180:183], v[40:43]
	v_mfma_f32_16x16x32_bf16 v[40:43], v[176:179], v[184:187], v[40:43]
	v_mfma_f32_16x16x32_bf16 v[32:35], v[164:167], v[188:191], v[32:35]
	v_mfma_f32_16x16x32_bf16 v[32:35], v[168:171], v[194:197], v[32:35]
	v_mfma_f32_16x16x32_bf16 v[24:27], v[172:175], v[188:191], v[24:27]
	v_mfma_f32_16x16x32_bf16 v[24:27], v[176:179], v[194:197], v[24:27]
	v_mfma_f32_16x16x32_bf16 v[16:19], v[164:167], v[198:201], v[16:19]
	v_mfma_f32_16x16x32_bf16 v[16:19], v[168:171], v[202:205], v[16:19]
	v_mfma_f32_16x16x32_bf16 v[8:11], v[172:175], v[198:201], v[8:11]
	v_mfma_f32_16x16x32_bf16 v[8:11], v[176:179], v[202:205], v[8:11]
	v_mfma_f32_16x16x32_bf16 v[4:7], v[164:167], v[206:209], v[4:7]
	v_mfma_f32_16x16x32_bf16 v[4:7], v[168:171], v[210:213], v[4:7]
	v_mfma_f32_16x16x32_bf16 v[0:3], v[172:175], v[206:209], v[0:3]
	v_mfma_f32_16x16x32_bf16 v[0:3], v[176:179], v[210:213], v[0:3]
	s_setprio 0
	s_barrier
	s_add_i32 s54, 0, 0x18000
	s_add_i32 s55, 0, 0x1c000
	v_add_u32_e32 v160, s54, v143
	v_add_u32_e32 v176, s55, v143
	ds_read_b128 v[148:151], v160
	ds_read_b128 v[152:155], v160 offset:1024
	ds_read_b128 v[156:159], v160 offset:2048
	ds_read_b128 v[160:163], v160 offset:3072
	ds_read_b128 v[164:167], v176
	ds_read_b128 v[168:171], v176 offset:1024
	ds_read_b128 v[172:175], v176 offset:2048
	ds_read_b128 v[176:179], v176 offset:3072
	s_add_u32 s34, s34, 0x80000
	s_addc_u32 s35, s35, 0
	s_mov_b32 m0, s40
	v_lshl_add_u64 v[220:221], s[34:35], 0, v[134:135]
	ds_read_b128 v[180:183], v147 offset:32768
	ds_read_b128 v[184:187], v147 offset:33792
	ds_read_b128 v[188:191], v147 offset:34816
	ds_read_b128 v[194:197], v147 offset:35840
	ds_read_b128 v[198:201], v147 offset:36864
	ds_read_b128 v[202:205], v147 offset:37888
	ds_read_b128 v[206:209], v147 offset:38912
	ds_read_b128 v[210:213], v147 offset:39936
	global_load_lds_dwordx4 v[220:221], off
	v_lshl_add_u64 v[220:221], s[34:35], 0, v[130:131]
	s_mov_b32 m0, s41
	s_nop 0
	global_load_lds_dwordx4 v[220:221], off
	s_waitcnt vmcnt(8)
	s_waitcnt lgkmcnt(0)
	s_barrier
	s_setprio 1
	s_waitcnt lgkmcnt(0)
	v_mfma_f32_16x16x32_bf16 v[124:127], v[148:151], v[180:183], v[124:127]
	v_mfma_f32_16x16x32_bf16 v[124:127], v[152:155], v[184:187], v[124:127]
	v_mfma_f32_16x16x32_bf16 v[120:123], v[156:159], v[180:183], v[120:123]
	v_mfma_f32_16x16x32_bf16 v[120:123], v[160:163], v[184:187], v[120:123]
	v_mfma_f32_16x16x32_bf16 v[116:119], v[148:151], v[188:191], v[116:119]
	v_mfma_f32_16x16x32_bf16 v[116:119], v[152:155], v[194:197], v[116:119]
	v_mfma_f32_16x16x32_bf16 v[108:111], v[156:159], v[188:191], v[108:111]
	v_mfma_f32_16x16x32_bf16 v[108:111], v[160:163], v[194:197], v[108:111]
	v_mfma_f32_16x16x32_bf16 v[100:103], v[148:151], v[198:201], v[100:103]
	v_mfma_f32_16x16x32_bf16 v[100:103], v[152:155], v[202:205], v[100:103]
	v_mfma_f32_16x16x32_bf16 v[92:95], v[156:159], v[198:201], v[92:95]
	v_mfma_f32_16x16x32_bf16 v[92:95], v[160:163], v[202:205], v[92:95]
	v_mfma_f32_16x16x32_bf16 v[84:87], v[148:151], v[206:209], v[84:87]
	v_mfma_f32_16x16x32_bf16 v[84:87], v[152:155], v[210:213], v[84:87]
	v_mfma_f32_16x16x32_bf16 v[76:79], v[156:159], v[206:209], v[76:79]
	v_mfma_f32_16x16x32_bf16 v[76:79], v[160:163], v[210:213], v[76:79]
	s_setprio 0
	s_setprio 1
	v_mfma_f32_16x16x32_bf16 v[112:115], v[164:167], v[180:183], v[112:115]
	v_mfma_f32_16x16x32_bf16 v[112:115], v[168:171], v[184:187], v[112:115]
	v_mfma_f32_16x16x32_bf16 v[104:107], v[172:175], v[180:183], v[104:107]
	v_mfma_f32_16x16x32_bf16 v[104:107], v[176:179], v[184:187], v[104:107]
	v_mfma_f32_16x16x32_bf16 v[96:99], v[164:167], v[188:191], v[96:99]
	v_mfma_f32_16x16x32_bf16 v[96:99], v[168:171], v[194:197], v[96:99]
	v_mfma_f32_16x16x32_bf16 v[88:91], v[172:175], v[188:191], v[88:91]
	v_mfma_f32_16x16x32_bf16 v[88:91], v[176:179], v[194:197], v[88:91]
	v_mfma_f32_16x16x32_bf16 v[80:83], v[164:167], v[198:201], v[80:83]
	v_mfma_f32_16x16x32_bf16 v[80:83], v[168:171], v[202:205], v[80:83]
	v_mfma_f32_16x16x32_bf16 v[72:75], v[172:175], v[198:201], v[72:75]
	v_mfma_f32_16x16x32_bf16 v[72:75], v[176:179], v[202:205], v[72:75]
	v_mfma_f32_16x16x32_bf16 v[68:71], v[164:167], v[206:209], v[68:71]
	v_mfma_f32_16x16x32_bf16 v[68:71], v[168:171], v[210:213], v[68:71]
	v_mfma_f32_16x16x32_bf16 v[64:67], v[172:175], v[206:209], v[64:67]
	v_mfma_f32_16x16x32_bf16 v[64:67], v[176:179], v[210:213], v[64:67]
	s_setprio 0
	s_barrier
; #define PG8_STAGE(bufoff, gbase, voff) do { _Pragma("unroll") for (int _i = 0; _i < 2; ++_i) \
;         __builtin_amdgcn_global_load_lds((const unsigned*)((const char*)(gbase) + (voff)[_i]), (LAS unsigned*)(lds + (bufoff) + ldsw + _i * 8192), 16, 0, 0); } while (0)
; #define PG8_LDA(dst, b, h) do { _Pragma("unroll") for (int m = 0; m < 4; ++m) _Pragma("unroll") for (int k = 0; k < 2; ++k) dst[m][k] = *(const LAS bf16x8*)(lds + PG8_SA(b, h) + aoff + m * 2048 + k * 1024); } while (0)
; #define PG8_MMA(ai, bj, At, Bt) do { __builtin_amdgcn_s_setprio(1); _Pragma("unroll") for (int m = 0; m < 4; ++m) _Pragma("unroll") for (int n = 0; n < 2; ++n) _Pragma("unroll") for (int k = 0; k < 2; ++k) \
;         acc[ai][bj][m][n] = __builtin_amdgcn_mfma_f32_16x16x32_bf16(Bt[n][k], At[m][k], acc[ai][bj][m][n], 0, 0, 0); __builtin_amdgcn_s_setprio(0); } while (0)
; #define PG8_WAIT_V(n) asm volatile("s_waitcnt vmcnt(" #n ")" ::: "memory")
; #define PG8_WAIT_L(n) asm volatile("s_waitcnt lgkmcnt(" #n ")" ::: "memory")
; #define PG8_BAR __builtin_amdgcn_s_barrier()
; #define PG8_SCHED __builtin_amdgcn_sched_barrier(0)
; template <class Epi, bool ALIGN_EPI>
; __device__ __forceinline__ void gemm_phase(LAS unsigned char* lds, const Gemm g, const StaticOrder& S, const Epi& E) {
;     ...
;             PG8_LDA(At, 1, 1); PG8_STAGE(PG8_SB(1, 0), b3, voffB); PG8_STAGE(PG8_SB(1, 1), b3 + hB, voffB); PG8_STAGE(PG8_SA(1, 0), a3, voffA);
;             PG8_WAIT_V(8); PG8_WAIT_L(0); PG8_BAR; PG8_MMA(1, 0, At, B0); PG8_MMA(1, 1, At, B1); PG8_BAR; PG8_SCHED;
;         }
;         if constexpr (ALIGN_EPI) { if (wr == 0) PG8_BAR; }
	s_add_i32 s34, s54, s1
	v_lshl_add_u64 v[140:141], v[140:141], 0, s[10:11]
	s_mov_b32 m0, s34
	ds_read_b128 v[180:183], v147 offset:49152
	ds_read_b128 v[184:187], v147 offset:50176
	ds_read_b128 v[188:191], v147 offset:51200
	ds_read_b128 v[194:197], v147 offset:52224
	ds_read_b128 v[198:201], v147 offset:53248
	ds_read_b128 v[202:205], v147 offset:54272
	ds_read_b128 v[206:209], v147 offset:55296
	ds_read_b128 v[210:213], v147 offset:56320
	global_load_lds_dwordx4 v[140:141], off
	s_add_i32 m0, s34, 0x2000
	s_add_u32 s30, s30, 0x80080
	v_lshl_add_u64 v[140:141], v[214:215], 0, s[10:11]
	s_addc_u32 s31, s31, 0
	s_add_i32 s34, s55, s1
	global_load_lds_dwordx4 v[140:141], off
	v_lshl_add_u64 v[140:141], s[30:31], 0, v[132:133]
	s_mov_b32 m0, s34
	s_nop 0
	global_load_lds_dwordx4 v[140:141], off
	v_lshl_add_u64 v[140:141], s[30:31], 0, v[128:129]
	s_add_i32 m0, s34, 0x2000
	s_nop 0
	global_load_lds_dwordx4 v[140:141], off
	v_lshl_add_u64 v[140:141], v[216:217], 0, s[10:11]
	s_mov_b32 m0, s42
	s_nop 0
	global_load_lds_dwordx4 v[140:141], off
	v_lshl_add_u64 v[140:141], v[218:219], 0, s[10:11]
	s_mov_b32 m0, s43
	s_nop 0
	global_load_lds_dwordx4 v[140:141], off
	s_waitcnt vmcnt(8)
	s_waitcnt lgkmcnt(0)
	s_barrier
	s_setprio 1
	s_waitcnt lgkmcnt(0)
	v_mfma_f32_16x16x32_bf16 v[60:63], v[148:151], v[180:183], v[60:63]
	v_mfma_f32_16x16x32_bf16 v[60:63], v[152:155], v[184:187], v[60:63]
	v_mfma_f32_16x16x32_bf16 v[56:59], v[156:159], v[180:183], v[56:59]
	v_mfma_f32_16x16x32_bf16 v[56:59], v[160:163], v[184:187], v[56:59]
	v_mfma_f32_16x16x32_bf16 v[52:55], v[148:151], v[188:191], v[52:55]
	v_mfma_f32_16x16x32_bf16 v[52:55], v[152:155], v[194:197], v[52:55]
	v_mfma_f32_16x16x32_bf16 v[44:47], v[156:159], v[188:191], v[44:47]
	v_mfma_f32_16x16x32_bf16 v[44:47], v[160:163], v[194:197], v[44:47]
	v_mfma_f32_16x16x32_bf16 v[36:39], v[148:151], v[198:201], v[36:39]
	v_mfma_f32_16x16x32_bf16 v[36:39], v[152:155], v[202:205], v[36:39]
	v_mfma_f32_16x16x32_bf16 v[28:31], v[156:159], v[198:201], v[28:31]
	v_mfma_f32_16x16x32_bf16 v[28:31], v[160:163], v[202:205], v[28:31]
	v_mfma_f32_16x16x32_bf16 v[20:23], v[148:151], v[206:209], v[20:23]
	v_mfma_f32_16x16x32_bf16 v[20:23], v[152:155], v[210:213], v[20:23]
	v_mfma_f32_16x16x32_bf16 v[12:15], v[156:159], v[206:209], v[12:15]
	v_mfma_f32_16x16x32_bf16 v[12:15], v[160:163], v[210:213], v[12:15]
	s_setprio 0
	s_setprio 1
	v_mfma_f32_16x16x32_bf16 v[48:51], v[164:167], v[180:183], v[48:51]
	v_mfma_f32_16x16x32_bf16 v[48:51], v[168:171], v[184:187], v[48:51]
	v_mfma_f32_16x16x32_bf16 v[40:43], v[172:175], v[180:183], v[40:43]
	v_mfma_f32_16x16x32_bf16 v[40:43], v[176:179], v[184:187], v[40:43]
	v_mfma_f32_16x16x32_bf16 v[32:35], v[164:167], v[188:191], v[32:35]
	v_mfma_f32_16x16x32_bf16 v[32:35], v[168:171], v[194:197], v[32:35]
	v_mfma_f32_16x16x32_bf16 v[24:27], v[172:175], v[188:191], v[24:27]
	v_mfma_f32_16x16x32_bf16 v[24:27], v[176:179], v[194:197], v[24:27]
	v_mfma_f32_16x16x32_bf16 v[16:19], v[164:167], v[198:201], v[16:19]
	v_mfma_f32_16x16x32_bf16 v[16:19], v[168:171], v[202:205], v[16:19]
	v_mfma_f32_16x16x32_bf16 v[8:11], v[172:175], v[198:201], v[8:11]
	v_mfma_f32_16x16x32_bf16 v[8:11], v[176:179], v[202:205], v[8:11]
	v_mfma_f32_16x16x32_bf16 v[4:7], v[164:167], v[206:209], v[4:7]
	v_mfma_f32_16x16x32_bf16 v[4:7], v[168:171], v[210:213], v[4:7]
	v_mfma_f32_16x16x32_bf16 v[0:3], v[172:175], v[206:209], v[0:3]
	v_mfma_f32_16x16x32_bf16 v[0:3], v[176:179], v[210:213], v[0:3]
	s_setprio 0
	s_barrier
	s_add_i32 s53, s53, 2
	s_add_u32 s28, s28, 0x100
	s_addc_u32 s29, s29, 0
	s_add_u32 s51, s51, 0x100
	s_addc_u32 s52, s52, 0
	s_cmp_gt_u32 s53, 29
	s_cbranch_scc0 .LBB0_419
	s_and_b64 vcc, exec, s[14:15]
	s_cbranch_vccz .LBB0_422
	s_barrier

; #define PG8_STAGE(bufoff, gbase, voff) do { _Pragma("unroll") for (int _i = 0; _i < 2; ++_i) \
;         __builtin_amdgcn_global_load_lds((const unsigned*)((const char*)(gbase) + (voff)[_i]), (LAS unsigned*)(lds + (bufoff) + ldsw + _i * 8192), 16, 0, 0); } while (0)
; #define PG8_LDA(dst, b, h) do { _Pragma("unroll") for (int m = 0; m < 4; ++m) _Pragma("unroll") for (int k = 0; k < 2; ++k) dst[m][k] = *(const LAS bf16x8*)(lds + PG8_SA(b, h) + aoff + m * 2048 + k * 1024); } while (0)
; #define PG8_LDB(dst, b, h) do { _Pragma("unroll") for (int n = 0; n < 2; ++n) _Pragma("unroll") for (int k = 0; k < 2; ++k) dst[n][k] = *(const LAS bf16x8*)(lds + PG8_SB(b, h) + boff + n * 2048 + k * 1024); } while (0)
; #define PG8_MMA(ai, bj, At, Bt) do { __builtin_amdgcn_s_setprio(1); _Pragma("unroll") for (int m = 0; m < 4; ++m) _Pragma("unroll") for (int n = 0; n < 2; ++n) _Pragma("unroll") for (int k = 0; k < 2; ++k) \
;         acc[ai][bj][m][n] = __builtin_amdgcn_mfma_f32_16x16x32_bf16(Bt[n][k], At[m][k], acc[ai][bj][m][n], 0, 0, 0); __builtin_amdgcn_s_setprio(0); } while (0)
; #define PG8_WAIT_V(n) asm volatile("s_waitcnt vmcnt(" #n ")" ::: "memory")
; #define PG8_WAIT_L(n) asm volatile("s_waitcnt lgkmcnt(" #n ")" ::: "memory")
; #define PG8_BAR __builtin_amdgcn_s_barrier()
; #define PG8_SCHED __builtin_amdgcn_sched_barrier(0)
; template <class Epi, bool ALIGN_EPI>
; __device__ __forceinline__ void gemm_phase(LAS unsigned char* lds, const Gemm g, const StaticOrder& S, const Epi& E) {
;     ...
;         for (int t = 0; t < nt; t += 2) {
;             const bool last = (t == nt - 2);
;             const char* a1 = cA + (size_t)(t + 1) * kstep;
;             const char* a2 = last ? nA : cA + (size_t)(t + 2) * kstep; const char* b2 = last ? nB : cB + (size_t)(t + 2) * kstep;
;             const char* a3 = a2 + kstep; const char* b3 = b2 + kstep;
;             PG8_LDB(B0, 0, 0); PG8_LDB(B1, 0, 1); PG8_SCHED; PG8_LDA(At, 0, 0); PG8_STAGE(PG8_SA(1, 1), a1 + hA, voffA);
;             PG8_WAIT_V(8); PG8_WAIT_L(0); PG8_BAR; PG8_MMA(0, 0, At, B0); PG8_MMA(0, 1, At, B1); PG8_BAR; PG8_SCHED;
;             PG8_LDA(At, 0, 1); PG8_STAGE(PG8_SB(0, 0), b2, voffB); PG8_STAGE(PG8_SB(0, 1), b2 + hB, voffB); PG8_STAGE(PG8_SA(0, 0), a2, voffA);
;             PG8_WAIT_V(8); PG8_WAIT_L(0); PG8_BAR; PG8_MMA(1, 0, At, B0); PG8_MMA(1, 1, At, B1); PG8_BAR; PG8_SCHED;
.LBB0_775:
	ds_read_b128 v[128:131], v196
	ds_read_b128 v[132:135], v196 offset:1024
	ds_read_b128 v[136:139], v196 offset:2048
	ds_read_b128 v[140:143], v196 offset:3072
	ds_read_b128 v[144:147], v197
	ds_read_b128 v[148:151], v197 offset:1024
	ds_read_b128 v[152:155], v197 offset:2048
	ds_read_b128 v[156:159], v197 offset:3072
	s_add_u32 s37, s40, 0xfff80080
	s_addc_u32 s38, s41, -1
	s_cmp_eq_u32 s29, 28
	s_cselect_b32 s45, s0, s38
	s_cselect_b32 s44, s1, s37
	s_cselect_b32 s43, s2, s27
	s_cselect_b32 s42, s3, s9
	v_lshl_add_u64 v[216:217], s[40:41], 0, v[168:169]
	s_add_i32 m0, s50, 0xc000
	ds_read_b128 v[176:179], v198
	ds_read_b128 v[180:183], v198 offset:1024
	ds_read_b128 v[184:187], v198 offset:2048
	ds_read_b128 v[188:191], v198 offset:3072
	ds_read_b128 v[200:203], v198 offset:4096
	ds_read_b128 v[204:207], v198 offset:5120
	ds_read_b128 v[208:211], v198 offset:6144
	ds_read_b128 v[212:215], v198 offset:7168
	global_load_lds_dwordx4 v[216:217], off
	v_lshl_add_u64 v[216:217], s[40:41], 0, v[170:171]
	s_add_i32 m0, s50, 0xe000
	s_nop 0
	global_load_lds_dwordx4 v[216:217], off
	s_waitcnt vmcnt(8)
	s_waitcnt lgkmcnt(0)
	s_barrier
	s_setprio 1
	s_waitcnt lgkmcnt(0)
	v_mfma_f32_16x16x32_bf16 v[124:127], v[128:131], v[176:179], v[124:127]
	v_mfma_f32_16x16x32_bf16 v[124:127], v[132:135], v[180:183], v[124:127]
	v_mfma_f32_16x16x32_bf16 v[120:123], v[136:139], v[176:179], v[120:123]
	v_mfma_f32_16x16x32_bf16 v[120:123], v[140:143], v[180:183], v[120:123]
	v_mfma_f32_16x16x32_bf16 v[108:111], v[128:131], v[184:187], v[108:111]
	v_mfma_f32_16x16x32_bf16 v[108:111], v[132:135], v[188:191], v[108:111]
	v_mfma_f32_16x16x32_bf16 v[104:107], v[136:139], v[184:187], v[104:107]
	v_mfma_f32_16x16x32_bf16 v[104:107], v[140:143], v[188:191], v[104:107]
	v_mfma_f32_16x16x32_bf16 v[92:95], v[128:131], v[200:203], v[92:95]
	v_mfma_f32_16x16x32_bf16 v[92:95], v[132:135], v[204:207], v[92:95]
	v_mfma_f32_16x16x32_bf16 v[88:91], v[136:139], v[200:203], v[88:91]
	v_mfma_f32_16x16x32_bf16 v[88:91], v[140:143], v[204:207], v[88:91]
	v_mfma_f32_16x16x32_bf16 v[76:79], v[128:131], v[208:211], v[76:79]
	v_mfma_f32_16x16x32_bf16 v[76:79], v[132:135], v[212:215], v[76:79]
	v_mfma_f32_16x16x32_bf16 v[72:75], v[136:139], v[208:211], v[72:75]
	v_mfma_f32_16x16x32_bf16 v[72:75], v[140:143], v[212:215], v[72:75]
	s_setprio 0
	s_setprio 1
	v_mfma_f32_16x16x32_bf16 v[116:119], v[144:147], v[176:179], v[116:119]
	v_mfma_f32_16x16x32_bf16 v[116:119], v[148:151], v[180:183], v[116:119]
	v_mfma_f32_16x16x32_bf16 v[112:115], v[152:155], v[176:179], v[112:115]
	v_mfma_f32_16x16x32_bf16 v[112:115], v[156:159], v[180:183], v[112:115]
	v_mfma_f32_16x16x32_bf16 v[100:103], v[144:147], v[184:187], v[100:103]
	v_mfma_f32_16x16x32_bf16 v[100:103], v[148:151], v[188:191], v[100:103]
	v_mfma_f32_16x16x32_bf16 v[96:99], v[152:155], v[184:187], v[96:99]
	v_mfma_f32_16x16x32_bf16 v[96:99], v[156:159], v[188:191], v[96:99]
	v_mfma_f32_16x16x32_bf16 v[84:87], v[144:147], v[200:203], v[84:87]
	v_mfma_f32_16x16x32_bf16 v[84:87], v[148:151], v[204:207], v[84:87]
	v_mfma_f32_16x16x32_bf16 v[80:83], v[152:155], v[200:203], v[80:83]
	v_mfma_f32_16x16x32_bf16 v[80:83], v[156:159], v[204:207], v[80:83]
	v_mfma_f32_16x16x32_bf16 v[68:71], v[144:147], v[208:211], v[68:71]
	v_mfma_f32_16x16x32_bf16 v[68:71], v[148:151], v[212:215], v[68:71]
	v_mfma_f32_16x16x32_bf16 v[64:67], v[152:155], v[208:211], v[64:67]
	v_mfma_f32_16x16x32_bf16 v[64:67], v[156:159], v[212:215], v[64:67]
	s_setprio 0
	s_barrier
	s_add_i32 s37, s60, s49
	v_lshl_add_u64 v[216:217], s[42:43], 0, v[162:163]
	s_mov_b32 m0, s37
	ds_read_b128 v[176:179], v198 offset:16384
	ds_read_b128 v[180:183], v198 offset:17408
	ds_read_b128 v[184:187], v198 offset:18432
	ds_read_b128 v[188:191], v198 offset:19456
	ds_read_b128 v[200:203], v198 offset:20480
	ds_read_b128 v[204:207], v198 offset:21504
	ds_read_b128 v[208:211], v198 offset:22528
	ds_read_b128 v[212:215], v198 offset:23552
	global_load_lds_dwordx4 v[216:217], off
	s_add_i32 m0, s37, 0x2000
	s_add_u32 s38, s42, 0x80000
	v_lshl_add_u64 v[218:219], s[42:43], 0, v[166:167]
	s_addc_u32 s39, s43, 0
	s_add_i32 s37, s61, s49
	global_load_lds_dwordx4 v[218:219], off
	v_lshl_add_u64 v[220:221], s[38:39], 0, v[162:163]
	s_mov_b32 m0, s37
	v_lshl_add_u64 v[222:223], s[44:45], 0, v[164:165]
	global_load_lds_dwordx4 v[220:221], off
	v_lshl_add_u64 v[220:221], s[38:39], 0, v[166:167]
	s_add_i32 m0, s37, 0x2000
	s_nop 0
	global_load_lds_dwordx4 v[220:221], off
	v_lshl_add_u64 v[220:221], s[44:45], 0, v[160:161]
	s_mov_b32 m0, s50
	s_nop 0
	global_load_lds_dwordx4 v[220:221], off
	s_mov_b32 m0, s51
	s_nop 0
	global_load_lds_dwordx4 v[222:223], off
	s_waitcnt vmcnt(8)
	s_waitcnt lgkmcnt(0)
	s_barrier
; #define PG8_STAGE(bufoff, gbase, voff) do { _Pragma("unroll") for (int _i = 0; _i < 2; ++_i) \
;         __builtin_amdgcn_global_load_lds((const unsigned*)((const char*)(gbase) + (voff)[_i]), (LAS unsigned*)(lds + (bufoff) + ldsw + _i * 8192), 16, 0, 0); } while (0)
; #define PG8_LDA(dst, b, h) do { _Pragma("unroll") for (int m = 0; m < 4; ++m) _Pragma("unroll") for (int k = 0; k < 2; ++k) dst[m][k] = *(const LAS bf16x8*)(lds + PG8_SA(b, h) + aoff + m * 2048 + k * 1024); } while (0)
; #define PG8_LDB(dst, b, h) do { _Pragma("unroll") for (int n = 0; n < 2; ++n) _Pragma("unroll") for (int k = 0; k < 2; ++k) dst[n][k] = *(const LAS bf16x8*)(lds + PG8_SB(b, h) + boff + n * 2048 + k * 1024); } while (0)
; #define PG8_MMA(ai, bj, At, Bt) do { __builtin_amdgcn_s_setprio(1); _Pragma("unroll") for (int m = 0; m < 4; ++m) _Pragma("unroll") for (int n = 0; n < 2; ++n) _Pragma("unroll") for (int k = 0; k < 2; ++k) \
;         acc[ai][bj][m][n] = __builtin_amdgcn_mfma_f32_16x16x32_bf16(Bt[n][k], At[m][k], acc[ai][bj][m][n], 0, 0, 0); __builtin_amdgcn_s_setprio(0); } while (0)
; #define PG8_WAIT_V(n) asm volatile("s_waitcnt vmcnt(" #n ")" ::: "memory")
; #define PG8_WAIT_L(n) asm volatile("s_waitcnt lgkmcnt(" #n ")" ::: "memory")
; #define PG8_BAR __builtin_amdgcn_s_barrier()
; #define PG8_SCHED __builtin_amdgcn_sched_barrier(0)
; template <class Epi, bool ALIGN_EPI>
; __device__ __forceinline__ void gemm_phase(LAS unsigned char* lds, const Gemm g, const StaticOrder& S, const Epi& E) {
;     ...
;             PG8_WAIT_V(8); PG8_WAIT_L(0); PG8_BAR; PG8_MMA(1, 0, At, B0); PG8_MMA(1, 1, At, B1); PG8_BAR; PG8_SCHED;
;             PG8_LDB(B0, 1, 0); PG8_LDB(B1, 1, 1); PG8_SCHED; PG8_LDA(At, 1, 0); PG8_STAGE(PG8_SA(0, 1), a2 + hA, voffA);
;             PG8_WAIT_V(8); PG8_WAIT_L(0); PG8_BAR; PG8_MMA(0, 0, At, B0); PG8_MMA(0, 1, At, B1); PG8_BAR; PG8_SCHED;
	s_setprio 1
	s_waitcnt lgkmcnt(0)
	v_mfma_f32_16x16x32_bf16 v[60:63], v[128:131], v[176:179], v[60:63]
	v_mfma_f32_16x16x32_bf16 v[60:63], v[132:135], v[180:183], v[60:63]
	v_mfma_f32_16x16x32_bf16 v[56:59], v[136:139], v[176:179], v[56:59]
	v_mfma_f32_16x16x32_bf16 v[56:59], v[140:143], v[180:183], v[56:59]
	v_mfma_f32_16x16x32_bf16 v[44:47], v[128:131], v[184:187], v[44:47]
	v_mfma_f32_16x16x32_bf16 v[44:47], v[132:135], v[188:191], v[44:47]
	v_mfma_f32_16x16x32_bf16 v[40:43], v[136:139], v[184:187], v[40:43]
	v_mfma_f32_16x16x32_bf16 v[40:43], v[140:143], v[188:191], v[40:43]
	v_mfma_f32_16x16x32_bf16 v[28:31], v[128:131], v[200:203], v[28:31]
	v_mfma_f32_16x16x32_bf16 v[28:31], v[132:135], v[204:207], v[28:31]
	v_mfma_f32_16x16x32_bf16 v[24:27], v[136:139], v[200:203], v[24:27]
	v_mfma_f32_16x16x32_bf16 v[24:27], v[140:143], v[204:207], v[24:27]
	v_mfma_f32_16x16x32_bf16 v[16:19], v[128:131], v[208:211], v[16:19]
	v_mfma_f32_16x16x32_bf16 v[16:19], v[132:135], v[212:215], v[16:19]
	v_mfma_f32_16x16x32_bf16 v[8:11], v[136:139], v[208:211], v[8:11]
	v_mfma_f32_16x16x32_bf16 v[8:11], v[140:143], v[212:215], v[8:11]
	s_setprio 0
	s_setprio 1
	v_mfma_f32_16x16x32_bf16 v[52:55], v[144:147], v[176:179], v[52:55]
	v_mfma_f32_16x16x32_bf16 v[52:55], v[148:151], v[180:183], v[52:55]
	v_mfma_f32_16x16x32_bf16 v[48:51], v[152:155], v[176:179], v[48:51]
	v_mfma_f32_16x16x32_bf16 v[48:51], v[156:159], v[180:183], v[48:51]
	v_mfma_f32_16x16x32_bf16 v[36:39], v[144:147], v[184:187], v[36:39]
	v_mfma_f32_16x16x32_bf16 v[36:39], v[148:151], v[188:191], v[36:39]
	v_mfma_f32_16x16x32_bf16 v[32:35], v[152:155], v[184:187], v[32:35]
	v_mfma_f32_16x16x32_bf16 v[32:35], v[156:159], v[188:191], v[32:35]
	v_mfma_f32_16x16x32_bf16 v[20:23], v[144:147], v[200:203], v[20:23]
	v_mfma_f32_16x16x32_bf16 v[20:23], v[148:151], v[204:207], v[20:23]
	v_mfma_f32_16x16x32_bf16 v[12:15], v[152:155], v[200:203], v[12:15]
	v_mfma_f32_16x16x32_bf16 v[12:15], v[156:159], v[204:207], v[12:15]
	v_mfma_f32_16x16x32_bf16 v[4:7], v[144:147], v[208:211], v[4:7]
	v_mfma_f32_16x16x32_bf16 v[4:7], v[148:151], v[212:215], v[4:7]
	v_mfma_f32_16x16x32_bf16 v[0:3], v[152:155], v[208:211], v[0:3]
	v_mfma_f32_16x16x32_bf16 v[0:3], v[156:159], v[212:215], v[0:3]
	s_setprio 0
	s_barrier
	s_add_i32 s37, 0, 0x18000
	s_add_i32 s63, 0, 0x1c000
	v_add_u32_e32 v140, s37, v194
	v_add_u32_e32 v156, s63, v194
	ds_read_b128 v[128:131], v140
	ds_read_b128 v[132:135], v140 offset:1024
	ds_read_b128 v[136:139], v140 offset:2048
	ds_read_b128 v[140:143], v140 offset:3072
	ds_read_b128 v[144:147], v156
	ds_read_b128 v[148:151], v156 offset:1024
	ds_read_b128 v[152:155], v156 offset:2048
	ds_read_b128 v[156:159], v156 offset:3072
	s_add_u32 s38, s44, 0x80000
	s_addc_u32 s39, s45, 0
	s_mov_b32 m0, s52
	v_lshl_add_u64 v[224:225], s[38:39], 0, v[160:161]
	ds_read_b128 v[176:179], v198 offset:32768
	ds_read_b128 v[180:183], v198 offset:33792
	ds_read_b128 v[184:187], v198 offset:34816
	ds_read_b128 v[188:191], v198 offset:35840
	ds_read_b128 v[200:203], v198 offset:36864
	ds_read_b128 v[204:207], v198 offset:37888
	ds_read_b128 v[208:211], v198 offset:38912
	ds_read_b128 v[212:215], v198 offset:39936
	global_load_lds_dwordx4 v[224:225], off
	v_lshl_add_u64 v[224:225], s[38:39], 0, v[164:165]
	s_mov_b32 m0, s53
	s_nop 0
	global_load_lds_dwordx4 v[224:225], off
	s_waitcnt vmcnt(8)
	s_waitcnt lgkmcnt(0)
	s_barrier
	s_setprio 1
	s_waitcnt lgkmcnt(0)
	v_mfma_f32_16x16x32_bf16 v[124:127], v[128:131], v[176:179], v[124:127]
	v_mfma_f32_16x16x32_bf16 v[124:127], v[132:135], v[180:183], v[124:127]
	v_mfma_f32_16x16x32_bf16 v[120:123], v[136:139], v[176:179], v[120:123]
	v_mfma_f32_16x16x32_bf16 v[120:123], v[140:143], v[180:183], v[120:123]
	v_mfma_f32_16x16x32_bf16 v[108:111], v[128:131], v[184:187], v[108:111]
	v_mfma_f32_16x16x32_bf16 v[108:111], v[132:135], v[188:191], v[108:111]
	v_mfma_f32_16x16x32_bf16 v[104:107], v[136:139], v[184:187], v[104:107]
	v_mfma_f32_16x16x32_bf16 v[104:107], v[140:143], v[188:191], v[104:107]
	v_mfma_f32_16x16x32_bf16 v[92:95], v[128:131], v[200:203], v[92:95]
	v_mfma_f32_16x16x32_bf16 v[92:95], v[132:135], v[204:207], v[92:95]
	v_mfma_f32_16x16x32_bf16 v[88:91], v[136:139], v[200:203], v[88:91]
	v_mfma_f32_16x16x32_bf16 v[88:91], v[140:143], v[204:207], v[88:91]
	v_mfma_f32_16x16x32_bf16 v[76:79], v[128:131], v[208:211], v[76:79]
	v_mfma_f32_16x16x32_bf16 v[76:79], v[132:135], v[212:215], v[76:79]
	v_mfma_f32_16x16x32_bf16 v[72:75], v[136:139], v[208:211], v[72:75]
	v_mfma_f32_16x16x32_bf16 v[72:75], v[140:143], v[212:215], v[72:75]
	s_setprio 0
	s_setprio 1
	v_mfma_f32_16x16x32_bf16 v[116:119], v[144:147], v[176:179], v[116:119]
	v_mfma_f32_16x16x32_bf16 v[116:119], v[148:151], v[180:183], v[116:119]
	v_mfma_f32_16x16x32_bf16 v[112:115], v[152:155], v[176:179], v[112:115]
	v_mfma_f32_16x16x32_bf16 v[112:115], v[156:159], v[180:183], v[112:115]
	v_mfma_f32_16x16x32_bf16 v[100:103], v[144:147], v[184:187], v[100:103]
	v_mfma_f32_16x16x32_bf16 v[100:103], v[148:151], v[188:191], v[100:103]
	v_mfma_f32_16x16x32_bf16 v[96:99], v[152:155], v[184:187], v[96:99]
	v_mfma_f32_16x16x32_bf16 v[96:99], v[156:159], v[188:191], v[96:99]
	v_mfma_f32_16x16x32_bf16 v[84:87], v[144:147], v[200:203], v[84:87]
	v_mfma_f32_16x16x32_bf16 v[84:87], v[148:151], v[204:207], v[84:87]
	v_mfma_f32_16x16x32_bf16 v[80:83], v[152:155], v[200:203], v[80:83]
	v_mfma_f32_16x16x32_bf16 v[80:83], v[156:159], v[204:207], v[80:83]
	v_mfma_f32_16x16x32_bf16 v[68:71], v[144:147], v[208:211], v[68:71]
	v_mfma_f32_16x16x32_bf16 v[68:71], v[148:151], v[212:215], v[68:71]
	v_mfma_f32_16x16x32_bf16 v[64:67], v[152:155], v[208:211], v[64:67]
	v_mfma_f32_16x16x32_bf16 v[64:67], v[156:159], v[212:215], v[64:67]
	s_setprio 0
	s_barrier
; #define PG8_STAGE(bufoff, gbase, voff) do { _Pragma("unroll") for (int _i = 0; _i < 2; ++_i) \
;         __builtin_amdgcn_global_load_lds((const unsigned*)((const char*)(gbase) + (voff)[_i]), (LAS unsigned*)(lds + (bufoff) + ldsw + _i * 8192), 16, 0, 0); } while (0)
; #define PG8_LDA(dst, b, h) do { _Pragma("unroll") for (int m = 0; m < 4; ++m) _Pragma("unroll") for (int k = 0; k < 2; ++k) dst[m][k] = *(const LAS bf16x8*)(lds + PG8_SA(b, h) + aoff + m * 2048 + k * 1024); } while (0)
; #define PG8_MMA(ai, bj, At, Bt) do { __builtin_amdgcn_s_setprio(1); _Pragma("unroll") for (int m = 0; m < 4; ++m) _Pragma("unroll") for (int n = 0; n < 2; ++n) _Pragma("unroll") for (int k = 0; k < 2; ++k) \
;         acc[ai][bj][m][n] = __builtin_amdgcn_mfma_f32_16x16x32_bf16(Bt[n][k], At[m][k], acc[ai][bj][m][n], 0, 0, 0); __builtin_amdgcn_s_setprio(0); } while (0)
; #define PG8_WAIT_V(n) asm volatile("s_waitcnt vmcnt(" #n ")" ::: "memory")
; #define PG8_WAIT_L(n) asm volatile("s_waitcnt lgkmcnt(" #n ")" ::: "memory")
; #define PG8_BAR __builtin_amdgcn_s_barrier()
; #define PG8_SCHED __builtin_amdgcn_sched_barrier(0)
; template <class Epi, bool ALIGN_EPI>
; __device__ __forceinline__ void gemm_phase(LAS unsigned char* lds, const Gemm g, const StaticOrder& S, const Epi& E) {
;     ...
;             PG8_LDA(At, 1, 1); PG8_STAGE(PG8_SB(1, 0), b3, voffB); PG8_STAGE(PG8_SB(1, 1), b3 + hB, voffB); PG8_STAGE(PG8_SA(1, 0), a3, voffA);
;             PG8_WAIT_V(8); PG8_WAIT_L(0); PG8_BAR; PG8_MMA(1, 0, At, B0); PG8_MMA(1, 1, At, B1); PG8_BAR; PG8_SCHED;
;         }
;         if constexpr (ALIGN_EPI) { if (wr == 0) PG8_BAR; }
	s_add_i32 s37, s37, s49
	v_lshl_add_u64 v[216:217], v[216:217], 0, s[20:21]
	s_mov_b32 m0, s37
	ds_read_b128 v[176:179], v198 offset:49152
	ds_read_b128 v[180:183], v198 offset:50176
	ds_read_b128 v[184:187], v198 offset:51200
	ds_read_b128 v[188:191], v198 offset:52224
	ds_read_b128 v[200:203], v198 offset:53248
	ds_read_b128 v[204:207], v198 offset:54272
	ds_read_b128 v[208:211], v198 offset:55296
	ds_read_b128 v[212:215], v198 offset:56320
	global_load_lds_dwordx4 v[216:217], off
	s_add_i32 m0, s37, 0x2000
	s_add_u32 s38, s42, 0x80080
	v_lshl_add_u64 v[216:217], v[218:219], 0, s[20:21]
	s_addc_u32 s39, s43, 0
	s_add_i32 s37, s63, s49
	global_load_lds_dwordx4 v[216:217], off
	v_lshl_add_u64 v[216:217], s[38:39], 0, v[162:163]
	s_mov_b32 m0, s37
	s_nop 0
	global_load_lds_dwordx4 v[216:217], off
	v_lshl_add_u64 v[216:217], s[38:39], 0, v[166:167]
	s_add_i32 m0, s37, 0x2000
	s_nop 0
	global_load_lds_dwordx4 v[216:217], off
	v_lshl_add_u64 v[216:217], v[220:221], 0, s[20:21]
	s_mov_b32 m0, s57
	s_nop 0
	global_load_lds_dwordx4 v[216:217], off
	v_lshl_add_u64 v[216:217], v[222:223], 0, s[20:21]
	s_mov_b32 m0, s58
	s_nop 0
	global_load_lds_dwordx4 v[216:217], off
	s_waitcnt vmcnt(8)
	s_waitcnt lgkmcnt(0)
	s_barrier
	s_setprio 1
	s_waitcnt lgkmcnt(0)
	v_mfma_f32_16x16x32_bf16 v[60:63], v[128:131], v[176:179], v[60:63]
	v_mfma_f32_16x16x32_bf16 v[60:63], v[132:135], v[180:183], v[60:63]
	v_mfma_f32_16x16x32_bf16 v[56:59], v[136:139], v[176:179], v[56:59]
	v_mfma_f32_16x16x32_bf16 v[56:59], v[140:143], v[180:183], v[56:59]
	v_mfma_f32_16x16x32_bf16 v[44:47], v[128:131], v[184:187], v[44:47]
	v_mfma_f32_16x16x32_bf16 v[44:47], v[132:135], v[188:191], v[44:47]
	v_mfma_f32_16x16x32_bf16 v[40:43], v[136:139], v[184:187], v[40:43]
	v_mfma_f32_16x16x32_bf16 v[40:43], v[140:143], v[188:191], v[40:43]
	v_mfma_f32_16x16x32_bf16 v[28:31], v[128:131], v[200:203], v[28:31]
	v_mfma_f32_16x16x32_bf16 v[28:31], v[132:135], v[204:207], v[28:31]
	v_mfma_f32_16x16x32_bf16 v[24:27], v[136:139], v[200:203], v[24:27]
	v_mfma_f32_16x16x32_bf16 v[24:27], v[140:143], v[204:207], v[24:27]
	v_mfma_f32_16x16x32_bf16 v[16:19], v[128:131], v[208:211], v[16:19]
	v_mfma_f32_16x16x32_bf16 v[16:19], v[132:135], v[212:215], v[16:19]
	v_mfma_f32_16x16x32_bf16 v[8:11], v[136:139], v[208:211], v[8:11]
	v_mfma_f32_16x16x32_bf16 v[8:11], v[140:143], v[212:215], v[8:11]
	s_setprio 0
	s_setprio 1
	v_mfma_f32_16x16x32_bf16 v[52:55], v[144:147], v[176:179], v[52:55]
	v_mfma_f32_16x16x32_bf16 v[52:55], v[148:151], v[180:183], v[52:55]
	v_mfma_f32_16x16x32_bf16 v[48:51], v[152:155], v[176:179], v[48:51]
	v_mfma_f32_16x16x32_bf16 v[48:51], v[156:159], v[180:183], v[48:51]
	v_mfma_f32_16x16x32_bf16 v[36:39], v[144:147], v[184:187], v[36:39]
	v_mfma_f32_16x16x32_bf16 v[36:39], v[148:151], v[188:191], v[36:39]
	v_mfma_f32_16x16x32_bf16 v[32:35], v[152:155], v[184:187], v[32:35]
	v_mfma_f32_16x16x32_bf16 v[32:35], v[156:159], v[188:191], v[32:35]
	v_mfma_f32_16x16x32_bf16 v[20:23], v[144:147], v[200:203], v[20:23]
	v_mfma_f32_16x16x32_bf16 v[20:23], v[148:151], v[204:207], v[20:23]
	v_mfma_f32_16x16x32_bf16 v[12:15], v[152:155], v[200:203], v[12:15]
	v_mfma_f32_16x16x32_bf16 v[12:15], v[156:159], v[204:207], v[12:15]
	v_mfma_f32_16x16x32_bf16 v[4:7], v[144:147], v[208:211], v[4:7]
	v_mfma_f32_16x16x32_bf16 v[4:7], v[148:151], v[212:215], v[4:7]
	v_mfma_f32_16x16x32_bf16 v[0:3], v[152:155], v[208:211], v[0:3]
	v_mfma_f32_16x16x32_bf16 v[0:3], v[156:159], v[212:215], v[0:3]
	s_setprio 0
	s_barrier
	s_add_i32 s29, s29, 2
	s_add_u32 s40, s40, 0x100
	s_addc_u32 s41, s41, 0
	s_add_u32 s9, s9, 0x100
	s_addc_u32 s27, s27, 0
	s_cmp_gt_u32 s29, 29
	s_cbranch_scc0 .LBB0_775
	s_and_b64 vcc, exec, s[22:23]
	s_cbranch_vccz .LBB0_778
	s_barrier

; #define PG8_STAGE(bufoff, gbase, voff) do { _Pragma("unroll") for (int _i = 0; _i < 2; ++_i) \
;         __builtin_amdgcn_global_load_lds((const unsigned*)((const char*)(gbase) + (voff)[_i]), (LAS unsigned*)(lds + (bufoff) + ldsw + _i * 8192), 16, 0, 0); } while (0)
; #define PG8_LDA(dst, b, h) do { _Pragma("unroll") for (int m = 0; m < 4; ++m) _Pragma("unroll") for (int k = 0; k < 2; ++k) dst[m][k] = *(const LAS bf16x8*)(lds + PG8_SA(b, h) + aoff + m * 2048 + k * 1024); } while (0)
; #define PG8_LDB(dst, b, h) do { _Pragma("unroll") for (int n = 0; n < 2; ++n) _Pragma("unroll") for (int k = 0; k < 2; ++k) dst[n][k] = *(const LAS bf16x8*)(lds + PG8_SB(b, h) + boff + n * 2048 + k * 1024); } while (0)
; #define PG8_MMA(ai, bj, At, Bt) do { __builtin_amdgcn_s_setprio(1); _Pragma("unroll") for (int m = 0; m < 4; ++m) _Pragma("unroll") for (int n = 0; n < 2; ++n) _Pragma("unroll") for (int k = 0; k < 2; ++k) \
;         acc[ai][bj][m][n] = __builtin_amdgcn_mfma_f32_16x16x32_bf16(Bt[n][k], At[m][k], acc[ai][bj][m][n], 0, 0, 0); __builtin_amdgcn_s_setprio(0); } while (0)
; #define PG8_WAIT_V(n) asm volatile("s_waitcnt vmcnt(" #n ")" ::: "memory")
; #define PG8_WAIT_L(n) asm volatile("s_waitcnt lgkmcnt(" #n ")" ::: "memory")
; #define PG8_BAR __builtin_amdgcn_s_barrier()
; #define PG8_SCHED __builtin_amdgcn_sched_barrier(0)
; template <class Epi, bool ALIGN_EPI>
; __device__ __forceinline__ void gemm_phase(LAS unsigned char* lds, const Gemm g, const StaticOrder& S, const Epi& E) {
;     ...
;         for (int t = 0; t < nt; t += 2) {
;             const bool last = (t == nt - 2);
;             const char* a1 = cA + (size_t)(t + 1) * kstep;
;             const char* a2 = last ? nA : cA + (size_t)(t + 2) * kstep; const char* b2 = last ? nB : cB + (size_t)(t + 2) * kstep;
;             const char* a3 = a2 + kstep; const char* b3 = b2 + kstep;
;             PG8_LDB(B0, 0, 0); PG8_LDB(B1, 0, 1); PG8_SCHED; PG8_LDA(At, 0, 0); PG8_STAGE(PG8_SA(1, 1), a1 + hA, voffA);
;             PG8_WAIT_V(8); PG8_WAIT_L(0); PG8_BAR; PG8_MMA(0, 0, At, B0); PG8_MMA(0, 1, At, B1); PG8_BAR; PG8_SCHED;
;             PG8_LDA(At, 0, 1); PG8_STAGE(PG8_SB(0, 0), b2, voffB); PG8_STAGE(PG8_SB(0, 1), b2 + hB, voffB); PG8_STAGE(PG8_SA(0, 0), a2, voffA);
;             PG8_WAIT_V(8); PG8_WAIT_L(0); PG8_BAR; PG8_MMA(1, 0, At, B0); PG8_MMA(1, 1, At, B1); PG8_BAR; PG8_SCHED;
.LBB0_926:
	ds_read_b128 v[168:171], v153
	ds_read_b128 v[172:175], v153 offset:1024
	ds_read_b128 v[176:179], v153 offset:2048
	ds_read_b128 v[180:183], v153 offset:3072
	ds_read_b128 v[184:187], v155
	ds_read_b128 v[188:191], v155 offset:1024
	ds_read_b128 v[194:197], v155 offset:2048
	ds_read_b128 v[198:201], v155 offset:3072
	s_add_u32 s8, s6, 0xfff80080
	s_addc_u32 s9, s7, -1
	s_cmp_eq_u32 s71, 28
	s_cselect_b32 s55, s47, s9
	s_cselect_b32 s54, s67, s8
	s_cselect_b32 s9, s45, s70
	s_cselect_b32 s8, s68, s69
	v_lshl_add_u64 v[234:235], s[6:7], 0, v[136:137]
	s_add_i32 m0, s39, 0xc000
	ds_read_b128 v[202:205], v156
	ds_read_b128 v[206:209], v156 offset:1024
	ds_read_b128 v[210:213], v156 offset:2048
	ds_read_b128 v[214:217], v156 offset:3072
	ds_read_b128 v[218:221], v156 offset:4096
	ds_read_b128 v[222:225], v156 offset:5120
	ds_read_b128 v[226:229], v156 offset:6144
	ds_read_b128 v[230:233], v156 offset:7168
	global_load_lds_dwordx4 v[234:235], off
	v_lshl_add_u64 v[234:235], s[6:7], 0, v[138:139]
	s_add_i32 m0, s39, 0xe000
	s_nop 0
	global_load_lds_dwordx4 v[234:235], off
	s_waitcnt vmcnt(8)
	s_waitcnt lgkmcnt(0)
	s_barrier
	s_setprio 1
	s_waitcnt lgkmcnt(0)
	v_mfma_f32_16x16x32_bf16 v[124:127], v[168:171], v[202:205], v[124:127]
	v_mfma_f32_16x16x32_bf16 v[124:127], v[172:175], v[206:209], v[124:127]
	v_mfma_f32_16x16x32_bf16 v[120:123], v[176:179], v[202:205], v[120:123]
	v_mfma_f32_16x16x32_bf16 v[120:123], v[180:183], v[206:209], v[120:123]
	v_mfma_f32_16x16x32_bf16 v[108:111], v[168:171], v[210:213], v[108:111]
	v_mfma_f32_16x16x32_bf16 v[108:111], v[172:175], v[214:217], v[108:111]
	v_mfma_f32_16x16x32_bf16 v[104:107], v[176:179], v[210:213], v[104:107]
	v_mfma_f32_16x16x32_bf16 v[104:107], v[180:183], v[214:217], v[104:107]
	v_mfma_f32_16x16x32_bf16 v[92:95], v[168:171], v[218:221], v[92:95]
	v_mfma_f32_16x16x32_bf16 v[92:95], v[172:175], v[222:225], v[92:95]
	v_mfma_f32_16x16x32_bf16 v[88:91], v[176:179], v[218:221], v[88:91]
	v_mfma_f32_16x16x32_bf16 v[88:91], v[180:183], v[222:225], v[88:91]
	v_mfma_f32_16x16x32_bf16 v[76:79], v[168:171], v[226:229], v[76:79]
	v_mfma_f32_16x16x32_bf16 v[76:79], v[172:175], v[230:233], v[76:79]
	v_mfma_f32_16x16x32_bf16 v[72:75], v[176:179], v[226:229], v[72:75]
	v_mfma_f32_16x16x32_bf16 v[72:75], v[180:183], v[230:233], v[72:75]
	s_setprio 0
	s_setprio 1
	v_mfma_f32_16x16x32_bf16 v[116:119], v[184:187], v[202:205], v[116:119]
	v_mfma_f32_16x16x32_bf16 v[116:119], v[188:191], v[206:209], v[116:119]
	v_mfma_f32_16x16x32_bf16 v[112:115], v[194:197], v[202:205], v[112:115]
	v_mfma_f32_16x16x32_bf16 v[112:115], v[198:201], v[206:209], v[112:115]
	v_mfma_f32_16x16x32_bf16 v[100:103], v[184:187], v[210:213], v[100:103]
	v_mfma_f32_16x16x32_bf16 v[100:103], v[188:191], v[214:217], v[100:103]
	v_mfma_f32_16x16x32_bf16 v[96:99], v[194:197], v[210:213], v[96:99]
	v_mfma_f32_16x16x32_bf16 v[96:99], v[198:201], v[214:217], v[96:99]
	v_mfma_f32_16x16x32_bf16 v[84:87], v[184:187], v[218:221], v[84:87]
	v_mfma_f32_16x16x32_bf16 v[84:87], v[188:191], v[222:225], v[84:87]
	v_mfma_f32_16x16x32_bf16 v[80:83], v[194:197], v[218:221], v[80:83]
	v_mfma_f32_16x16x32_bf16 v[80:83], v[198:201], v[222:225], v[80:83]
	v_mfma_f32_16x16x32_bf16 v[68:71], v[184:187], v[226:229], v[68:71]
	v_mfma_f32_16x16x32_bf16 v[68:71], v[188:191], v[230:233], v[68:71]
	v_mfma_f32_16x16x32_bf16 v[64:67], v[194:197], v[226:229], v[64:67]
	v_mfma_f32_16x16x32_bf16 v[64:67], v[198:201], v[230:233], v[64:67]
	s_setprio 0
	s_barrier
	s_add_i32 s72, s63, s33
	v_lshl_add_u64 v[234:235], s[8:9], 0, v[132:133]
	s_mov_b32 m0, s72
	ds_read_b128 v[202:205], v156 offset:16384
	ds_read_b128 v[206:209], v156 offset:17408
	ds_read_b128 v[210:213], v156 offset:18432
	ds_read_b128 v[214:217], v156 offset:19456
	ds_read_b128 v[218:221], v156 offset:20480
	ds_read_b128 v[222:225], v156 offset:21504
	ds_read_b128 v[226:229], v156 offset:22528
	ds_read_b128 v[230:233], v156 offset:23552
	global_load_lds_dwordx4 v[234:235], off
	s_add_i32 m0, s72, 0x2000
	s_add_u32 s72, s8, 0x80000
	v_lshl_add_u64 v[236:237], s[8:9], 0, v[128:129]
	s_addc_u32 s73, s9, 0
	s_add_i32 s74, s64, s33
	global_load_lds_dwordx4 v[236:237], off
	v_lshl_add_u64 v[238:239], s[72:73], 0, v[132:133]
	s_mov_b32 m0, s74
	v_lshl_add_u64 v[240:241], s[54:55], 0, v[130:131]
	global_load_lds_dwordx4 v[238:239], off
	v_lshl_add_u64 v[238:239], s[72:73], 0, v[128:129]
	s_add_i32 m0, s74, 0x2000
	s_nop 0
	global_load_lds_dwordx4 v[238:239], off
	v_lshl_add_u64 v[238:239], s[54:55], 0, v[134:135]
	s_mov_b32 m0, s39
	s_nop 0
	global_load_lds_dwordx4 v[238:239], off
	s_mov_b32 m0, s53
	s_nop 0
	global_load_lds_dwordx4 v[240:241], off
	s_waitcnt vmcnt(8)
	s_waitcnt lgkmcnt(0)
	s_barrier
; #define PG8_STAGE(bufoff, gbase, voff) do { _Pragma("unroll") for (int _i = 0; _i < 2; ++_i) \
;         __builtin_amdgcn_global_load_lds((const unsigned*)((const char*)(gbase) + (voff)[_i]), (LAS unsigned*)(lds + (bufoff) + ldsw + _i * 8192), 16, 0, 0); } while (0)
; #define PG8_LDA(dst, b, h) do { _Pragma("unroll") for (int m = 0; m < 4; ++m) _Pragma("unroll") for (int k = 0; k < 2; ++k) dst[m][k] = *(const LAS bf16x8*)(lds + PG8_SA(b, h) + aoff + m * 2048 + k * 1024); } while (0)
; #define PG8_LDB(dst, b, h) do { _Pragma("unroll") for (int n = 0; n < 2; ++n) _Pragma("unroll") for (int k = 0; k < 2; ++k) dst[n][k] = *(const LAS bf16x8*)(lds + PG8_SB(b, h) + boff + n * 2048 + k * 1024); } while (0)
; #define PG8_MMA(ai, bj, At, Bt) do { __builtin_amdgcn_s_setprio(1); _Pragma("unroll") for (int m = 0; m < 4; ++m) _Pragma("unroll") for (int n = 0; n < 2; ++n) _Pragma("unroll") for (int k = 0; k < 2; ++k) \
;         acc[ai][bj][m][n] = __builtin_amdgcn_mfma_f32_16x16x32_bf16(Bt[n][k], At[m][k], acc[ai][bj][m][n], 0, 0, 0); __builtin_amdgcn_s_setprio(0); } while (0)
; #define PG8_WAIT_V(n) asm volatile("s_waitcnt vmcnt(" #n ")" ::: "memory")
; #define PG8_WAIT_L(n) asm volatile("s_waitcnt lgkmcnt(" #n ")" ::: "memory")
; #define PG8_BAR __builtin_amdgcn_s_barrier()
; #define PG8_SCHED __builtin_amdgcn_sched_barrier(0)
; template <class Epi, bool ALIGN_EPI>
; __device__ __forceinline__ void gemm_phase(LAS unsigned char* lds, const Gemm g, const StaticOrder& S, const Epi& E) {
;     ...
;             PG8_WAIT_V(8); PG8_WAIT_L(0); PG8_BAR; PG8_MMA(1, 0, At, B0); PG8_MMA(1, 1, At, B1); PG8_BAR; PG8_SCHED;
;             PG8_LDB(B0, 1, 0); PG8_LDB(B1, 1, 1); PG8_SCHED; PG8_LDA(At, 1, 0); PG8_STAGE(PG8_SA(0, 1), a2 + hA, voffA);
;             PG8_WAIT_V(8); PG8_WAIT_L(0); PG8_BAR; PG8_MMA(0, 0, At, B0); PG8_MMA(0, 1, At, B1); PG8_BAR; PG8_SCHED;
	s_setprio 1
	s_waitcnt lgkmcnt(0)
	v_mfma_f32_16x16x32_bf16 v[60:63], v[168:171], v[202:205], v[60:63]
	v_mfma_f32_16x16x32_bf16 v[60:63], v[172:175], v[206:209], v[60:63]
	v_mfma_f32_16x16x32_bf16 v[56:59], v[176:179], v[202:205], v[56:59]
	v_mfma_f32_16x16x32_bf16 v[56:59], v[180:183], v[206:209], v[56:59]
	v_mfma_f32_16x16x32_bf16 v[44:47], v[168:171], v[210:213], v[44:47]
	v_mfma_f32_16x16x32_bf16 v[44:47], v[172:175], v[214:217], v[44:47]
	v_mfma_f32_16x16x32_bf16 v[40:43], v[176:179], v[210:213], v[40:43]
	v_mfma_f32_16x16x32_bf16 v[40:43], v[180:183], v[214:217], v[40:43]
	v_mfma_f32_16x16x32_bf16 v[28:31], v[168:171], v[218:221], v[28:31]
	v_mfma_f32_16x16x32_bf16 v[28:31], v[172:175], v[222:225], v[28:31]
	v_mfma_f32_16x16x32_bf16 v[24:27], v[176:179], v[218:221], v[24:27]
	v_mfma_f32_16x16x32_bf16 v[24:27], v[180:183], v[222:225], v[24:27]
	v_mfma_f32_16x16x32_bf16 v[12:15], v[168:171], v[226:229], v[12:15]
	v_mfma_f32_16x16x32_bf16 v[12:15], v[172:175], v[230:233], v[12:15]
	v_mfma_f32_16x16x32_bf16 v[8:11], v[176:179], v[226:229], v[8:11]
	v_mfma_f32_16x16x32_bf16 v[8:11], v[180:183], v[230:233], v[8:11]
	s_setprio 0
	s_setprio 1
	v_mfma_f32_16x16x32_bf16 v[52:55], v[184:187], v[202:205], v[52:55]
	v_mfma_f32_16x16x32_bf16 v[52:55], v[188:191], v[206:209], v[52:55]
	v_mfma_f32_16x16x32_bf16 v[48:51], v[194:197], v[202:205], v[48:51]
	v_mfma_f32_16x16x32_bf16 v[48:51], v[198:201], v[206:209], v[48:51]
	v_mfma_f32_16x16x32_bf16 v[36:39], v[184:187], v[210:213], v[36:39]
	v_mfma_f32_16x16x32_bf16 v[36:39], v[188:191], v[214:217], v[36:39]
	v_mfma_f32_16x16x32_bf16 v[32:35], v[194:197], v[210:213], v[32:35]
	v_mfma_f32_16x16x32_bf16 v[32:35], v[198:201], v[214:217], v[32:35]
	v_mfma_f32_16x16x32_bf16 v[20:23], v[184:187], v[218:221], v[20:23]
	v_mfma_f32_16x16x32_bf16 v[20:23], v[188:191], v[222:225], v[20:23]
	v_mfma_f32_16x16x32_bf16 v[16:19], v[194:197], v[218:221], v[16:19]
	v_mfma_f32_16x16x32_bf16 v[16:19], v[198:201], v[222:225], v[16:19]
	v_mfma_f32_16x16x32_bf16 v[4:7], v[184:187], v[226:229], v[4:7]
	v_mfma_f32_16x16x32_bf16 v[4:7], v[188:191], v[230:233], v[4:7]
	v_mfma_f32_16x16x32_bf16 v[0:3], v[194:197], v[226:229], v[0:3]
	v_mfma_f32_16x16x32_bf16 v[0:3], v[198:201], v[230:233], v[0:3]
	s_setprio 0
	s_barrier
	s_add_i32 s72, 0, 0x18000
	v_add_u32_e32 v167, s72, v149
	s_add_i32 s73, 0, 0x1c000
	ds_read_b128 v[168:171], v167
	ds_read_b128 v[172:175], v167 offset:1024
	ds_read_b128 v[176:179], v167 offset:2048
	ds_read_b128 v[180:183], v167 offset:3072
	v_add_u32_e32 v167, s73, v149
	ds_read_b128 v[184:187], v167
	ds_read_b128 v[188:191], v167 offset:1024
	ds_read_b128 v[194:197], v167 offset:2048
	ds_read_b128 v[198:201], v167 offset:3072
	s_add_u32 s54, s54, 0x80000
	s_addc_u32 s55, s55, 0
	s_mov_b32 m0, s56
	v_lshl_add_u64 v[242:243], s[54:55], 0, v[134:135]
	ds_read_b128 v[202:205], v156 offset:32768
	ds_read_b128 v[206:209], v156 offset:33792
	ds_read_b128 v[210:213], v156 offset:34816
	ds_read_b128 v[214:217], v156 offset:35840
	ds_read_b128 v[218:221], v156 offset:36864
	ds_read_b128 v[222:225], v156 offset:37888
	ds_read_b128 v[226:229], v156 offset:38912
	ds_read_b128 v[230:233], v156 offset:39936
	global_load_lds_dwordx4 v[242:243], off
	v_lshl_add_u64 v[242:243], s[54:55], 0, v[130:131]
	s_mov_b32 m0, s57
	s_nop 0
	global_load_lds_dwordx4 v[242:243], off
	s_waitcnt vmcnt(8)
	s_waitcnt lgkmcnt(0)
	s_barrier
	s_setprio 1
	s_waitcnt lgkmcnt(0)
	v_mfma_f32_16x16x32_bf16 v[124:127], v[168:171], v[202:205], v[124:127]
	v_mfma_f32_16x16x32_bf16 v[124:127], v[172:175], v[206:209], v[124:127]
	v_mfma_f32_16x16x32_bf16 v[120:123], v[176:179], v[202:205], v[120:123]
	v_mfma_f32_16x16x32_bf16 v[120:123], v[180:183], v[206:209], v[120:123]
	v_mfma_f32_16x16x32_bf16 v[108:111], v[168:171], v[210:213], v[108:111]
	v_mfma_f32_16x16x32_bf16 v[108:111], v[172:175], v[214:217], v[108:111]
	v_mfma_f32_16x16x32_bf16 v[104:107], v[176:179], v[210:213], v[104:107]
	v_mfma_f32_16x16x32_bf16 v[104:107], v[180:183], v[214:217], v[104:107]
	v_mfma_f32_16x16x32_bf16 v[92:95], v[168:171], v[218:221], v[92:95]
	v_mfma_f32_16x16x32_bf16 v[92:95], v[172:175], v[222:225], v[92:95]
	v_mfma_f32_16x16x32_bf16 v[88:91], v[176:179], v[218:221], v[88:91]
	v_mfma_f32_16x16x32_bf16 v[88:91], v[180:183], v[222:225], v[88:91]
	v_mfma_f32_16x16x32_bf16 v[76:79], v[168:171], v[226:229], v[76:79]
	v_mfma_f32_16x16x32_bf16 v[76:79], v[172:175], v[230:233], v[76:79]
	v_mfma_f32_16x16x32_bf16 v[72:75], v[176:179], v[226:229], v[72:75]
	v_mfma_f32_16x16x32_bf16 v[72:75], v[180:183], v[230:233], v[72:75]
	s_setprio 0
	s_setprio 1
	v_mfma_f32_16x16x32_bf16 v[116:119], v[184:187], v[202:205], v[116:119]
	v_mfma_f32_16x16x32_bf16 v[116:119], v[188:191], v[206:209], v[116:119]
	v_mfma_f32_16x16x32_bf16 v[112:115], v[194:197], v[202:205], v[112:115]
	v_mfma_f32_16x16x32_bf16 v[112:115], v[198:201], v[206:209], v[112:115]
	v_mfma_f32_16x16x32_bf16 v[100:103], v[184:187], v[210:213], v[100:103]
	v_mfma_f32_16x16x32_bf16 v[100:103], v[188:191], v[214:217], v[100:103]
	v_mfma_f32_16x16x32_bf16 v[96:99], v[194:197], v[210:213], v[96:99]
	v_mfma_f32_16x16x32_bf16 v[96:99], v[198:201], v[214:217], v[96:99]
	v_mfma_f32_16x16x32_bf16 v[84:87], v[184:187], v[218:221], v[84:87]
	v_mfma_f32_16x16x32_bf16 v[84:87], v[188:191], v[222:225], v[84:87]
	v_mfma_f32_16x16x32_bf16 v[80:83], v[194:197], v[218:221], v[80:83]
	v_mfma_f32_16x16x32_bf16 v[80:83], v[198:201], v[222:225], v[80:83]
	v_mfma_f32_16x16x32_bf16 v[68:71], v[184:187], v[226:229], v[68:71]
	v_mfma_f32_16x16x32_bf16 v[68:71], v[188:191], v[230:233], v[68:71]
	v_mfma_f32_16x16x32_bf16 v[64:67], v[194:197], v[226:229], v[64:67]
	v_mfma_f32_16x16x32_bf16 v[64:67], v[198:201], v[230:233], v[64:67]
	s_setprio 0
	s_barrier
; #define PG8_STAGE(bufoff, gbase, voff) do { _Pragma("unroll") for (int _i = 0; _i < 2; ++_i) \
;         __builtin_amdgcn_global_load_lds((const unsigned*)((const char*)(gbase) + (voff)[_i]), (LAS unsigned*)(lds + (bufoff) + ldsw + _i * 8192), 16, 0, 0); } while (0)
; #define PG8_LDA(dst, b, h) do { _Pragma("unroll") for (int m = 0; m < 4; ++m) _Pragma("unroll") for (int k = 0; k < 2; ++k) dst[m][k] = *(const LAS bf16x8*)(lds + PG8_SA(b, h) + aoff + m * 2048 + k * 1024); } while (0)
; #define PG8_MMA(ai, bj, At, Bt) do { __builtin_amdgcn_s_setprio(1); _Pragma("unroll") for (int m = 0; m < 4; ++m) _Pragma("unroll") for (int n = 0; n < 2; ++n) _Pragma("unroll") for (int k = 0; k < 2; ++k) \
;         acc[ai][bj][m][n] = __builtin_amdgcn_mfma_f32_16x16x32_bf16(Bt[n][k], At[m][k], acc[ai][bj][m][n], 0, 0, 0); __builtin_amdgcn_s_setprio(0); } while (0)
; #define PG8_WAIT_V(n) asm volatile("s_waitcnt vmcnt(" #n ")" ::: "memory")
; #define PG8_WAIT_L(n) asm volatile("s_waitcnt lgkmcnt(" #n ")" ::: "memory")
; #define PG8_BAR __builtin_amdgcn_s_barrier()
; #define PG8_SCHED __builtin_amdgcn_sched_barrier(0)
; template <class Epi, bool ALIGN_EPI>
; __device__ __forceinline__ void gemm_phase(LAS unsigned char* lds, const Gemm g, const StaticOrder& S, const Epi& E) {
;     ...
;             PG8_LDA(At, 1, 1); PG8_STAGE(PG8_SB(1, 0), b3, voffB); PG8_STAGE(PG8_SB(1, 1), b3 + hB, voffB); PG8_STAGE(PG8_SA(1, 0), a3, voffA);
;             PG8_WAIT_V(8); PG8_WAIT_L(0); PG8_BAR; PG8_MMA(1, 0, At, B0); PG8_MMA(1, 1, At, B1); PG8_BAR; PG8_SCHED;
;         }
;         if constexpr (ALIGN_EPI) { if (wr == 0) PG8_BAR; }
	s_add_i32 s54, s72, s33
	v_lshl_add_u64 v[234:235], v[234:235], 0, s[18:19]
	s_mov_b32 m0, s54
	ds_read_b128 v[202:205], v156 offset:49152
	ds_read_b128 v[206:209], v156 offset:50176
	ds_read_b128 v[210:213], v156 offset:51200
	ds_read_b128 v[214:217], v156 offset:52224
	ds_read_b128 v[218:221], v156 offset:53248
	ds_read_b128 v[222:225], v156 offset:54272
	ds_read_b128 v[226:229], v156 offset:55296
	ds_read_b128 v[230:233], v156 offset:56320
	global_load_lds_dwordx4 v[234:235], off
	s_add_i32 m0, s54, 0x2000
	s_add_u32 s8, s8, 0x80080
	v_lshl_add_u64 v[234:235], v[236:237], 0, s[18:19]
	s_addc_u32 s9, s9, 0
	s_add_i32 s54, s73, s33
	global_load_lds_dwordx4 v[234:235], off
	v_lshl_add_u64 v[234:235], s[8:9], 0, v[132:133]
	s_mov_b32 m0, s54
	s_nop 0
	global_load_lds_dwordx4 v[234:235], off
	v_lshl_add_u64 v[234:235], s[8:9], 0, v[128:129]
	s_add_i32 m0, s54, 0x2000
	s_nop 0
	global_load_lds_dwordx4 v[234:235], off
	v_lshl_add_u64 v[234:235], v[238:239], 0, s[18:19]
	s_mov_b32 m0, s60
	s_nop 0
	global_load_lds_dwordx4 v[234:235], off
	v_lshl_add_u64 v[234:235], v[240:241], 0, s[18:19]
	s_mov_b32 m0, s61
	s_nop 0
	global_load_lds_dwordx4 v[234:235], off
	s_waitcnt vmcnt(8)
	s_waitcnt lgkmcnt(0)
	s_barrier
	s_setprio 1
	s_waitcnt lgkmcnt(0)
	v_mfma_f32_16x16x32_bf16 v[60:63], v[168:171], v[202:205], v[60:63]
	v_mfma_f32_16x16x32_bf16 v[60:63], v[172:175], v[206:209], v[60:63]
	v_mfma_f32_16x16x32_bf16 v[56:59], v[176:179], v[202:205], v[56:59]
	v_mfma_f32_16x16x32_bf16 v[56:59], v[180:183], v[206:209], v[56:59]
	v_mfma_f32_16x16x32_bf16 v[44:47], v[168:171], v[210:213], v[44:47]
	v_mfma_f32_16x16x32_bf16 v[44:47], v[172:175], v[214:217], v[44:47]
	v_mfma_f32_16x16x32_bf16 v[40:43], v[176:179], v[210:213], v[40:43]
	v_mfma_f32_16x16x32_bf16 v[40:43], v[180:183], v[214:217], v[40:43]
	v_mfma_f32_16x16x32_bf16 v[28:31], v[168:171], v[218:221], v[28:31]
	v_mfma_f32_16x16x32_bf16 v[28:31], v[172:175], v[222:225], v[28:31]
	v_mfma_f32_16x16x32_bf16 v[24:27], v[176:179], v[218:221], v[24:27]
	v_mfma_f32_16x16x32_bf16 v[24:27], v[180:183], v[222:225], v[24:27]
	v_mfma_f32_16x16x32_bf16 v[12:15], v[168:171], v[226:229], v[12:15]
	v_mfma_f32_16x16x32_bf16 v[12:15], v[172:175], v[230:233], v[12:15]
	v_mfma_f32_16x16x32_bf16 v[8:11], v[176:179], v[226:229], v[8:11]
	v_mfma_f32_16x16x32_bf16 v[8:11], v[180:183], v[230:233], v[8:11]
	s_setprio 0
	s_setprio 1
	v_mfma_f32_16x16x32_bf16 v[52:55], v[184:187], v[202:205], v[52:55]
	v_mfma_f32_16x16x32_bf16 v[52:55], v[188:191], v[206:209], v[52:55]
	v_mfma_f32_16x16x32_bf16 v[48:51], v[194:197], v[202:205], v[48:51]
	v_mfma_f32_16x16x32_bf16 v[48:51], v[198:201], v[206:209], v[48:51]
	v_mfma_f32_16x16x32_bf16 v[36:39], v[184:187], v[210:213], v[36:39]
	v_mfma_f32_16x16x32_bf16 v[36:39], v[188:191], v[214:217], v[36:39]
	v_mfma_f32_16x16x32_bf16 v[32:35], v[194:197], v[210:213], v[32:35]
	v_mfma_f32_16x16x32_bf16 v[32:35], v[198:201], v[214:217], v[32:35]
	v_mfma_f32_16x16x32_bf16 v[20:23], v[184:187], v[218:221], v[20:23]
	v_mfma_f32_16x16x32_bf16 v[20:23], v[188:191], v[222:225], v[20:23]
	v_mfma_f32_16x16x32_bf16 v[16:19], v[194:197], v[218:221], v[16:19]
	v_mfma_f32_16x16x32_bf16 v[16:19], v[198:201], v[222:225], v[16:19]
	v_mfma_f32_16x16x32_bf16 v[4:7], v[184:187], v[226:229], v[4:7]
	v_mfma_f32_16x16x32_bf16 v[4:7], v[188:191], v[230:233], v[4:7]
	v_mfma_f32_16x16x32_bf16 v[0:3], v[194:197], v[226:229], v[0:3]
	v_mfma_f32_16x16x32_bf16 v[0:3], v[198:201], v[230:233], v[0:3]
	s_setprio 0
	s_barrier
	s_add_i32 s71, s71, 2
	s_add_u32 s6, s6, 0x100
	s_addc_u32 s7, s7, 0
	s_add_u32 s69, s69, 0x100
	s_addc_u32 s70, s70, 0
	s_cmp_gt_u32 s71, 29
	s_cbranch_scc0 .LBB0_926
	s_and_b64 vcc, exec, s[20:21]
	s_cbranch_vccz .LBB0_929
	s_barrier

; #define PG8_STAGE(bufoff, gbase, voff) do { _Pragma("unroll") for (int _i = 0; _i < 2; ++_i) \
;         __builtin_amdgcn_global_load_lds((const unsigned*)((const char*)(gbase) + (voff)[_i]), (LAS unsigned*)(lds + (bufoff) + ldsw + _i * 8192), 16, 0, 0); } while (0)
; #define PG8_LDA(dst, b, h) do { _Pragma("unroll") for (int m = 0; m < 4; ++m) _Pragma("unroll") for (int k = 0; k < 2; ++k) dst[m][k] = *(const LAS bf16x8*)(lds + PG8_SA(b, h) + aoff + m * 2048 + k * 1024); } while (0)
; #define PG8_LDB(dst, b, h) do { _Pragma("unroll") for (int n = 0; n < 2; ++n) _Pragma("unroll") for (int k = 0; k < 2; ++k) dst[n][k] = *(const LAS bf16x8*)(lds + PG8_SB(b, h) + boff + n * 2048 + k * 1024); } while (0)
; #define PG8_MMA(ai, bj, At, Bt) do { __builtin_amdgcn_s_setprio(1); _Pragma("unroll") for (int m = 0; m < 4; ++m) _Pragma("unroll") for (int n = 0; n < 2; ++n) _Pragma("unroll") for (int k = 0; k < 2; ++k) \
;         acc[ai][bj][m][n] = __builtin_amdgcn_mfma_f32_16x16x32_bf16(Bt[n][k], At[m][k], acc[ai][bj][m][n], 0, 0, 0); __builtin_amdgcn_s_setprio(0); } while (0)
; #define PG8_WAIT_V(n) asm volatile("s_waitcnt vmcnt(" #n ")" ::: "memory")
; #define PG8_WAIT_L(n) asm volatile("s_waitcnt lgkmcnt(" #n ")" ::: "memory")
; #define PG8_BAR __builtin_amdgcn_s_barrier()
; #define PG8_SCHED __builtin_amdgcn_sched_barrier(0)
; template <class Epi, bool ALIGN_EPI>
; __device__ __forceinline__ void gemm_phase(LAS unsigned char* lds, const Gemm g, const StaticOrder& S, const Epi& E) {
;     ...
;         for (int t = 0; t < nt; t += 2) {
;             const bool last = (t == nt - 2);
;             const char* a1 = cA + (size_t)(t + 1) * kstep;
;             const char* a2 = last ? nA : cA + (size_t)(t + 2) * kstep; const char* b2 = last ? nB : cB + (size_t)(t + 2) * kstep;
;             const char* a3 = a2 + kstep; const char* b3 = b2 + kstep;
;             PG8_LDB(B0, 0, 0); PG8_LDB(B1, 0, 1); PG8_SCHED; PG8_LDA(At, 0, 0); PG8_STAGE(PG8_SA(1, 1), a1 + hA, voffA);
;             PG8_WAIT_V(8); PG8_WAIT_L(0); PG8_BAR; PG8_MMA(0, 0, At, B0); PG8_MMA(0, 1, At, B1); PG8_BAR; PG8_SCHED;
;             PG8_LDA(At, 0, 1); PG8_STAGE(PG8_SB(0, 0), b2, voffB); PG8_STAGE(PG8_SB(0, 1), b2 + hB, voffB); PG8_STAGE(PG8_SA(0, 0), a2, voffA);
;             PG8_WAIT_V(8); PG8_WAIT_L(0); PG8_BAR; PG8_MMA(1, 0, At, B0); PG8_MMA(1, 1, At, B1); PG8_BAR; PG8_SCHED;
.LBB0_1005:
	ds_read_b128 v[128:131], v175
	ds_read_b128 v[132:135], v175 offset:1024
	ds_read_b128 v[136:139], v175 offset:2048
	ds_read_b128 v[140:143], v175 offset:3072
	ds_read_b128 v[160:163], v176
	ds_read_b128 v[164:167], v176 offset:1024
	ds_read_b128 v[168:171], v176 offset:2048
	ds_read_b128 v[180:183], v176 offset:3072
	s_add_u32 s40, s36, 0xffe00080
	s_addc_u32 s41, s37, -1
	s_cmpk_eq_i32 s57, 0x7c
	s_cselect_b32 s43, s25, s41
	s_cselect_b32 s42, s31, s40
	s_cselect_b32 s41, s23, s56
	s_cselect_b32 s40, s54, s55
	v_lshl_add_u64 v[218:219], s[36:37], 0, v[152:153]
	s_add_i32 m0, s35, 0xc000
	ds_read_b128 v[184:187], v177
	ds_read_b128 v[188:191], v177 offset:1024
	ds_read_b128 v[194:197], v177 offset:2048
	ds_read_b128 v[198:201], v177 offset:3072
	ds_read_b128 v[202:205], v177 offset:4096
	ds_read_b128 v[206:209], v177 offset:5120
	ds_read_b128 v[210:213], v177 offset:6144
	ds_read_b128 v[214:217], v177 offset:7168
	global_load_lds_dwordx4 v[218:219], off
	v_lshl_add_u64 v[218:219], s[36:37], 0, v[154:155]
	s_add_i32 m0, s35, 0xe000
	s_nop 0
	global_load_lds_dwordx4 v[218:219], off
	s_waitcnt vmcnt(8)
	s_waitcnt lgkmcnt(0)
	s_barrier
	s_setprio 1
	s_waitcnt lgkmcnt(0)
	v_mfma_f32_16x16x32_bf16 v[124:127], v[128:131], v[184:187], v[124:127]
	v_mfma_f32_16x16x32_bf16 v[124:127], v[132:135], v[188:191], v[124:127]
	v_mfma_f32_16x16x32_bf16 v[120:123], v[136:139], v[184:187], v[120:123]
	v_mfma_f32_16x16x32_bf16 v[120:123], v[140:143], v[188:191], v[120:123]
	v_mfma_f32_16x16x32_bf16 v[112:115], v[128:131], v[194:197], v[112:115]
	v_mfma_f32_16x16x32_bf16 v[112:115], v[132:135], v[198:201], v[112:115]
	v_mfma_f32_16x16x32_bf16 v[104:107], v[136:139], v[194:197], v[104:107]
	v_mfma_f32_16x16x32_bf16 v[104:107], v[140:143], v[198:201], v[104:107]
	v_mfma_f32_16x16x32_bf16 v[92:95], v[128:131], v[202:205], v[92:95]
	v_mfma_f32_16x16x32_bf16 v[92:95], v[132:135], v[206:209], v[92:95]
	v_mfma_f32_16x16x32_bf16 v[88:91], v[136:139], v[202:205], v[88:91]
	v_mfma_f32_16x16x32_bf16 v[88:91], v[140:143], v[206:209], v[88:91]
	v_mfma_f32_16x16x32_bf16 v[76:79], v[128:131], v[210:213], v[76:79]
	v_mfma_f32_16x16x32_bf16 v[76:79], v[132:135], v[214:217], v[76:79]
	v_mfma_f32_16x16x32_bf16 v[72:75], v[136:139], v[210:213], v[72:75]
	v_mfma_f32_16x16x32_bf16 v[72:75], v[140:143], v[214:217], v[72:75]
	s_setprio 0
	s_setprio 1
	v_mfma_f32_16x16x32_bf16 v[116:119], v[160:163], v[184:187], v[116:119]
	v_mfma_f32_16x16x32_bf16 v[116:119], v[164:167], v[188:191], v[116:119]
	v_mfma_f32_16x16x32_bf16 v[108:111], v[168:171], v[184:187], v[108:111]
	v_mfma_f32_16x16x32_bf16 v[108:111], v[180:183], v[188:191], v[108:111]
	v_mfma_f32_16x16x32_bf16 v[100:103], v[160:163], v[194:197], v[100:103]
	v_mfma_f32_16x16x32_bf16 v[100:103], v[164:167], v[198:201], v[100:103]
	v_mfma_f32_16x16x32_bf16 v[96:99], v[168:171], v[194:197], v[96:99]
	v_mfma_f32_16x16x32_bf16 v[96:99], v[180:183], v[198:201], v[96:99]
	v_mfma_f32_16x16x32_bf16 v[84:87], v[160:163], v[202:205], v[84:87]
	v_mfma_f32_16x16x32_bf16 v[84:87], v[164:167], v[206:209], v[84:87]
	v_mfma_f32_16x16x32_bf16 v[80:83], v[168:171], v[202:205], v[80:83]
	v_mfma_f32_16x16x32_bf16 v[80:83], v[180:183], v[206:209], v[80:83]
	v_mfma_f32_16x16x32_bf16 v[68:71], v[160:163], v[210:213], v[68:71]
	v_mfma_f32_16x16x32_bf16 v[68:71], v[164:167], v[214:217], v[68:71]
	v_mfma_f32_16x16x32_bf16 v[64:67], v[168:171], v[210:213], v[64:67]
	v_mfma_f32_16x16x32_bf16 v[64:67], v[180:183], v[214:217], v[64:67]
	s_setprio 0
	s_barrier
	s_add_i32 s58, s51, s33
	v_lshl_add_u64 v[218:219], s[40:41], 0, v[146:147]
	s_mov_b32 m0, s58
	ds_read_b128 v[184:187], v177 offset:16384
	ds_read_b128 v[188:191], v177 offset:17408
	ds_read_b128 v[194:197], v177 offset:18432
	ds_read_b128 v[198:201], v177 offset:19456
	ds_read_b128 v[202:205], v177 offset:20480
	ds_read_b128 v[206:209], v177 offset:21504
	ds_read_b128 v[210:213], v177 offset:22528
	ds_read_b128 v[214:217], v177 offset:23552
	global_load_lds_dwordx4 v[218:219], off
	s_add_i32 m0, s58, 0x2000
	s_add_u32 s58, s40, 0x200000
	v_lshl_add_u64 v[220:221], s[40:41], 0, v[150:151]
	s_addc_u32 s59, s41, 0
	s_add_i32 s60, s52, s33
	global_load_lds_dwordx4 v[220:221], off
	v_lshl_add_u64 v[222:223], s[58:59], 0, v[146:147]
	s_mov_b32 m0, s60
	v_lshl_add_u64 v[224:225], s[42:43], 0, v[148:149]
	global_load_lds_dwordx4 v[222:223], off
	v_lshl_add_u64 v[222:223], s[58:59], 0, v[150:151]
	s_add_i32 m0, s60, 0x2000
	s_nop 0
	global_load_lds_dwordx4 v[222:223], off
	v_lshl_add_u64 v[222:223], s[42:43], 0, v[144:145]
	s_mov_b32 m0, s35
	s_nop 0
	global_load_lds_dwordx4 v[222:223], off
	s_mov_b32 m0, s38
	s_nop 0
	global_load_lds_dwordx4 v[224:225], off
	s_waitcnt vmcnt(8)
	s_waitcnt lgkmcnt(0)
	s_barrier
; #define PG8_STAGE(bufoff, gbase, voff) do { _Pragma("unroll") for (int _i = 0; _i < 2; ++_i) \
;         __builtin_amdgcn_global_load_lds((const unsigned*)((const char*)(gbase) + (voff)[_i]), (LAS unsigned*)(lds + (bufoff) + ldsw + _i * 8192), 16, 0, 0); } while (0)
; #define PG8_LDA(dst, b, h) do { _Pragma("unroll") for (int m = 0; m < 4; ++m) _Pragma("unroll") for (int k = 0; k < 2; ++k) dst[m][k] = *(const LAS bf16x8*)(lds + PG8_SA(b, h) + aoff + m * 2048 + k * 1024); } while (0)
; #define PG8_LDB(dst, b, h) do { _Pragma("unroll") for (int n = 0; n < 2; ++n) _Pragma("unroll") for (int k = 0; k < 2; ++k) dst[n][k] = *(const LAS bf16x8*)(lds + PG8_SB(b, h) + boff + n * 2048 + k * 1024); } while (0)
; #define PG8_MMA(ai, bj, At, Bt) do { __builtin_amdgcn_s_setprio(1); _Pragma("unroll") for (int m = 0; m < 4; ++m) _Pragma("unroll") for (int n = 0; n < 2; ++n) _Pragma("unroll") for (int k = 0; k < 2; ++k) \
;         acc[ai][bj][m][n] = __builtin_amdgcn_mfma_f32_16x16x32_bf16(Bt[n][k], At[m][k], acc[ai][bj][m][n], 0, 0, 0); __builtin_amdgcn_s_setprio(0); } while (0)
; #define PG8_WAIT_V(n) asm volatile("s_waitcnt vmcnt(" #n ")" ::: "memory")
; #define PG8_WAIT_L(n) asm volatile("s_waitcnt lgkmcnt(" #n ")" ::: "memory")
; #define PG8_BAR __builtin_amdgcn_s_barrier()
; #define PG8_SCHED __builtin_amdgcn_sched_barrier(0)
; template <class Epi, bool ALIGN_EPI>
; __device__ __forceinline__ void gemm_phase(LAS unsigned char* lds, const Gemm g, const StaticOrder& S, const Epi& E) {
;     ...
;             PG8_WAIT_V(8); PG8_WAIT_L(0); PG8_BAR; PG8_MMA(1, 0, At, B0); PG8_MMA(1, 1, At, B1); PG8_BAR; PG8_SCHED;
;             PG8_LDB(B0, 1, 0); PG8_LDB(B1, 1, 1); PG8_SCHED; PG8_LDA(At, 1, 0); PG8_STAGE(PG8_SA(0, 1), a2 + hA, voffA);
;             PG8_WAIT_V(8); PG8_WAIT_L(0); PG8_BAR; PG8_MMA(0, 0, At, B0); PG8_MMA(0, 1, At, B1); PG8_BAR; PG8_SCHED;
	s_setprio 1
	s_waitcnt lgkmcnt(0)
	v_mfma_f32_16x16x32_bf16 v[60:63], v[128:131], v[184:187], v[60:63]
	v_mfma_f32_16x16x32_bf16 v[60:63], v[132:135], v[188:191], v[60:63]
	v_mfma_f32_16x16x32_bf16 v[56:59], v[136:139], v[184:187], v[56:59]
	v_mfma_f32_16x16x32_bf16 v[56:59], v[140:143], v[188:191], v[56:59]
	v_mfma_f32_16x16x32_bf16 v[44:47], v[128:131], v[194:197], v[44:47]
	v_mfma_f32_16x16x32_bf16 v[44:47], v[132:135], v[198:201], v[44:47]
	v_mfma_f32_16x16x32_bf16 v[40:43], v[136:139], v[194:197], v[40:43]
	v_mfma_f32_16x16x32_bf16 v[40:43], v[140:143], v[198:201], v[40:43]
	v_mfma_f32_16x16x32_bf16 v[28:31], v[128:131], v[202:205], v[28:31]
	v_mfma_f32_16x16x32_bf16 v[28:31], v[132:135], v[206:209], v[28:31]
	v_mfma_f32_16x16x32_bf16 v[24:27], v[136:139], v[202:205], v[24:27]
	v_mfma_f32_16x16x32_bf16 v[24:27], v[140:143], v[206:209], v[24:27]
	v_mfma_f32_16x16x32_bf16 v[12:15], v[128:131], v[210:213], v[12:15]
	v_mfma_f32_16x16x32_bf16 v[12:15], v[132:135], v[214:217], v[12:15]
	v_mfma_f32_16x16x32_bf16 v[8:11], v[136:139], v[210:213], v[8:11]
	v_mfma_f32_16x16x32_bf16 v[8:11], v[140:143], v[214:217], v[8:11]
	s_setprio 0
	s_setprio 1
	v_mfma_f32_16x16x32_bf16 v[52:55], v[160:163], v[184:187], v[52:55]
	v_mfma_f32_16x16x32_bf16 v[52:55], v[164:167], v[188:191], v[52:55]
	v_mfma_f32_16x16x32_bf16 v[48:51], v[168:171], v[184:187], v[48:51]
	v_mfma_f32_16x16x32_bf16 v[48:51], v[180:183], v[188:191], v[48:51]
	v_mfma_f32_16x16x32_bf16 v[36:39], v[160:163], v[194:197], v[36:39]
	v_mfma_f32_16x16x32_bf16 v[36:39], v[164:167], v[198:201], v[36:39]
	v_mfma_f32_16x16x32_bf16 v[32:35], v[168:171], v[194:197], v[32:35]
	v_mfma_f32_16x16x32_bf16 v[32:35], v[180:183], v[198:201], v[32:35]
	v_mfma_f32_16x16x32_bf16 v[20:23], v[160:163], v[202:205], v[20:23]
	v_mfma_f32_16x16x32_bf16 v[20:23], v[164:167], v[206:209], v[20:23]
	v_mfma_f32_16x16x32_bf16 v[16:19], v[168:171], v[202:205], v[16:19]
	v_mfma_f32_16x16x32_bf16 v[16:19], v[180:183], v[206:209], v[16:19]
	v_mfma_f32_16x16x32_bf16 v[4:7], v[160:163], v[210:213], v[4:7]
	v_mfma_f32_16x16x32_bf16 v[4:7], v[164:167], v[214:217], v[4:7]
	v_mfma_f32_16x16x32_bf16 v[0:3], v[168:171], v[210:213], v[0:3]
	v_mfma_f32_16x16x32_bf16 v[0:3], v[180:183], v[214:217], v[0:3]
	s_setprio 0
	s_barrier
	s_add_i32 s58, 0, 0x18000
	s_add_i32 s59, 0, 0x1c000
	v_add_u32_e32 v140, s58, v173
	v_add_u32_e32 v179, s59, v173
	ds_read_b128 v[128:131], v140
	ds_read_b128 v[132:135], v140 offset:1024
	ds_read_b128 v[136:139], v140 offset:2048
	ds_read_b128 v[140:143], v140 offset:3072
	ds_read_b128 v[160:163], v179
	ds_read_b128 v[164:167], v179 offset:1024
	ds_read_b128 v[168:171], v179 offset:2048
	ds_read_b128 v[180:183], v179 offset:3072
	s_add_u32 s42, s42, 0x200000
	s_addc_u32 s43, s43, 0
	s_mov_b32 m0, s39
	v_lshl_add_u64 v[226:227], s[42:43], 0, v[144:145]
	ds_read_b128 v[184:187], v177 offset:32768
	ds_read_b128 v[188:191], v177 offset:33792
	ds_read_b128 v[194:197], v177 offset:34816
	ds_read_b128 v[198:201], v177 offset:35840
	ds_read_b128 v[202:205], v177 offset:36864
	ds_read_b128 v[206:209], v177 offset:37888
	ds_read_b128 v[210:213], v177 offset:38912
	ds_read_b128 v[214:217], v177 offset:39936
	global_load_lds_dwordx4 v[226:227], off
	v_lshl_add_u64 v[226:227], s[42:43], 0, v[148:149]
	s_mov_b32 m0, s44
	s_nop 0
	global_load_lds_dwordx4 v[226:227], off
	s_waitcnt vmcnt(8)
	s_waitcnt lgkmcnt(0)
	s_barrier
	s_setprio 1
	s_waitcnt lgkmcnt(0)
	v_mfma_f32_16x16x32_bf16 v[124:127], v[128:131], v[184:187], v[124:127]
	v_mfma_f32_16x16x32_bf16 v[124:127], v[132:135], v[188:191], v[124:127]
	v_mfma_f32_16x16x32_bf16 v[120:123], v[136:139], v[184:187], v[120:123]
	v_mfma_f32_16x16x32_bf16 v[120:123], v[140:143], v[188:191], v[120:123]
	v_mfma_f32_16x16x32_bf16 v[112:115], v[128:131], v[194:197], v[112:115]
	v_mfma_f32_16x16x32_bf16 v[112:115], v[132:135], v[198:201], v[112:115]
	v_mfma_f32_16x16x32_bf16 v[104:107], v[136:139], v[194:197], v[104:107]
	v_mfma_f32_16x16x32_bf16 v[104:107], v[140:143], v[198:201], v[104:107]
	v_mfma_f32_16x16x32_bf16 v[92:95], v[128:131], v[202:205], v[92:95]
	v_mfma_f32_16x16x32_bf16 v[92:95], v[132:135], v[206:209], v[92:95]
	v_mfma_f32_16x16x32_bf16 v[88:91], v[136:139], v[202:205], v[88:91]
	v_mfma_f32_16x16x32_bf16 v[88:91], v[140:143], v[206:209], v[88:91]
	v_mfma_f32_16x16x32_bf16 v[76:79], v[128:131], v[210:213], v[76:79]
	v_mfma_f32_16x16x32_bf16 v[76:79], v[132:135], v[214:217], v[76:79]
	v_mfma_f32_16x16x32_bf16 v[72:75], v[136:139], v[210:213], v[72:75]
	v_mfma_f32_16x16x32_bf16 v[72:75], v[140:143], v[214:217], v[72:75]
	s_setprio 0
	s_setprio 1
	v_mfma_f32_16x16x32_bf16 v[116:119], v[160:163], v[184:187], v[116:119]
	v_mfma_f32_16x16x32_bf16 v[116:119], v[164:167], v[188:191], v[116:119]
	v_mfma_f32_16x16x32_bf16 v[108:111], v[168:171], v[184:187], v[108:111]
	v_mfma_f32_16x16x32_bf16 v[108:111], v[180:183], v[188:191], v[108:111]
	v_mfma_f32_16x16x32_bf16 v[100:103], v[160:163], v[194:197], v[100:103]
	v_mfma_f32_16x16x32_bf16 v[100:103], v[164:167], v[198:201], v[100:103]
	v_mfma_f32_16x16x32_bf16 v[96:99], v[168:171], v[194:197], v[96:99]
	v_mfma_f32_16x16x32_bf16 v[96:99], v[180:183], v[198:201], v[96:99]
	v_mfma_f32_16x16x32_bf16 v[84:87], v[160:163], v[202:205], v[84:87]
	v_mfma_f32_16x16x32_bf16 v[84:87], v[164:167], v[206:209], v[84:87]
	v_mfma_f32_16x16x32_bf16 v[80:83], v[168:171], v[202:205], v[80:83]
	v_mfma_f32_16x16x32_bf16 v[80:83], v[180:183], v[206:209], v[80:83]
	v_mfma_f32_16x16x32_bf16 v[68:71], v[160:163], v[210:213], v[68:71]
	v_mfma_f32_16x16x32_bf16 v[68:71], v[164:167], v[214:217], v[68:71]
	v_mfma_f32_16x16x32_bf16 v[64:67], v[168:171], v[210:213], v[64:67]
	v_mfma_f32_16x16x32_bf16 v[64:67], v[180:183], v[214:217], v[64:67]
	s_setprio 0
	s_barrier
; #define PG8_STAGE(bufoff, gbase, voff) do { _Pragma("unroll") for (int _i = 0; _i < 2; ++_i) \
;         __builtin_amdgcn_global_load_lds((const unsigned*)((const char*)(gbase) + (voff)[_i]), (LAS unsigned*)(lds + (bufoff) + ldsw + _i * 8192), 16, 0, 0); } while (0)
; #define PG8_LDA(dst, b, h) do { _Pragma("unroll") for (int m = 0; m < 4; ++m) _Pragma("unroll") for (int k = 0; k < 2; ++k) dst[m][k] = *(const LAS bf16x8*)(lds + PG8_SA(b, h) + aoff + m * 2048 + k * 1024); } while (0)
; #define PG8_MMA(ai, bj, At, Bt) do { __builtin_amdgcn_s_setprio(1); _Pragma("unroll") for (int m = 0; m < 4; ++m) _Pragma("unroll") for (int n = 0; n < 2; ++n) _Pragma("unroll") for (int k = 0; k < 2; ++k) \
;         acc[ai][bj][m][n] = __builtin_amdgcn_mfma_f32_16x16x32_bf16(Bt[n][k], At[m][k], acc[ai][bj][m][n], 0, 0, 0); __builtin_amdgcn_s_setprio(0); } while (0)
; #define PG8_WAIT_V(n) asm volatile("s_waitcnt vmcnt(" #n ")" ::: "memory")
; #define PG8_WAIT_L(n) asm volatile("s_waitcnt lgkmcnt(" #n ")" ::: "memory")
; #define PG8_BAR __builtin_amdgcn_s_barrier()
; #define PG8_SCHED __builtin_amdgcn_sched_barrier(0)
; template <class Epi, bool ALIGN_EPI>
; __device__ __forceinline__ void gemm_phase(LAS unsigned char* lds, const Gemm g, const StaticOrder& S, const Epi& E) {
;     ...
;             PG8_LDA(At, 1, 1); PG8_STAGE(PG8_SB(1, 0), b3, voffB); PG8_STAGE(PG8_SB(1, 1), b3 + hB, voffB); PG8_STAGE(PG8_SA(1, 0), a3, voffA);
;             PG8_WAIT_V(8); PG8_WAIT_L(0); PG8_BAR; PG8_MMA(1, 0, At, B0); PG8_MMA(1, 1, At, B1); PG8_BAR; PG8_SCHED;
;         }
	s_add_i32 s42, s58, s33
	v_lshl_add_u64 v[218:219], v[218:219], 0, s[16:17]
	s_mov_b32 m0, s42
	ds_read_b128 v[184:187], v177 offset:49152
	ds_read_b128 v[188:191], v177 offset:50176
	ds_read_b128 v[194:197], v177 offset:51200
	ds_read_b128 v[198:201], v177 offset:52224
	ds_read_b128 v[202:205], v177 offset:53248
	ds_read_b128 v[206:209], v177 offset:54272
	ds_read_b128 v[210:213], v177 offset:55296
	ds_read_b128 v[214:217], v177 offset:56320
	global_load_lds_dwordx4 v[218:219], off
	s_add_i32 m0, s42, 0x2000
	s_add_u32 s40, s40, 0x200080
	v_lshl_add_u64 v[218:219], v[220:221], 0, s[16:17]
	s_addc_u32 s41, s41, 0
	s_add_i32 s42, s59, s33
	global_load_lds_dwordx4 v[218:219], off
	v_lshl_add_u64 v[218:219], s[40:41], 0, v[146:147]
	s_mov_b32 m0, s42
	s_nop 0
	global_load_lds_dwordx4 v[218:219], off
	v_lshl_add_u64 v[218:219], s[40:41], 0, v[150:151]
	s_add_i32 m0, s42, 0x2000
	s_nop 0
	global_load_lds_dwordx4 v[218:219], off
	v_lshl_add_u64 v[218:219], v[222:223], 0, s[16:17]
	s_mov_b32 m0, s48
	s_nop 0
	global_load_lds_dwordx4 v[218:219], off
	v_lshl_add_u64 v[218:219], v[224:225], 0, s[16:17]
	s_mov_b32 m0, s49
	s_nop 0
	global_load_lds_dwordx4 v[218:219], off
	s_waitcnt vmcnt(8)
	s_waitcnt lgkmcnt(0)
	s_barrier
	s_setprio 1
	s_waitcnt lgkmcnt(0)
	v_mfma_f32_16x16x32_bf16 v[60:63], v[128:131], v[184:187], v[60:63]
	v_mfma_f32_16x16x32_bf16 v[60:63], v[132:135], v[188:191], v[60:63]
	v_mfma_f32_16x16x32_bf16 v[56:59], v[136:139], v[184:187], v[56:59]
	v_mfma_f32_16x16x32_bf16 v[56:59], v[140:143], v[188:191], v[56:59]
	v_mfma_f32_16x16x32_bf16 v[44:47], v[128:131], v[194:197], v[44:47]
	v_mfma_f32_16x16x32_bf16 v[44:47], v[132:135], v[198:201], v[44:47]
	v_mfma_f32_16x16x32_bf16 v[40:43], v[136:139], v[194:197], v[40:43]
	v_mfma_f32_16x16x32_bf16 v[40:43], v[140:143], v[198:201], v[40:43]
	v_mfma_f32_16x16x32_bf16 v[28:31], v[128:131], v[202:205], v[28:31]
	v_mfma_f32_16x16x32_bf16 v[28:31], v[132:135], v[206:209], v[28:31]
	v_mfma_f32_16x16x32_bf16 v[24:27], v[136:139], v[202:205], v[24:27]
	v_mfma_f32_16x16x32_bf16 v[24:27], v[140:143], v[206:209], v[24:27]
	v_mfma_f32_16x16x32_bf16 v[12:15], v[128:131], v[210:213], v[12:15]
	v_mfma_f32_16x16x32_bf16 v[12:15], v[132:135], v[214:217], v[12:15]
	v_mfma_f32_16x16x32_bf16 v[8:11], v[136:139], v[210:213], v[8:11]
	v_mfma_f32_16x16x32_bf16 v[8:11], v[140:143], v[214:217], v[8:11]
	s_setprio 0
	s_setprio 1
	v_mfma_f32_16x16x32_bf16 v[52:55], v[160:163], v[184:187], v[52:55]
	v_mfma_f32_16x16x32_bf16 v[52:55], v[164:167], v[188:191], v[52:55]
	v_mfma_f32_16x16x32_bf16 v[48:51], v[168:171], v[184:187], v[48:51]
	v_mfma_f32_16x16x32_bf16 v[48:51], v[180:183], v[188:191], v[48:51]
	v_mfma_f32_16x16x32_bf16 v[36:39], v[160:163], v[194:197], v[36:39]
	v_mfma_f32_16x16x32_bf16 v[36:39], v[164:167], v[198:201], v[36:39]
	v_mfma_f32_16x16x32_bf16 v[32:35], v[168:171], v[194:197], v[32:35]
	v_mfma_f32_16x16x32_bf16 v[32:35], v[180:183], v[198:201], v[32:35]
	v_mfma_f32_16x16x32_bf16 v[20:23], v[160:163], v[202:205], v[20:23]
	v_mfma_f32_16x16x32_bf16 v[20:23], v[164:167], v[206:209], v[20:23]
	v_mfma_f32_16x16x32_bf16 v[16:19], v[168:171], v[202:205], v[16:19]
	v_mfma_f32_16x16x32_bf16 v[16:19], v[180:183], v[206:209], v[16:19]
	v_mfma_f32_16x16x32_bf16 v[4:7], v[160:163], v[210:213], v[4:7]
	v_mfma_f32_16x16x32_bf16 v[4:7], v[164:167], v[214:217], v[4:7]
	v_mfma_f32_16x16x32_bf16 v[0:3], v[168:171], v[210:213], v[0:3]
	v_mfma_f32_16x16x32_bf16 v[0:3], v[180:183], v[214:217], v[0:3]
	s_setprio 0
	s_barrier
	s_add_i32 s57, s57, 2
	s_add_u32 s36, s36, 0x100
	s_addc_u32 s37, s37, 0
	s_add_u32 s55, s55, 0x100
	s_addc_u32 s56, s56, 0
	s_cmpk_gt_u32 s57, 0x7d
	s_cbranch_scc0 .LBB0_1005
	s_and_b64 vcc, exec, s[18:19]
	s_cbranch_vccz .LBB0_1008
	s_barrier

; #define PG8_STAGE(bufoff, gbase, voff) do { _Pragma("unroll") for (int _i = 0; _i < 2; ++_i) \
;         __builtin_amdgcn_global_load_lds((const unsigned*)((const char*)(gbase) + (voff)[_i]), (LAS unsigned*)(lds + (bufoff) + ldsw + _i * 8192), 16, 0, 0); } while (0)
; #define PG8_LDA(dst, b, h) do { _Pragma("unroll") for (int m = 0; m < 4; ++m) _Pragma("unroll") for (int k = 0; k < 2; ++k) dst[m][k] = *(const LAS bf16x8*)(lds + PG8_SA(b, h) + aoff + m * 2048 + k * 1024); } while (0)
; #define PG8_LDB(dst, b, h) do { _Pragma("unroll") for (int n = 0; n < 2; ++n) _Pragma("unroll") for (int k = 0; k < 2; ++k) dst[n][k] = *(const LAS bf16x8*)(lds + PG8_SB(b, h) + boff + n * 2048 + k * 1024); } while (0)
; #define PG8_MMA(ai, bj, At, Bt) do { __builtin_amdgcn_s_setprio(1); _Pragma("unroll") for (int m = 0; m < 4; ++m) _Pragma("unroll") for (int n = 0; n < 2; ++n) _Pragma("unroll") for (int k = 0; k < 2; ++k) \
;         acc[ai][bj][m][n] = __builtin_amdgcn_mfma_f32_16x16x32_bf16(Bt[n][k], At[m][k], acc[ai][bj][m][n], 0, 0, 0); __builtin_amdgcn_s_setprio(0); } while (0)
; #define PG8_WAIT_V(n) asm volatile("s_waitcnt vmcnt(" #n ")" ::: "memory")
; #define PG8_WAIT_L(n) asm volatile("s_waitcnt lgkmcnt(" #n ")" ::: "memory")
; #define PG8_BAR __builtin_amdgcn_s_barrier()
; #define PG8_SCHED __builtin_amdgcn_sched_barrier(0)
; template <class Epi, bool ALIGN_EPI>
; __device__ __forceinline__ void gemm_phase(LAS unsigned char* lds, const Gemm g, const StaticOrder& S, const Epi& E) {
;     ...
;         for (int t = 0; t < nt; t += 2) {
;             const bool last = (t == nt - 2);
;             const char* a1 = cA + (size_t)(t + 1) * kstep;
;             const char* a2 = last ? nA : cA + (size_t)(t + 2) * kstep; const char* b2 = last ? nB : cB + (size_t)(t + 2) * kstep;
;             const char* a3 = a2 + kstep; const char* b3 = b2 + kstep;
;             PG8_LDB(B0, 0, 0); PG8_LDB(B1, 0, 1); PG8_SCHED; PG8_LDA(At, 0, 0); PG8_STAGE(PG8_SA(1, 1), a1 + hA, voffA);
;             PG8_WAIT_V(8); PG8_WAIT_L(0); PG8_BAR; PG8_MMA(0, 0, At, B0); PG8_MMA(0, 1, At, B1); PG8_BAR; PG8_SCHED;
;             PG8_LDA(At, 0, 1); PG8_STAGE(PG8_SB(0, 0), b2, voffB); PG8_STAGE(PG8_SB(0, 1), b2 + hB, voffB); PG8_STAGE(PG8_SA(0, 0), a2, voffA);
;             PG8_WAIT_V(8); PG8_WAIT_L(0); PG8_BAR; PG8_MMA(1, 0, At, B0); PG8_MMA(1, 1, At, B1); PG8_BAR; PG8_SCHED;
.LBB0_1094:
	ds_read_b128 v[146:149], v153
	ds_read_b128 v[174:177], v153 offset:1024
	ds_read_b128 v[178:181], v153 offset:2048
	ds_read_b128 v[182:185], v153 offset:3072
	ds_read_b128 v[186:189], v154
	ds_read_b128 v[194:197], v154 offset:1024
	ds_read_b128 v[198:201], v154 offset:2048
	ds_read_b128 v[202:205], v154 offset:3072
	s_add_u32 s36, s4, 0xfff80080
	s_addc_u32 s37, s5, -1
	s_cmp_eq_u32 s38, 28
	s_cselect_b32 s45, s0, s37
	s_cselect_b32 s44, s1, s36
	s_cselect_b32 s37, s2, s29
	s_cselect_b32 s36, s3, s27
	v_lshl_add_u64 v[190:191], s[4:5], 0, v[136:137]
	s_add_i32 m0, s41, 0xc000
	ds_read_b128 v[206:209], v155
	ds_read_b128 v[210:213], v155 offset:1024
	ds_read_b128 v[214:217], v155 offset:2048
	ds_read_b128 v[218:221], v155 offset:3072
	ds_read_b128 v[222:225], v155 offset:4096
	ds_read_b128 v[226:229], v155 offset:5120
	ds_read_b128 v[230:233], v155 offset:6144
	ds_read_b128 v[234:237], v155 offset:7168
	global_load_lds_dwordx4 v[190:191], off
	v_lshl_add_u64 v[190:191], s[4:5], 0, v[138:139]
	s_add_i32 m0, s41, 0xe000
	s_nop 0
	global_load_lds_dwordx4 v[190:191], off
	s_waitcnt vmcnt(8)
	s_waitcnt lgkmcnt(0)
	s_barrier
	s_setprio 1
	s_waitcnt lgkmcnt(0)
	v_mfma_f32_16x16x32_bf16 v[124:127], v[146:149], v[206:209], v[124:127]
	v_mfma_f32_16x16x32_bf16 v[124:127], v[174:177], v[210:213], v[124:127]
	v_mfma_f32_16x16x32_bf16 v[120:123], v[178:181], v[206:209], v[120:123]
	v_mfma_f32_16x16x32_bf16 v[120:123], v[182:185], v[210:213], v[120:123]
	v_mfma_f32_16x16x32_bf16 v[108:111], v[146:149], v[214:217], v[108:111]
	v_mfma_f32_16x16x32_bf16 v[108:111], v[174:177], v[218:221], v[108:111]
	v_mfma_f32_16x16x32_bf16 v[104:107], v[178:181], v[214:217], v[104:107]
	v_mfma_f32_16x16x32_bf16 v[104:107], v[182:185], v[218:221], v[104:107]
	v_mfma_f32_16x16x32_bf16 v[92:95], v[146:149], v[222:225], v[92:95]
	v_mfma_f32_16x16x32_bf16 v[92:95], v[174:177], v[226:229], v[92:95]
	v_mfma_f32_16x16x32_bf16 v[88:91], v[178:181], v[222:225], v[88:91]
	v_mfma_f32_16x16x32_bf16 v[88:91], v[182:185], v[226:229], v[88:91]
	v_mfma_f32_16x16x32_bf16 v[76:79], v[146:149], v[230:233], v[76:79]
	v_mfma_f32_16x16x32_bf16 v[76:79], v[174:177], v[234:237], v[76:79]
	v_mfma_f32_16x16x32_bf16 v[72:75], v[178:181], v[230:233], v[72:75]
	v_mfma_f32_16x16x32_bf16 v[72:75], v[182:185], v[234:237], v[72:75]
	s_setprio 0
	s_setprio 1
	v_mfma_f32_16x16x32_bf16 v[116:119], v[186:189], v[206:209], v[116:119]
	v_mfma_f32_16x16x32_bf16 v[116:119], v[194:197], v[210:213], v[116:119]
	v_mfma_f32_16x16x32_bf16 v[112:115], v[198:201], v[206:209], v[112:115]
	v_mfma_f32_16x16x32_bf16 v[112:115], v[202:205], v[210:213], v[112:115]
	v_mfma_f32_16x16x32_bf16 v[100:103], v[186:189], v[214:217], v[100:103]
	v_mfma_f32_16x16x32_bf16 v[100:103], v[194:197], v[218:221], v[100:103]
	v_mfma_f32_16x16x32_bf16 v[96:99], v[198:201], v[214:217], v[96:99]
	v_mfma_f32_16x16x32_bf16 v[96:99], v[202:205], v[218:221], v[96:99]
	v_mfma_f32_16x16x32_bf16 v[84:87], v[186:189], v[222:225], v[84:87]
	v_mfma_f32_16x16x32_bf16 v[84:87], v[194:197], v[226:229], v[84:87]
	v_mfma_f32_16x16x32_bf16 v[80:83], v[198:201], v[222:225], v[80:83]
	v_mfma_f32_16x16x32_bf16 v[80:83], v[202:205], v[226:229], v[80:83]
	v_mfma_f32_16x16x32_bf16 v[68:71], v[186:189], v[230:233], v[68:71]
	v_mfma_f32_16x16x32_bf16 v[68:71], v[194:197], v[234:237], v[68:71]
	v_mfma_f32_16x16x32_bf16 v[64:67], v[198:201], v[230:233], v[64:67]
	v_mfma_f32_16x16x32_bf16 v[64:67], v[202:205], v[234:237], v[64:67]
	s_setprio 0
	s_barrier
	s_add_i32 s39, s61, s51
	v_lshl_add_u64 v[190:191], s[36:37], 0, v[130:131]
	s_mov_b32 m0, s39
	ds_read_b128 v[206:209], v155 offset:16384
	ds_read_b128 v[210:213], v155 offset:17408
	ds_read_b128 v[214:217], v155 offset:18432
	ds_read_b128 v[218:221], v155 offset:19456
	ds_read_b128 v[222:225], v155 offset:20480
	ds_read_b128 v[226:229], v155 offset:21504
	ds_read_b128 v[230:233], v155 offset:22528
	ds_read_b128 v[234:237], v155 offset:23552
	global_load_lds_dwordx4 v[190:191], off
	s_add_i32 m0, s39, 0x2000
	s_add_u32 s46, s36, 0x80000
	v_lshl_add_u64 v[238:239], s[36:37], 0, v[134:135]
	s_addc_u32 s47, s37, 0
	s_add_i32 s39, s62, s51
	global_load_lds_dwordx4 v[238:239], off
	v_lshl_add_u64 v[240:241], s[46:47], 0, v[130:131]
	s_mov_b32 m0, s39
	v_lshl_add_u64 v[242:243], s[44:45], 0, v[132:133]
	global_load_lds_dwordx4 v[240:241], off
	v_lshl_add_u64 v[240:241], s[46:47], 0, v[134:135]
	s_add_i32 m0, s39, 0x2000
	s_nop 0
	global_load_lds_dwordx4 v[240:241], off
	v_lshl_add_u64 v[240:241], s[44:45], 0, v[128:129]
	s_mov_b32 m0, s41
	s_nop 0
	global_load_lds_dwordx4 v[240:241], off
	s_mov_b32 m0, s43
	s_nop 0
	global_load_lds_dwordx4 v[242:243], off
	s_waitcnt vmcnt(8)
	s_waitcnt lgkmcnt(0)
	s_barrier
; #define PG8_STAGE(bufoff, gbase, voff) do { _Pragma("unroll") for (int _i = 0; _i < 2; ++_i) \
;         __builtin_amdgcn_global_load_lds((const unsigned*)((const char*)(gbase) + (voff)[_i]), (LAS unsigned*)(lds + (bufoff) + ldsw + _i * 8192), 16, 0, 0); } while (0)
; #define PG8_LDA(dst, b, h) do { _Pragma("unroll") for (int m = 0; m < 4; ++m) _Pragma("unroll") for (int k = 0; k < 2; ++k) dst[m][k] = *(const LAS bf16x8*)(lds + PG8_SA(b, h) + aoff + m * 2048 + k * 1024); } while (0)
; #define PG8_LDB(dst, b, h) do { _Pragma("unroll") for (int n = 0; n < 2; ++n) _Pragma("unroll") for (int k = 0; k < 2; ++k) dst[n][k] = *(const LAS bf16x8*)(lds + PG8_SB(b, h) + boff + n * 2048 + k * 1024); } while (0)
; #define PG8_MMA(ai, bj, At, Bt) do { __builtin_amdgcn_s_setprio(1); _Pragma("unroll") for (int m = 0; m < 4; ++m) _Pragma("unroll") for (int n = 0; n < 2; ++n) _Pragma("unroll") for (int k = 0; k < 2; ++k) \
;         acc[ai][bj][m][n] = __builtin_amdgcn_mfma_f32_16x16x32_bf16(Bt[n][k], At[m][k], acc[ai][bj][m][n], 0, 0, 0); __builtin_amdgcn_s_setprio(0); } while (0)
; #define PG8_WAIT_V(n) asm volatile("s_waitcnt vmcnt(" #n ")" ::: "memory")
; #define PG8_WAIT_L(n) asm volatile("s_waitcnt lgkmcnt(" #n ")" ::: "memory")
; #define PG8_BAR __builtin_amdgcn_s_barrier()
; #define PG8_SCHED __builtin_amdgcn_sched_barrier(0)
; template <class Epi, bool ALIGN_EPI>
; __device__ __forceinline__ void gemm_phase(LAS unsigned char* lds, const Gemm g, const StaticOrder& S, const Epi& E) {
;     ...
;             PG8_WAIT_V(8); PG8_WAIT_L(0); PG8_BAR; PG8_MMA(1, 0, At, B0); PG8_MMA(1, 1, At, B1); PG8_BAR; PG8_SCHED;
;             PG8_LDB(B0, 1, 0); PG8_LDB(B1, 1, 1); PG8_SCHED; PG8_LDA(At, 1, 0); PG8_STAGE(PG8_SA(0, 1), a2 + hA, voffA);
;             PG8_WAIT_V(8); PG8_WAIT_L(0); PG8_BAR; PG8_MMA(0, 0, At, B0); PG8_MMA(0, 1, At, B1); PG8_BAR; PG8_SCHED;
	s_setprio 1
	s_waitcnt lgkmcnt(0)
	v_mfma_f32_16x16x32_bf16 v[60:63], v[146:149], v[206:209], v[60:63]
	v_mfma_f32_16x16x32_bf16 v[60:63], v[174:177], v[210:213], v[60:63]
	v_mfma_f32_16x16x32_bf16 v[56:59], v[178:181], v[206:209], v[56:59]
	v_mfma_f32_16x16x32_bf16 v[56:59], v[182:185], v[210:213], v[56:59]
	v_mfma_f32_16x16x32_bf16 v[44:47], v[146:149], v[214:217], v[44:47]
	v_mfma_f32_16x16x32_bf16 v[44:47], v[174:177], v[218:221], v[44:47]
	v_mfma_f32_16x16x32_bf16 v[40:43], v[178:181], v[214:217], v[40:43]
	v_mfma_f32_16x16x32_bf16 v[40:43], v[182:185], v[218:221], v[40:43]
	v_mfma_f32_16x16x32_bf16 v[28:31], v[146:149], v[222:225], v[28:31]
	v_mfma_f32_16x16x32_bf16 v[28:31], v[174:177], v[226:229], v[28:31]
	v_mfma_f32_16x16x32_bf16 v[24:27], v[178:181], v[222:225], v[24:27]
	v_mfma_f32_16x16x32_bf16 v[24:27], v[182:185], v[226:229], v[24:27]
	v_mfma_f32_16x16x32_bf16 v[12:15], v[146:149], v[230:233], v[12:15]
	v_mfma_f32_16x16x32_bf16 v[12:15], v[174:177], v[234:237], v[12:15]
	v_mfma_f32_16x16x32_bf16 v[8:11], v[178:181], v[230:233], v[8:11]
	v_mfma_f32_16x16x32_bf16 v[8:11], v[182:185], v[234:237], v[8:11]
	s_setprio 0
	s_setprio 1
	v_mfma_f32_16x16x32_bf16 v[52:55], v[186:189], v[206:209], v[52:55]
	v_mfma_f32_16x16x32_bf16 v[52:55], v[194:197], v[210:213], v[52:55]
	v_mfma_f32_16x16x32_bf16 v[48:51], v[198:201], v[206:209], v[48:51]
	v_mfma_f32_16x16x32_bf16 v[48:51], v[202:205], v[210:213], v[48:51]
	v_mfma_f32_16x16x32_bf16 v[36:39], v[186:189], v[214:217], v[36:39]
	v_mfma_f32_16x16x32_bf16 v[36:39], v[194:197], v[218:221], v[36:39]
	v_mfma_f32_16x16x32_bf16 v[32:35], v[198:201], v[214:217], v[32:35]
	v_mfma_f32_16x16x32_bf16 v[32:35], v[202:205], v[218:221], v[32:35]
	v_mfma_f32_16x16x32_bf16 v[20:23], v[186:189], v[222:225], v[20:23]
	v_mfma_f32_16x16x32_bf16 v[20:23], v[194:197], v[226:229], v[20:23]
	v_mfma_f32_16x16x32_bf16 v[16:19], v[198:201], v[222:225], v[16:19]
	v_mfma_f32_16x16x32_bf16 v[16:19], v[202:205], v[226:229], v[16:19]
	v_mfma_f32_16x16x32_bf16 v[4:7], v[186:189], v[230:233], v[4:7]
	v_mfma_f32_16x16x32_bf16 v[4:7], v[194:197], v[234:237], v[4:7]
	v_mfma_f32_16x16x32_bf16 v[0:3], v[198:201], v[230:233], v[0:3]
	v_mfma_f32_16x16x32_bf16 v[0:3], v[202:205], v[234:237], v[0:3]
	s_setprio 0
	s_barrier
	s_add_i32 s39, 0, 0x18000
	v_add_u32_e32 v145, s39, v151
	s_add_i32 s46, 0, 0x1c000
	ds_read_b128 v[146:149], v145
	ds_read_b128 v[174:177], v145 offset:1024
	ds_read_b128 v[178:181], v145 offset:2048
	ds_read_b128 v[182:185], v145 offset:3072
	v_add_u32_e32 v145, s46, v151
	ds_read_b128 v[186:189], v145
	ds_read_b128 v[194:197], v145 offset:1024
	ds_read_b128 v[198:201], v145 offset:2048
	ds_read_b128 v[202:205], v145 offset:3072
	s_add_u32 s44, s44, 0x80000
	s_addc_u32 s45, s45, 0
	s_mov_b32 m0, s52
	v_lshl_add_u64 v[244:245], s[44:45], 0, v[128:129]
	ds_read_b128 v[206:209], v155 offset:32768
	ds_read_b128 v[210:213], v155 offset:33792
	ds_read_b128 v[214:217], v155 offset:34816
	ds_read_b128 v[218:221], v155 offset:35840
	ds_read_b128 v[222:225], v155 offset:36864
	ds_read_b128 v[226:229], v155 offset:37888
	ds_read_b128 v[230:233], v155 offset:38912
	ds_read_b128 v[234:237], v155 offset:39936
	global_load_lds_dwordx4 v[244:245], off
	v_lshl_add_u64 v[244:245], s[44:45], 0, v[132:133]
	s_mov_b32 m0, s53
	s_nop 0
	global_load_lds_dwordx4 v[244:245], off
	s_waitcnt vmcnt(8)
	s_waitcnt lgkmcnt(0)
	s_barrier
	s_setprio 1
	s_waitcnt lgkmcnt(0)
	v_mfma_f32_16x16x32_bf16 v[124:127], v[146:149], v[206:209], v[124:127]
	v_mfma_f32_16x16x32_bf16 v[124:127], v[174:177], v[210:213], v[124:127]
	v_mfma_f32_16x16x32_bf16 v[120:123], v[178:181], v[206:209], v[120:123]
	v_mfma_f32_16x16x32_bf16 v[120:123], v[182:185], v[210:213], v[120:123]
	v_mfma_f32_16x16x32_bf16 v[108:111], v[146:149], v[214:217], v[108:111]
	v_mfma_f32_16x16x32_bf16 v[108:111], v[174:177], v[218:221], v[108:111]
	v_mfma_f32_16x16x32_bf16 v[104:107], v[178:181], v[214:217], v[104:107]
	v_mfma_f32_16x16x32_bf16 v[104:107], v[182:185], v[218:221], v[104:107]
	v_mfma_f32_16x16x32_bf16 v[92:95], v[146:149], v[222:225], v[92:95]
	v_mfma_f32_16x16x32_bf16 v[92:95], v[174:177], v[226:229], v[92:95]
	v_mfma_f32_16x16x32_bf16 v[88:91], v[178:181], v[222:225], v[88:91]
	v_mfma_f32_16x16x32_bf16 v[88:91], v[182:185], v[226:229], v[88:91]
	v_mfma_f32_16x16x32_bf16 v[76:79], v[146:149], v[230:233], v[76:79]
	v_mfma_f32_16x16x32_bf16 v[76:79], v[174:177], v[234:237], v[76:79]
	v_mfma_f32_16x16x32_bf16 v[72:75], v[178:181], v[230:233], v[72:75]
	v_mfma_f32_16x16x32_bf16 v[72:75], v[182:185], v[234:237], v[72:75]
	s_setprio 0
	s_setprio 1
	v_mfma_f32_16x16x32_bf16 v[116:119], v[186:189], v[206:209], v[116:119]
	v_mfma_f32_16x16x32_bf16 v[116:119], v[194:197], v[210:213], v[116:119]
	v_mfma_f32_16x16x32_bf16 v[112:115], v[198:201], v[206:209], v[112:115]
	v_mfma_f32_16x16x32_bf16 v[112:115], v[202:205], v[210:213], v[112:115]
	v_mfma_f32_16x16x32_bf16 v[100:103], v[186:189], v[214:217], v[100:103]
	v_mfma_f32_16x16x32_bf16 v[100:103], v[194:197], v[218:221], v[100:103]
	v_mfma_f32_16x16x32_bf16 v[96:99], v[198:201], v[214:217], v[96:99]
	v_mfma_f32_16x16x32_bf16 v[96:99], v[202:205], v[218:221], v[96:99]
	v_mfma_f32_16x16x32_bf16 v[84:87], v[186:189], v[222:225], v[84:87]
	v_mfma_f32_16x16x32_bf16 v[84:87], v[194:197], v[226:229], v[84:87]
	v_mfma_f32_16x16x32_bf16 v[80:83], v[198:201], v[222:225], v[80:83]
	v_mfma_f32_16x16x32_bf16 v[80:83], v[202:205], v[226:229], v[80:83]
	v_mfma_f32_16x16x32_bf16 v[68:71], v[186:189], v[230:233], v[68:71]
	v_mfma_f32_16x16x32_bf16 v[68:71], v[194:197], v[234:237], v[68:71]
	v_mfma_f32_16x16x32_bf16 v[64:67], v[198:201], v[230:233], v[64:67]
	v_mfma_f32_16x16x32_bf16 v[64:67], v[202:205], v[234:237], v[64:67]
	s_setprio 0
	s_barrier
; #define PG8_STAGE(bufoff, gbase, voff) do { _Pragma("unroll") for (int _i = 0; _i < 2; ++_i) \
;         __builtin_amdgcn_global_load_lds((const unsigned*)((const char*)(gbase) + (voff)[_i]), (LAS unsigned*)(lds + (bufoff) + ldsw + _i * 8192), 16, 0, 0); } while (0)
; #define PG8_LDA(dst, b, h) do { _Pragma("unroll") for (int m = 0; m < 4; ++m) _Pragma("unroll") for (int k = 0; k < 2; ++k) dst[m][k] = *(const LAS bf16x8*)(lds + PG8_SA(b, h) + aoff + m * 2048 + k * 1024); } while (0)
; #define PG8_MMA(ai, bj, At, Bt) do { __builtin_amdgcn_s_setprio(1); _Pragma("unroll") for (int m = 0; m < 4; ++m) _Pragma("unroll") for (int n = 0; n < 2; ++n) _Pragma("unroll") for (int k = 0; k < 2; ++k) \
;         acc[ai][bj][m][n] = __builtin_amdgcn_mfma_f32_16x16x32_bf16(Bt[n][k], At[m][k], acc[ai][bj][m][n], 0, 0, 0); __builtin_amdgcn_s_setprio(0); } while (0)
; #define PG8_WAIT_V(n) asm volatile("s_waitcnt vmcnt(" #n ")" ::: "memory")
; #define PG8_WAIT_L(n) asm volatile("s_waitcnt lgkmcnt(" #n ")" ::: "memory")
; #define PG8_BAR __builtin_amdgcn_s_barrier()
; #define PG8_SCHED __builtin_amdgcn_sched_barrier(0)
; template <class Epi, bool ALIGN_EPI>
; __device__ __forceinline__ void gemm_phase(LAS unsigned char* lds, const Gemm g, const StaticOrder& S, const Epi& E) {
;     ...
;             PG8_LDA(At, 1, 1); PG8_STAGE(PG8_SB(1, 0), b3, voffB); PG8_STAGE(PG8_SB(1, 1), b3 + hB, voffB); PG8_STAGE(PG8_SA(1, 0), a3, voffA);
;             PG8_WAIT_V(8); PG8_WAIT_L(0); PG8_BAR; PG8_MMA(1, 0, At, B0); PG8_MMA(1, 1, At, B1); PG8_BAR; PG8_SCHED;
;         }
	s_add_i32 s39, s39, s51
	v_lshl_add_u64 v[190:191], v[190:191], 0, s[20:21]
	s_mov_b32 m0, s39
	ds_read_b128 v[206:209], v155 offset:49152
	ds_read_b128 v[210:213], v155 offset:50176
	ds_read_b128 v[214:217], v155 offset:51200
	ds_read_b128 v[218:221], v155 offset:52224
	ds_read_b128 v[222:225], v155 offset:53248
	ds_read_b128 v[226:229], v155 offset:54272
	ds_read_b128 v[230:233], v155 offset:55296
	ds_read_b128 v[234:237], v155 offset:56320
	global_load_lds_dwordx4 v[190:191], off
	s_add_i32 m0, s39, 0x2000
	s_add_u32 s36, s36, 0x80080
	v_lshl_add_u64 v[190:191], v[238:239], 0, s[20:21]
	s_addc_u32 s37, s37, 0
	s_add_i32 s39, s46, s51
	global_load_lds_dwordx4 v[190:191], off
	v_lshl_add_u64 v[190:191], s[36:37], 0, v[130:131]
	s_mov_b32 m0, s39
	s_nop 0
	global_load_lds_dwordx4 v[190:191], off
	v_lshl_add_u64 v[190:191], s[36:37], 0, v[134:135]
	s_add_i32 m0, s39, 0x2000
	s_nop 0
	global_load_lds_dwordx4 v[190:191], off
	v_lshl_add_u64 v[190:191], v[240:241], 0, s[20:21]
	s_mov_b32 m0, s57
	s_nop 0
	global_load_lds_dwordx4 v[190:191], off
	v_lshl_add_u64 v[190:191], v[242:243], 0, s[20:21]
	s_mov_b32 m0, s58
	s_nop 0
	global_load_lds_dwordx4 v[190:191], off
	s_waitcnt vmcnt(8)
	s_waitcnt lgkmcnt(0)
	s_barrier
	s_setprio 1
	s_waitcnt lgkmcnt(0)
	v_mfma_f32_16x16x32_bf16 v[60:63], v[146:149], v[206:209], v[60:63]
	v_mfma_f32_16x16x32_bf16 v[60:63], v[174:177], v[210:213], v[60:63]
	v_mfma_f32_16x16x32_bf16 v[56:59], v[178:181], v[206:209], v[56:59]
	v_mfma_f32_16x16x32_bf16 v[56:59], v[182:185], v[210:213], v[56:59]
	v_mfma_f32_16x16x32_bf16 v[44:47], v[146:149], v[214:217], v[44:47]
	v_mfma_f32_16x16x32_bf16 v[44:47], v[174:177], v[218:221], v[44:47]
	v_mfma_f32_16x16x32_bf16 v[40:43], v[178:181], v[214:217], v[40:43]
	v_mfma_f32_16x16x32_bf16 v[40:43], v[182:185], v[218:221], v[40:43]
	v_mfma_f32_16x16x32_bf16 v[28:31], v[146:149], v[222:225], v[28:31]
	v_mfma_f32_16x16x32_bf16 v[28:31], v[174:177], v[226:229], v[28:31]
	v_mfma_f32_16x16x32_bf16 v[24:27], v[178:181], v[222:225], v[24:27]
	v_mfma_f32_16x16x32_bf16 v[24:27], v[182:185], v[226:229], v[24:27]
	v_mfma_f32_16x16x32_bf16 v[12:15], v[146:149], v[230:233], v[12:15]
	v_mfma_f32_16x16x32_bf16 v[12:15], v[174:177], v[234:237], v[12:15]
	v_mfma_f32_16x16x32_bf16 v[8:11], v[178:181], v[230:233], v[8:11]
	v_mfma_f32_16x16x32_bf16 v[8:11], v[182:185], v[234:237], v[8:11]
	s_setprio 0
	s_setprio 1
	v_mfma_f32_16x16x32_bf16 v[52:55], v[186:189], v[206:209], v[52:55]
	v_mfma_f32_16x16x32_bf16 v[52:55], v[194:197], v[210:213], v[52:55]
	v_mfma_f32_16x16x32_bf16 v[48:51], v[198:201], v[206:209], v[48:51]
	v_mfma_f32_16x16x32_bf16 v[48:51], v[202:205], v[210:213], v[48:51]
	v_mfma_f32_16x16x32_bf16 v[36:39], v[186:189], v[214:217], v[36:39]
	v_mfma_f32_16x16x32_bf16 v[36:39], v[194:197], v[218:221], v[36:39]
	v_mfma_f32_16x16x32_bf16 v[32:35], v[198:201], v[214:217], v[32:35]
	v_mfma_f32_16x16x32_bf16 v[32:35], v[202:205], v[218:221], v[32:35]
	v_mfma_f32_16x16x32_bf16 v[20:23], v[186:189], v[222:225], v[20:23]
	v_mfma_f32_16x16x32_bf16 v[20:23], v[194:197], v[226:229], v[20:23]
	v_mfma_f32_16x16x32_bf16 v[16:19], v[198:201], v[222:225], v[16:19]
	v_mfma_f32_16x16x32_bf16 v[16:19], v[202:205], v[226:229], v[16:19]
	v_mfma_f32_16x16x32_bf16 v[4:7], v[186:189], v[230:233], v[4:7]
	v_mfma_f32_16x16x32_bf16 v[4:7], v[194:197], v[234:237], v[4:7]
	v_mfma_f32_16x16x32_bf16 v[0:3], v[198:201], v[230:233], v[0:3]
	v_mfma_f32_16x16x32_bf16 v[0:3], v[202:205], v[234:237], v[0:3]
	s_setprio 0
	s_barrier
	s_add_i32 s38, s38, 2
	s_add_u32 s4, s4, 0x100
	s_addc_u32 s5, s5, 0
	s_add_u32 s27, s27, 0x100
	s_addc_u32 s29, s29, 0
	s_cmp_gt_u32 s38, 29
	s_cbranch_scc0 .LBB0_1094
	s_and_b64 vcc, exec, s[22:23]
	s_cbranch_vccz .LBB0_1097
	s_barrier

; #define PG8_STAGE(bufoff, gbase, voff) do { _Pragma("unroll") for (int _i = 0; _i < 2; ++_i) \
;         __builtin_amdgcn_global_load_lds((const unsigned*)((const char*)(gbase) + (voff)[_i]), (LAS unsigned*)(lds + (bufoff) + ldsw + _i * 8192), 16, 0, 0); } while (0)
; #define PG8_LDA(dst, b, h) do { _Pragma("unroll") for (int m = 0; m < 4; ++m) _Pragma("unroll") for (int k = 0; k < 2; ++k) dst[m][k] = *(const LAS bf16x8*)(lds + PG8_SA(b, h) + aoff + m * 2048 + k * 1024); } while (0)
; #define PG8_LDB(dst, b, h) do { _Pragma("unroll") for (int n = 0; n < 2; ++n) _Pragma("unroll") for (int k = 0; k < 2; ++k) dst[n][k] = *(const LAS bf16x8*)(lds + PG8_SB(b, h) + boff + n * 2048 + k * 1024); } while (0)
; #define PG8_MMA(ai, bj, At, Bt) do { __builtin_amdgcn_s_setprio(1); _Pragma("unroll") for (int m = 0; m < 4; ++m) _Pragma("unroll") for (int n = 0; n < 2; ++n) _Pragma("unroll") for (int k = 0; k < 2; ++k) \
;         acc[ai][bj][m][n] = __builtin_amdgcn_mfma_f32_16x16x32_bf16(Bt[n][k], At[m][k], acc[ai][bj][m][n], 0, 0, 0); __builtin_amdgcn_s_setprio(0); } while (0)
; #define PG8_WAIT_V(n) asm volatile("s_waitcnt vmcnt(" #n ")" ::: "memory")
; #define PG8_WAIT_L(n) asm volatile("s_waitcnt lgkmcnt(" #n ")" ::: "memory")
; #define PG8_BAR __builtin_amdgcn_s_barrier()
; #define PG8_SCHED __builtin_amdgcn_sched_barrier(0)
; template <class Epi, bool ALIGN_EPI>
; __device__ __forceinline__ void gemm_phase(LAS unsigned char* lds, const Gemm g, const StaticOrder& S, const Epi& E) {
;     ...
;         for (int t = 0; t < nt; t += 2) {
;             const bool last = (t == nt - 2);
;             const char* a1 = cA + (size_t)(t + 1) * kstep;
;             const char* a2 = last ? nA : cA + (size_t)(t + 2) * kstep; const char* b2 = last ? nB : cB + (size_t)(t + 2) * kstep;
;             const char* a3 = a2 + kstep; const char* b3 = b2 + kstep;
;             PG8_LDB(B0, 0, 0); PG8_LDB(B1, 0, 1); PG8_SCHED; PG8_LDA(At, 0, 0); PG8_STAGE(PG8_SA(1, 1), a1 + hA, voffA);
;             PG8_WAIT_V(8); PG8_WAIT_L(0); PG8_BAR; PG8_MMA(0, 0, At, B0); PG8_MMA(0, 1, At, B1); PG8_BAR; PG8_SCHED;
;             PG8_LDA(At, 0, 1); PG8_STAGE(PG8_SB(0, 0), b2, voffB); PG8_STAGE(PG8_SB(0, 1), b2 + hB, voffB); PG8_STAGE(PG8_SA(0, 0), a2, voffA);
;             PG8_WAIT_V(8); PG8_WAIT_L(0); PG8_BAR; PG8_MMA(1, 0, At, B0); PG8_MMA(1, 1, At, B1); PG8_BAR; PG8_SCHED;
.LBB0_1585:
	ds_read_b128 v[128:131], v175
	ds_read_b128 v[132:135], v175 offset:1024
	ds_read_b128 v[136:139], v175 offset:2048
	ds_read_b128 v[140:143], v175 offset:3072
	ds_read_b128 v[160:163], v176
	ds_read_b128 v[164:167], v176 offset:1024
	ds_read_b128 v[168:171], v176 offset:2048
	ds_read_b128 v[180:183], v176 offset:3072
	s_add_u32 s40, s36, 0xfff80080
	s_addc_u32 s41, s37, -1
	s_cmp_eq_u32 s57, 28
	s_cselect_b32 s43, s25, s41
	s_cselect_b32 s42, s31, s40
	s_cselect_b32 s41, s23, s56
	s_cselect_b32 s40, s54, s55
	v_lshl_add_u64 v[218:219], s[36:37], 0, v[152:153]
	s_add_i32 m0, s35, 0xc000
	ds_read_b128 v[184:187], v177
	ds_read_b128 v[188:191], v177 offset:1024
	ds_read_b128 v[194:197], v177 offset:2048
	ds_read_b128 v[198:201], v177 offset:3072
	ds_read_b128 v[202:205], v177 offset:4096
	ds_read_b128 v[206:209], v177 offset:5120
	ds_read_b128 v[210:213], v177 offset:6144
	ds_read_b128 v[214:217], v177 offset:7168
	global_load_lds_dwordx4 v[218:219], off
	v_lshl_add_u64 v[218:219], s[36:37], 0, v[154:155]
	s_add_i32 m0, s35, 0xe000
	s_nop 0
	global_load_lds_dwordx4 v[218:219], off
	s_waitcnt vmcnt(8)
	s_waitcnt lgkmcnt(0)
	s_barrier
	s_setprio 1
	s_waitcnt lgkmcnt(0)
	v_mfma_f32_16x16x32_bf16 v[124:127], v[128:131], v[184:187], v[124:127]
	v_mfma_f32_16x16x32_bf16 v[124:127], v[132:135], v[188:191], v[124:127]
	v_mfma_f32_16x16x32_bf16 v[120:123], v[136:139], v[184:187], v[120:123]
	v_mfma_f32_16x16x32_bf16 v[120:123], v[140:143], v[188:191], v[120:123]
	v_mfma_f32_16x16x32_bf16 v[112:115], v[128:131], v[194:197], v[112:115]
	v_mfma_f32_16x16x32_bf16 v[112:115], v[132:135], v[198:201], v[112:115]
	v_mfma_f32_16x16x32_bf16 v[104:107], v[136:139], v[194:197], v[104:107]
	v_mfma_f32_16x16x32_bf16 v[104:107], v[140:143], v[198:201], v[104:107]
	v_mfma_f32_16x16x32_bf16 v[92:95], v[128:131], v[202:205], v[92:95]
	v_mfma_f32_16x16x32_bf16 v[92:95], v[132:135], v[206:209], v[92:95]
	v_mfma_f32_16x16x32_bf16 v[88:91], v[136:139], v[202:205], v[88:91]
	v_mfma_f32_16x16x32_bf16 v[88:91], v[140:143], v[206:209], v[88:91]
	v_mfma_f32_16x16x32_bf16 v[76:79], v[128:131], v[210:213], v[76:79]
	v_mfma_f32_16x16x32_bf16 v[76:79], v[132:135], v[214:217], v[76:79]
	v_mfma_f32_16x16x32_bf16 v[72:75], v[136:139], v[210:213], v[72:75]
	v_mfma_f32_16x16x32_bf16 v[72:75], v[140:143], v[214:217], v[72:75]
	s_setprio 0
	s_setprio 1
	v_mfma_f32_16x16x32_bf16 v[116:119], v[160:163], v[184:187], v[116:119]
	v_mfma_f32_16x16x32_bf16 v[116:119], v[164:167], v[188:191], v[116:119]
	v_mfma_f32_16x16x32_bf16 v[108:111], v[168:171], v[184:187], v[108:111]
	v_mfma_f32_16x16x32_bf16 v[108:111], v[180:183], v[188:191], v[108:111]
	v_mfma_f32_16x16x32_bf16 v[100:103], v[160:163], v[194:197], v[100:103]
	v_mfma_f32_16x16x32_bf16 v[100:103], v[164:167], v[198:201], v[100:103]
	v_mfma_f32_16x16x32_bf16 v[96:99], v[168:171], v[194:197], v[96:99]
	v_mfma_f32_16x16x32_bf16 v[96:99], v[180:183], v[198:201], v[96:99]
	v_mfma_f32_16x16x32_bf16 v[84:87], v[160:163], v[202:205], v[84:87]
	v_mfma_f32_16x16x32_bf16 v[84:87], v[164:167], v[206:209], v[84:87]
	v_mfma_f32_16x16x32_bf16 v[80:83], v[168:171], v[202:205], v[80:83]
	v_mfma_f32_16x16x32_bf16 v[80:83], v[180:183], v[206:209], v[80:83]
	v_mfma_f32_16x16x32_bf16 v[68:71], v[160:163], v[210:213], v[68:71]
	v_mfma_f32_16x16x32_bf16 v[68:71], v[164:167], v[214:217], v[68:71]
	v_mfma_f32_16x16x32_bf16 v[64:67], v[168:171], v[210:213], v[64:67]
	v_mfma_f32_16x16x32_bf16 v[64:67], v[180:183], v[214:217], v[64:67]
	s_setprio 0
	s_barrier
	s_add_i32 s58, s51, s33
	v_lshl_add_u64 v[218:219], s[40:41], 0, v[146:147]
	s_mov_b32 m0, s58
	ds_read_b128 v[184:187], v177 offset:16384
	ds_read_b128 v[188:191], v177 offset:17408
	ds_read_b128 v[194:197], v177 offset:18432
	ds_read_b128 v[198:201], v177 offset:19456
	ds_read_b128 v[202:205], v177 offset:20480
	ds_read_b128 v[206:209], v177 offset:21504
	ds_read_b128 v[210:213], v177 offset:22528
	ds_read_b128 v[214:217], v177 offset:23552
	global_load_lds_dwordx4 v[218:219], off
	s_add_i32 m0, s58, 0x2000
	s_add_u32 s58, s40, 0x80000
	v_lshl_add_u64 v[220:221], s[40:41], 0, v[150:151]
	s_addc_u32 s59, s41, 0
	s_add_i32 s60, s52, s33
	global_load_lds_dwordx4 v[220:221], off
	v_lshl_add_u64 v[222:223], s[58:59], 0, v[146:147]
	s_mov_b32 m0, s60
	v_lshl_add_u64 v[224:225], s[42:43], 0, v[148:149]
	global_load_lds_dwordx4 v[222:223], off
	v_lshl_add_u64 v[222:223], s[58:59], 0, v[150:151]
	s_add_i32 m0, s60, 0x2000
	s_nop 0
	global_load_lds_dwordx4 v[222:223], off
	v_lshl_add_u64 v[222:223], s[42:43], 0, v[144:145]
	s_mov_b32 m0, s35
	s_nop 0
	global_load_lds_dwordx4 v[222:223], off
	s_mov_b32 m0, s38
	s_nop 0
	global_load_lds_dwordx4 v[224:225], off
	s_waitcnt vmcnt(8)
	s_waitcnt lgkmcnt(0)
	s_barrier
; #define PG8_STAGE(bufoff, gbase, voff) do { _Pragma("unroll") for (int _i = 0; _i < 2; ++_i) \
;         __builtin_amdgcn_global_load_lds((const unsigned*)((const char*)(gbase) + (voff)[_i]), (LAS unsigned*)(lds + (bufoff) + ldsw + _i * 8192), 16, 0, 0); } while (0)
; #define PG8_LDA(dst, b, h) do { _Pragma("unroll") for (int m = 0; m < 4; ++m) _Pragma("unroll") for (int k = 0; k < 2; ++k) dst[m][k] = *(const LAS bf16x8*)(lds + PG8_SA(b, h) + aoff + m * 2048 + k * 1024); } while (0)
; #define PG8_LDB(dst, b, h) do { _Pragma("unroll") for (int n = 0; n < 2; ++n) _Pragma("unroll") for (int k = 0; k < 2; ++k) dst[n][k] = *(const LAS bf16x8*)(lds + PG8_SB(b, h) + boff + n * 2048 + k * 1024); } while (0)
; #define PG8_MMA(ai, bj, At, Bt) do { __builtin_amdgcn_s_setprio(1); _Pragma("unroll") for (int m = 0; m < 4; ++m) _Pragma("unroll") for (int n = 0; n < 2; ++n) _Pragma("unroll") for (int k = 0; k < 2; ++k) \
;         acc[ai][bj][m][n] = __builtin_amdgcn_mfma_f32_16x16x32_bf16(Bt[n][k], At[m][k], acc[ai][bj][m][n], 0, 0, 0); __builtin_amdgcn_s_setprio(0); } while (0)
; #define PG8_WAIT_V(n) asm volatile("s_waitcnt vmcnt(" #n ")" ::: "memory")
; #define PG8_WAIT_L(n) asm volatile("s_waitcnt lgkmcnt(" #n ")" ::: "memory")
; #define PG8_BAR __builtin_amdgcn_s_barrier()
; #define PG8_SCHED __builtin_amdgcn_sched_barrier(0)
; template <class Epi, bool ALIGN_EPI>
; __device__ __forceinline__ void gemm_phase(LAS unsigned char* lds, const Gemm g, const StaticOrder& S, const Epi& E) {
;     ...
;             PG8_WAIT_V(8); PG8_WAIT_L(0); PG8_BAR; PG8_MMA(1, 0, At, B0); PG8_MMA(1, 1, At, B1); PG8_BAR; PG8_SCHED;
;             PG8_LDB(B0, 1, 0); PG8_LDB(B1, 1, 1); PG8_SCHED; PG8_LDA(At, 1, 0); PG8_STAGE(PG8_SA(0, 1), a2 + hA, voffA);
;             PG8_WAIT_V(8); PG8_WAIT_L(0); PG8_BAR; PG8_MMA(0, 0, At, B0); PG8_MMA(0, 1, At, B1); PG8_BAR; PG8_SCHED;
	s_setprio 1
	s_waitcnt lgkmcnt(0)
	v_mfma_f32_16x16x32_bf16 v[60:63], v[128:131], v[184:187], v[60:63]
	v_mfma_f32_16x16x32_bf16 v[60:63], v[132:135], v[188:191], v[60:63]
	v_mfma_f32_16x16x32_bf16 v[56:59], v[136:139], v[184:187], v[56:59]
	v_mfma_f32_16x16x32_bf16 v[56:59], v[140:143], v[188:191], v[56:59]
	v_mfma_f32_16x16x32_bf16 v[44:47], v[128:131], v[194:197], v[44:47]
	v_mfma_f32_16x16x32_bf16 v[44:47], v[132:135], v[198:201], v[44:47]
	v_mfma_f32_16x16x32_bf16 v[40:43], v[136:139], v[194:197], v[40:43]
	v_mfma_f32_16x16x32_bf16 v[40:43], v[140:143], v[198:201], v[40:43]
	v_mfma_f32_16x16x32_bf16 v[28:31], v[128:131], v[202:205], v[28:31]
	v_mfma_f32_16x16x32_bf16 v[28:31], v[132:135], v[206:209], v[28:31]
	v_mfma_f32_16x16x32_bf16 v[24:27], v[136:139], v[202:205], v[24:27]
	v_mfma_f32_16x16x32_bf16 v[24:27], v[140:143], v[206:209], v[24:27]
	v_mfma_f32_16x16x32_bf16 v[12:15], v[128:131], v[210:213], v[12:15]
	v_mfma_f32_16x16x32_bf16 v[12:15], v[132:135], v[214:217], v[12:15]
	v_mfma_f32_16x16x32_bf16 v[8:11], v[136:139], v[210:213], v[8:11]
	v_mfma_f32_16x16x32_bf16 v[8:11], v[140:143], v[214:217], v[8:11]
	s_setprio 0
	s_setprio 1
	v_mfma_f32_16x16x32_bf16 v[52:55], v[160:163], v[184:187], v[52:55]
	v_mfma_f32_16x16x32_bf16 v[52:55], v[164:167], v[188:191], v[52:55]
	v_mfma_f32_16x16x32_bf16 v[48:51], v[168:171], v[184:187], v[48:51]
	v_mfma_f32_16x16x32_bf16 v[48:51], v[180:183], v[188:191], v[48:51]
	v_mfma_f32_16x16x32_bf16 v[36:39], v[160:163], v[194:197], v[36:39]
	v_mfma_f32_16x16x32_bf16 v[36:39], v[164:167], v[198:201], v[36:39]
	v_mfma_f32_16x16x32_bf16 v[32:35], v[168:171], v[194:197], v[32:35]
	v_mfma_f32_16x16x32_bf16 v[32:35], v[180:183], v[198:201], v[32:35]
	v_mfma_f32_16x16x32_bf16 v[20:23], v[160:163], v[202:205], v[20:23]
	v_mfma_f32_16x16x32_bf16 v[20:23], v[164:167], v[206:209], v[20:23]
	v_mfma_f32_16x16x32_bf16 v[16:19], v[168:171], v[202:205], v[16:19]
	v_mfma_f32_16x16x32_bf16 v[16:19], v[180:183], v[206:209], v[16:19]
	v_mfma_f32_16x16x32_bf16 v[4:7], v[160:163], v[210:213], v[4:7]
	v_mfma_f32_16x16x32_bf16 v[4:7], v[164:167], v[214:217], v[4:7]
	v_mfma_f32_16x16x32_bf16 v[0:3], v[168:171], v[210:213], v[0:3]
	v_mfma_f32_16x16x32_bf16 v[0:3], v[180:183], v[214:217], v[0:3]
	s_setprio 0
	s_barrier
	s_add_i32 s58, 0, 0x18000
	s_add_i32 s59, 0, 0x1c000
	v_add_u32_e32 v140, s58, v173
	v_add_u32_e32 v179, s59, v173
	ds_read_b128 v[128:131], v140
	ds_read_b128 v[132:135], v140 offset:1024
	ds_read_b128 v[136:139], v140 offset:2048
	ds_read_b128 v[140:143], v140 offset:3072
	ds_read_b128 v[160:163], v179
	ds_read_b128 v[164:167], v179 offset:1024
	ds_read_b128 v[168:171], v179 offset:2048
	ds_read_b128 v[180:183], v179 offset:3072
	s_add_u32 s42, s42, 0x80000
	s_addc_u32 s43, s43, 0
	s_mov_b32 m0, s39
	v_lshl_add_u64 v[226:227], s[42:43], 0, v[144:145]
	ds_read_b128 v[184:187], v177 offset:32768
	ds_read_b128 v[188:191], v177 offset:33792
	ds_read_b128 v[194:197], v177 offset:34816
	ds_read_b128 v[198:201], v177 offset:35840
	ds_read_b128 v[202:205], v177 offset:36864
	ds_read_b128 v[206:209], v177 offset:37888
	ds_read_b128 v[210:213], v177 offset:38912
	ds_read_b128 v[214:217], v177 offset:39936
	global_load_lds_dwordx4 v[226:227], off
	v_lshl_add_u64 v[226:227], s[42:43], 0, v[148:149]
	s_mov_b32 m0, s44
	s_nop 0
	global_load_lds_dwordx4 v[226:227], off
	s_waitcnt vmcnt(8)
	s_waitcnt lgkmcnt(0)
	s_barrier
	s_setprio 1
	s_waitcnt lgkmcnt(0)
	v_mfma_f32_16x16x32_bf16 v[124:127], v[128:131], v[184:187], v[124:127]
	v_mfma_f32_16x16x32_bf16 v[124:127], v[132:135], v[188:191], v[124:127]
	v_mfma_f32_16x16x32_bf16 v[120:123], v[136:139], v[184:187], v[120:123]
	v_mfma_f32_16x16x32_bf16 v[120:123], v[140:143], v[188:191], v[120:123]
	v_mfma_f32_16x16x32_bf16 v[112:115], v[128:131], v[194:197], v[112:115]
	v_mfma_f32_16x16x32_bf16 v[112:115], v[132:135], v[198:201], v[112:115]
	v_mfma_f32_16x16x32_bf16 v[104:107], v[136:139], v[194:197], v[104:107]
	v_mfma_f32_16x16x32_bf16 v[104:107], v[140:143], v[198:201], v[104:107]
	v_mfma_f32_16x16x32_bf16 v[92:95], v[128:131], v[202:205], v[92:95]
	v_mfma_f32_16x16x32_bf16 v[92:95], v[132:135], v[206:209], v[92:95]
	v_mfma_f32_16x16x32_bf16 v[88:91], v[136:139], v[202:205], v[88:91]
	v_mfma_f32_16x16x32_bf16 v[88:91], v[140:143], v[206:209], v[88:91]
	v_mfma_f32_16x16x32_bf16 v[76:79], v[128:131], v[210:213], v[76:79]
	v_mfma_f32_16x16x32_bf16 v[76:79], v[132:135], v[214:217], v[76:79]
	v_mfma_f32_16x16x32_bf16 v[72:75], v[136:139], v[210:213], v[72:75]
	v_mfma_f32_16x16x32_bf16 v[72:75], v[140:143], v[214:217], v[72:75]
	s_setprio 0
	s_setprio 1
	v_mfma_f32_16x16x32_bf16 v[116:119], v[160:163], v[184:187], v[116:119]
	v_mfma_f32_16x16x32_bf16 v[116:119], v[164:167], v[188:191], v[116:119]
	v_mfma_f32_16x16x32_bf16 v[108:111], v[168:171], v[184:187], v[108:111]
	v_mfma_f32_16x16x32_bf16 v[108:111], v[180:183], v[188:191], v[108:111]
	v_mfma_f32_16x16x32_bf16 v[100:103], v[160:163], v[194:197], v[100:103]
	v_mfma_f32_16x16x32_bf16 v[100:103], v[164:167], v[198:201], v[100:103]
	v_mfma_f32_16x16x32_bf16 v[96:99], v[168:171], v[194:197], v[96:99]
	v_mfma_f32_16x16x32_bf16 v[96:99], v[180:183], v[198:201], v[96:99]
	v_mfma_f32_16x16x32_bf16 v[84:87], v[160:163], v[202:205], v[84:87]
	v_mfma_f32_16x16x32_bf16 v[84:87], v[164:167], v[206:209], v[84:87]
	v_mfma_f32_16x16x32_bf16 v[80:83], v[168:171], v[202:205], v[80:83]
	v_mfma_f32_16x16x32_bf16 v[80:83], v[180:183], v[206:209], v[80:83]
	v_mfma_f32_16x16x32_bf16 v[68:71], v[160:163], v[210:213], v[68:71]
	v_mfma_f32_16x16x32_bf16 v[68:71], v[164:167], v[214:217], v[68:71]
	v_mfma_f32_16x16x32_bf16 v[64:67], v[168:171], v[210:213], v[64:67]
	v_mfma_f32_16x16x32_bf16 v[64:67], v[180:183], v[214:217], v[64:67]
	s_setprio 0
	s_barrier
; #define PG8_STAGE(bufoff, gbase, voff) do { _Pragma("unroll") for (int _i = 0; _i < 2; ++_i) \
;         __builtin_amdgcn_global_load_lds((const unsigned*)((const char*)(gbase) + (voff)[_i]), (LAS unsigned*)(lds + (bufoff) + ldsw + _i * 8192), 16, 0, 0); } while (0)
; #define PG8_LDA(dst, b, h) do { _Pragma("unroll") for (int m = 0; m < 4; ++m) _Pragma("unroll") for (int k = 0; k < 2; ++k) dst[m][k] = *(const LAS bf16x8*)(lds + PG8_SA(b, h) + aoff + m * 2048 + k * 1024); } while (0)
; #define PG8_MMA(ai, bj, At, Bt) do { __builtin_amdgcn_s_setprio(1); _Pragma("unroll") for (int m = 0; m < 4; ++m) _Pragma("unroll") for (int n = 0; n < 2; ++n) _Pragma("unroll") for (int k = 0; k < 2; ++k) \
;         acc[ai][bj][m][n] = __builtin_amdgcn_mfma_f32_16x16x32_bf16(Bt[n][k], At[m][k], acc[ai][bj][m][n], 0, 0, 0); __builtin_amdgcn_s_setprio(0); } while (0)
; #define PG8_WAIT_V(n) asm volatile("s_waitcnt vmcnt(" #n ")" ::: "memory")
; #define PG8_WAIT_L(n) asm volatile("s_waitcnt lgkmcnt(" #n ")" ::: "memory")
; #define PG8_BAR __builtin_amdgcn_s_barrier()
; #define PG8_SCHED __builtin_amdgcn_sched_barrier(0)
; template <class Epi, bool ALIGN_EPI>
; __device__ __forceinline__ void gemm_phase(LAS unsigned char* lds, const Gemm g, const StaticOrder& S, const Epi& E) {
;     ...
;             PG8_LDA(At, 1, 1); PG8_STAGE(PG8_SB(1, 0), b3, voffB); PG8_STAGE(PG8_SB(1, 1), b3 + hB, voffB); PG8_STAGE(PG8_SA(1, 0), a3, voffA);
;             PG8_WAIT_V(8); PG8_WAIT_L(0); PG8_BAR; PG8_MMA(1, 0, At, B0); PG8_MMA(1, 1, At, B1); PG8_BAR; PG8_SCHED;
;         }
	s_add_i32 s42, s58, s33
	v_lshl_add_u64 v[218:219], v[218:219], 0, s[18:19]
	s_mov_b32 m0, s42
	ds_read_b128 v[184:187], v177 offset:49152
	ds_read_b128 v[188:191], v177 offset:50176
	ds_read_b128 v[194:197], v177 offset:51200
	ds_read_b128 v[198:201], v177 offset:52224
	ds_read_b128 v[202:205], v177 offset:53248
	ds_read_b128 v[206:209], v177 offset:54272
	ds_read_b128 v[210:213], v177 offset:55296
	ds_read_b128 v[214:217], v177 offset:56320
	global_load_lds_dwordx4 v[218:219], off
	s_add_i32 m0, s42, 0x2000
	s_add_u32 s40, s40, 0x80080
	v_lshl_add_u64 v[218:219], v[220:221], 0, s[18:19]
	s_addc_u32 s41, s41, 0
	s_add_i32 s42, s59, s33
	global_load_lds_dwordx4 v[218:219], off
	v_lshl_add_u64 v[218:219], s[40:41], 0, v[146:147]
	s_mov_b32 m0, s42
	s_nop 0
	global_load_lds_dwordx4 v[218:219], off
	v_lshl_add_u64 v[218:219], s[40:41], 0, v[150:151]
	s_add_i32 m0, s42, 0x2000
	s_nop 0
	global_load_lds_dwordx4 v[218:219], off
	v_lshl_add_u64 v[218:219], v[222:223], 0, s[18:19]
	s_mov_b32 m0, s48
	s_nop 0
	global_load_lds_dwordx4 v[218:219], off
	v_lshl_add_u64 v[218:219], v[224:225], 0, s[18:19]
	s_mov_b32 m0, s49
	s_nop 0
	global_load_lds_dwordx4 v[218:219], off
	s_waitcnt vmcnt(8)
	s_waitcnt lgkmcnt(0)
	s_barrier
	s_setprio 1
	s_waitcnt lgkmcnt(0)
	v_mfma_f32_16x16x32_bf16 v[60:63], v[128:131], v[184:187], v[60:63]
	v_mfma_f32_16x16x32_bf16 v[60:63], v[132:135], v[188:191], v[60:63]
	v_mfma_f32_16x16x32_bf16 v[56:59], v[136:139], v[184:187], v[56:59]
	v_mfma_f32_16x16x32_bf16 v[56:59], v[140:143], v[188:191], v[56:59]
	v_mfma_f32_16x16x32_bf16 v[44:47], v[128:131], v[194:197], v[44:47]
	v_mfma_f32_16x16x32_bf16 v[44:47], v[132:135], v[198:201], v[44:47]
	v_mfma_f32_16x16x32_bf16 v[40:43], v[136:139], v[194:197], v[40:43]
	v_mfma_f32_16x16x32_bf16 v[40:43], v[140:143], v[198:201], v[40:43]
	v_mfma_f32_16x16x32_bf16 v[28:31], v[128:131], v[202:205], v[28:31]
	v_mfma_f32_16x16x32_bf16 v[28:31], v[132:135], v[206:209], v[28:31]
	v_mfma_f32_16x16x32_bf16 v[24:27], v[136:139], v[202:205], v[24:27]
	v_mfma_f32_16x16x32_bf16 v[24:27], v[140:143], v[206:209], v[24:27]
	v_mfma_f32_16x16x32_bf16 v[12:15], v[128:131], v[210:213], v[12:15]
	v_mfma_f32_16x16x32_bf16 v[12:15], v[132:135], v[214:217], v[12:15]
	v_mfma_f32_16x16x32_bf16 v[8:11], v[136:139], v[210:213], v[8:11]
	v_mfma_f32_16x16x32_bf16 v[8:11], v[140:143], v[214:217], v[8:11]
	s_setprio 0
	s_setprio 1
	v_mfma_f32_16x16x32_bf16 v[52:55], v[160:163], v[184:187], v[52:55]
	v_mfma_f32_16x16x32_bf16 v[52:55], v[164:167], v[188:191], v[52:55]
	v_mfma_f32_16x16x32_bf16 v[48:51], v[168:171], v[184:187], v[48:51]
	v_mfma_f32_16x16x32_bf16 v[48:51], v[180:183], v[188:191], v[48:51]
	v_mfma_f32_16x16x32_bf16 v[36:39], v[160:163], v[194:197], v[36:39]
	v_mfma_f32_16x16x32_bf16 v[36:39], v[164:167], v[198:201], v[36:39]
	v_mfma_f32_16x16x32_bf16 v[32:35], v[168:171], v[194:197], v[32:35]
	v_mfma_f32_16x16x32_bf16 v[32:35], v[180:183], v[198:201], v[32:35]
	v_mfma_f32_16x16x32_bf16 v[20:23], v[160:163], v[202:205], v[20:23]
	v_mfma_f32_16x16x32_bf16 v[20:23], v[164:167], v[206:209], v[20:23]
	v_mfma_f32_16x16x32_bf16 v[16:19], v[168:171], v[202:205], v[16:19]
	v_mfma_f32_16x16x32_bf16 v[16:19], v[180:183], v[206:209], v[16:19]
	v_mfma_f32_16x16x32_bf16 v[4:7], v[160:163], v[210:213], v[4:7]
	v_mfma_f32_16x16x32_bf16 v[4:7], v[164:167], v[214:217], v[4:7]
	v_mfma_f32_16x16x32_bf16 v[0:3], v[168:171], v[210:213], v[0:3]
	v_mfma_f32_16x16x32_bf16 v[0:3], v[180:183], v[214:217], v[0:3]
	s_setprio 0
	s_barrier
	s_add_i32 s57, s57, 2
	s_add_u32 s36, s36, 0x100
	s_addc_u32 s37, s37, 0
	s_add_u32 s55, s55, 0x100
	s_addc_u32 s56, s56, 0
	s_cmp_gt_u32 s57, 29
	s_cbranch_scc0 .LBB0_1585
	s_and_b64 vcc, exec, s[20:21]
	s_cbranch_vccz .LBB0_1588
	s_barrier

; #define PG8_STAGE(bufoff, gbase, voff) do { _Pragma("unroll") for (int _i = 0; _i < 2; ++_i) \
;         __builtin_amdgcn_global_load_lds((const unsigned*)((const char*)(gbase) + (voff)[_i]), (LAS unsigned*)(lds + (bufoff) + ldsw + _i * 8192), 16, 0, 0); } while (0)
; #define PG8_LDA(dst, b, h) do { _Pragma("unroll") for (int m = 0; m < 4; ++m) _Pragma("unroll") for (int k = 0; k < 2; ++k) dst[m][k] = *(const LAS bf16x8*)(lds + PG8_SA(b, h) + aoff + m * 2048 + k * 1024); } while (0)
; #define PG8_LDB(dst, b, h) do { _Pragma("unroll") for (int n = 0; n < 2; ++n) _Pragma("unroll") for (int k = 0; k < 2; ++k) dst[n][k] = *(const LAS bf16x8*)(lds + PG8_SB(b, h) + boff + n * 2048 + k * 1024); } while (0)
; #define PG8_MMA(ai, bj, At, Bt) do { __builtin_amdgcn_s_setprio(1); _Pragma("unroll") for (int m = 0; m < 4; ++m) _Pragma("unroll") for (int n = 0; n < 2; ++n) _Pragma("unroll") for (int k = 0; k < 2; ++k) \
;         acc[ai][bj][m][n] = __builtin_amdgcn_mfma_f32_16x16x32_bf16(Bt[n][k], At[m][k], acc[ai][bj][m][n], 0, 0, 0); __builtin_amdgcn_s_setprio(0); } while (0)
; #define PG8_WAIT_V(n) asm volatile("s_waitcnt vmcnt(" #n ")" ::: "memory")
; #define PG8_WAIT_L(n) asm volatile("s_waitcnt lgkmcnt(" #n ")" ::: "memory")
; #define PG8_BAR __builtin_amdgcn_s_barrier()
; #define PG8_SCHED __builtin_amdgcn_sched_barrier(0)
; template <class Epi, bool ALIGN_EPI>
; __device__ __forceinline__ void gemm_phase(LAS unsigned char* lds, const Gemm g, const StaticOrder& S, const Epi& E) {
;     ...
;         for (int t = 0; t < nt; t += 2) {
;             const bool last = (t == nt - 2);
;             const char* a1 = cA + (size_t)(t + 1) * kstep;
;             const char* a2 = last ? nA : cA + (size_t)(t + 2) * kstep; const char* b2 = last ? nB : cB + (size_t)(t + 2) * kstep;
;             const char* a3 = a2 + kstep; const char* b3 = b2 + kstep;
;             PG8_LDB(B0, 0, 0); PG8_LDB(B1, 0, 1); PG8_SCHED; PG8_LDA(At, 0, 0); PG8_STAGE(PG8_SA(1, 1), a1 + hA, voffA);
;             PG8_WAIT_V(8); PG8_WAIT_L(0); PG8_BAR; PG8_MMA(0, 0, At, B0); PG8_MMA(0, 1, At, B1); PG8_BAR; PG8_SCHED;
;             PG8_LDA(At, 0, 1); PG8_STAGE(PG8_SB(0, 0), b2, voffB); PG8_STAGE(PG8_SB(0, 1), b2 + hB, voffB); PG8_STAGE(PG8_SA(0, 0), a2, voffA);
;             PG8_WAIT_V(8); PG8_WAIT_L(0); PG8_BAR; PG8_MMA(1, 0, At, B0); PG8_MMA(1, 1, At, B1); PG8_BAR; PG8_SCHED;
.LBB0_1755:
	ds_read_b128 v[128:131], v183
	ds_read_b128 v[132:135], v183 offset:1024
	ds_read_b128 v[152:155], v183 offset:2048
	ds_read_b128 v[156:159], v183 offset:3072
	ds_read_b128 v[160:163], v184
	ds_read_b128 v[164:167], v184 offset:1024
	ds_read_b128 v[168:171], v184 offset:2048
	ds_read_b128 v[172:175], v184 offset:3072
	s_add_u32 s30, s28, 0xffe00080
	s_addc_u32 s31, s29, -1
	s_cmpk_eq_i32 s51, 0x7c
	s_cselect_b32 s35, s5, s31
	s_cselect_b32 s34, s21, s30
	s_cselect_b32 s31, s19, s50
	s_cselect_b32 s30, s48, s49
	v_lshl_add_u64 v[214:215], s[28:29], 0, v[144:145]
	s_add_i32 m0, s27, 0xc000
	ds_read_b128 v[176:179], v185
	ds_read_b128 v[186:189], v185 offset:1024
	ds_read_b128 v[190:193], v185 offset:2048
	ds_read_b128 v[194:197], v185 offset:3072
	ds_read_b128 v[198:201], v185 offset:4096
	ds_read_b128 v[202:205], v185 offset:5120
	ds_read_b128 v[206:209], v185 offset:6144
	ds_read_b128 v[210:213], v185 offset:7168
	global_load_lds_dwordx4 v[214:215], off
	v_lshl_add_u64 v[214:215], s[28:29], 0, v[146:147]
	s_add_i32 m0, s27, 0xe000
	s_nop 0
	global_load_lds_dwordx4 v[214:215], off
	s_waitcnt vmcnt(8)
	s_waitcnt lgkmcnt(0)
	s_barrier
	s_setprio 1
	s_waitcnt lgkmcnt(0)
	v_mfma_f32_16x16x32_bf16 v[120:123], v[128:131], v[176:179], v[120:123]
	v_mfma_f32_16x16x32_bf16 v[120:123], v[132:135], v[186:189], v[120:123]
	v_mfma_f32_16x16x32_bf16 v[124:127], v[152:155], v[176:179], v[124:127]
	v_mfma_f32_16x16x32_bf16 v[124:127], v[156:159], v[186:189], v[124:127]
	v_mfma_f32_16x16x32_bf16 v[104:107], v[128:131], v[190:193], v[104:107]
	v_mfma_f32_16x16x32_bf16 v[104:107], v[132:135], v[194:197], v[104:107]
	v_mfma_f32_16x16x32_bf16 v[108:111], v[152:155], v[190:193], v[108:111]
	v_mfma_f32_16x16x32_bf16 v[108:111], v[156:159], v[194:197], v[108:111]
	v_mfma_f32_16x16x32_bf16 v[88:91], v[128:131], v[198:201], v[88:91]
	v_mfma_f32_16x16x32_bf16 v[88:91], v[132:135], v[202:205], v[88:91]
	v_mfma_f32_16x16x32_bf16 v[92:95], v[152:155], v[198:201], v[92:95]
	v_mfma_f32_16x16x32_bf16 v[92:95], v[156:159], v[202:205], v[92:95]
	v_mfma_f32_16x16x32_bf16 v[72:75], v[128:131], v[206:209], v[72:75]
	v_mfma_f32_16x16x32_bf16 v[72:75], v[132:135], v[210:213], v[72:75]
	v_mfma_f32_16x16x32_bf16 v[76:79], v[152:155], v[206:209], v[76:79]
	v_mfma_f32_16x16x32_bf16 v[76:79], v[156:159], v[210:213], v[76:79]
	s_setprio 0
	s_setprio 1
	v_mfma_f32_16x16x32_bf16 v[112:115], v[160:163], v[176:179], v[112:115]
	v_mfma_f32_16x16x32_bf16 v[112:115], v[164:167], v[186:189], v[112:115]
	v_mfma_f32_16x16x32_bf16 v[116:119], v[168:171], v[176:179], v[116:119]
	v_mfma_f32_16x16x32_bf16 v[116:119], v[172:175], v[186:189], v[116:119]
	v_mfma_f32_16x16x32_bf16 v[96:99], v[160:163], v[190:193], v[96:99]
	v_mfma_f32_16x16x32_bf16 v[96:99], v[164:167], v[194:197], v[96:99]
	v_mfma_f32_16x16x32_bf16 v[100:103], v[168:171], v[190:193], v[100:103]
	v_mfma_f32_16x16x32_bf16 v[100:103], v[172:175], v[194:197], v[100:103]
	v_mfma_f32_16x16x32_bf16 v[80:83], v[160:163], v[198:201], v[80:83]
	v_mfma_f32_16x16x32_bf16 v[80:83], v[164:167], v[202:205], v[80:83]
	v_mfma_f32_16x16x32_bf16 v[84:87], v[168:171], v[198:201], v[84:87]
	v_mfma_f32_16x16x32_bf16 v[84:87], v[172:175], v[202:205], v[84:87]
	v_mfma_f32_16x16x32_bf16 v[64:67], v[160:163], v[206:209], v[64:67]
	v_mfma_f32_16x16x32_bf16 v[64:67], v[164:167], v[210:213], v[64:67]
	v_mfma_f32_16x16x32_bf16 v[68:71], v[168:171], v[206:209], v[68:71]
	v_mfma_f32_16x16x32_bf16 v[68:71], v[172:175], v[210:213], v[68:71]
	s_setprio 0
	s_barrier
	s_add_i32 s52, s46, s37
	v_lshl_add_u64 v[214:215], s[30:31], 0, v[138:139]
	s_mov_b32 m0, s52
	ds_read_b128 v[176:179], v185 offset:16384
	ds_read_b128 v[186:189], v185 offset:17408
	ds_read_b128 v[190:193], v185 offset:18432
	ds_read_b128 v[194:197], v185 offset:19456
	ds_read_b128 v[198:201], v185 offset:20480
	ds_read_b128 v[202:205], v185 offset:21504
	ds_read_b128 v[206:209], v185 offset:22528
	ds_read_b128 v[210:213], v185 offset:23552
	global_load_lds_dwordx4 v[214:215], off
	s_add_i32 m0, s52, 0x2000
	s_add_u32 s52, s30, 0x200000
	v_lshl_add_u64 v[216:217], s[30:31], 0, v[142:143]
	s_addc_u32 s53, s31, 0
	s_add_i32 s54, s47, s37
	global_load_lds_dwordx4 v[216:217], off
	v_lshl_add_u64 v[218:219], s[52:53], 0, v[138:139]
	s_mov_b32 m0, s54
	v_lshl_add_u64 v[220:221], s[34:35], 0, v[140:141]
	global_load_lds_dwordx4 v[218:219], off
	v_lshl_add_u64 v[218:219], s[52:53], 0, v[142:143]
	s_add_i32 m0, s54, 0x2000
	s_nop 0
	global_load_lds_dwordx4 v[218:219], off
	v_lshl_add_u64 v[218:219], s[34:35], 0, v[136:137]
	s_mov_b32 m0, s27
	s_nop 0
	global_load_lds_dwordx4 v[218:219], off
	s_mov_b32 m0, s38
	s_nop 0
	global_load_lds_dwordx4 v[220:221], off
	s_waitcnt vmcnt(8)
	s_waitcnt lgkmcnt(0)
	s_barrier
; #define PG8_STAGE(bufoff, gbase, voff) do { _Pragma("unroll") for (int _i = 0; _i < 2; ++_i) \
;         __builtin_amdgcn_global_load_lds((const unsigned*)((const char*)(gbase) + (voff)[_i]), (LAS unsigned*)(lds + (bufoff) + ldsw + _i * 8192), 16, 0, 0); } while (0)
; #define PG8_LDA(dst, b, h) do { _Pragma("unroll") for (int m = 0; m < 4; ++m) _Pragma("unroll") for (int k = 0; k < 2; ++k) dst[m][k] = *(const LAS bf16x8*)(lds + PG8_SA(b, h) + aoff + m * 2048 + k * 1024); } while (0)
; #define PG8_LDB(dst, b, h) do { _Pragma("unroll") for (int n = 0; n < 2; ++n) _Pragma("unroll") for (int k = 0; k < 2; ++k) dst[n][k] = *(const LAS bf16x8*)(lds + PG8_SB(b, h) + boff + n * 2048 + k * 1024); } while (0)
; #define PG8_MMA(ai, bj, At, Bt) do { __builtin_amdgcn_s_setprio(1); _Pragma("unroll") for (int m = 0; m < 4; ++m) _Pragma("unroll") for (int n = 0; n < 2; ++n) _Pragma("unroll") for (int k = 0; k < 2; ++k) \
;         acc[ai][bj][m][n] = __builtin_amdgcn_mfma_f32_16x16x32_bf16(Bt[n][k], At[m][k], acc[ai][bj][m][n], 0, 0, 0); __builtin_amdgcn_s_setprio(0); } while (0)
; #define PG8_WAIT_V(n) asm volatile("s_waitcnt vmcnt(" #n ")" ::: "memory")
; #define PG8_WAIT_L(n) asm volatile("s_waitcnt lgkmcnt(" #n ")" ::: "memory")
; #define PG8_BAR __builtin_amdgcn_s_barrier()
; #define PG8_SCHED __builtin_amdgcn_sched_barrier(0)
; template <class Epi, bool ALIGN_EPI>
; __device__ __forceinline__ void gemm_phase(LAS unsigned char* lds, const Gemm g, const StaticOrder& S, const Epi& E) {
;     ...
;             PG8_WAIT_V(8); PG8_WAIT_L(0); PG8_BAR; PG8_MMA(1, 0, At, B0); PG8_MMA(1, 1, At, B1); PG8_BAR; PG8_SCHED;
;             PG8_LDB(B0, 1, 0); PG8_LDB(B1, 1, 1); PG8_SCHED; PG8_LDA(At, 1, 0); PG8_STAGE(PG8_SA(0, 1), a2 + hA, voffA);
;             PG8_WAIT_V(8); PG8_WAIT_L(0); PG8_BAR; PG8_MMA(0, 0, At, B0); PG8_MMA(0, 1, At, B1); PG8_BAR; PG8_SCHED;
	s_setprio 1
	s_waitcnt lgkmcnt(0)
	v_mfma_f32_16x16x32_bf16 v[56:59], v[128:131], v[176:179], v[56:59]
	v_mfma_f32_16x16x32_bf16 v[56:59], v[132:135], v[186:189], v[56:59]
	v_mfma_f32_16x16x32_bf16 v[60:63], v[152:155], v[176:179], v[60:63]
	v_mfma_f32_16x16x32_bf16 v[60:63], v[156:159], v[186:189], v[60:63]
	v_mfma_f32_16x16x32_bf16 v[40:43], v[128:131], v[190:193], v[40:43]
	v_mfma_f32_16x16x32_bf16 v[40:43], v[132:135], v[194:197], v[40:43]
	v_mfma_f32_16x16x32_bf16 v[44:47], v[152:155], v[190:193], v[44:47]
	v_mfma_f32_16x16x32_bf16 v[44:47], v[156:159], v[194:197], v[44:47]
	v_mfma_f32_16x16x32_bf16 v[24:27], v[128:131], v[198:201], v[24:27]
	v_mfma_f32_16x16x32_bf16 v[24:27], v[132:135], v[202:205], v[24:27]
	v_mfma_f32_16x16x32_bf16 v[28:31], v[152:155], v[198:201], v[28:31]
	v_mfma_f32_16x16x32_bf16 v[28:31], v[156:159], v[202:205], v[28:31]
	v_mfma_f32_16x16x32_bf16 v[8:11], v[128:131], v[206:209], v[8:11]
	v_mfma_f32_16x16x32_bf16 v[8:11], v[132:135], v[210:213], v[8:11]
	v_mfma_f32_16x16x32_bf16 v[12:15], v[152:155], v[206:209], v[12:15]
	v_mfma_f32_16x16x32_bf16 v[12:15], v[156:159], v[210:213], v[12:15]
	s_setprio 0
	s_setprio 1
	v_mfma_f32_16x16x32_bf16 v[48:51], v[160:163], v[176:179], v[48:51]
	v_mfma_f32_16x16x32_bf16 v[48:51], v[164:167], v[186:189], v[48:51]
	v_mfma_f32_16x16x32_bf16 v[52:55], v[168:171], v[176:179], v[52:55]
	v_mfma_f32_16x16x32_bf16 v[52:55], v[172:175], v[186:189], v[52:55]
	v_mfma_f32_16x16x32_bf16 v[32:35], v[160:163], v[190:193], v[32:35]
	v_mfma_f32_16x16x32_bf16 v[32:35], v[164:167], v[194:197], v[32:35]
	v_mfma_f32_16x16x32_bf16 v[36:39], v[168:171], v[190:193], v[36:39]
	v_mfma_f32_16x16x32_bf16 v[36:39], v[172:175], v[194:197], v[36:39]
	v_mfma_f32_16x16x32_bf16 v[16:19], v[160:163], v[198:201], v[16:19]
	v_mfma_f32_16x16x32_bf16 v[16:19], v[164:167], v[202:205], v[16:19]
	v_mfma_f32_16x16x32_bf16 v[20:23], v[168:171], v[198:201], v[20:23]
	v_mfma_f32_16x16x32_bf16 v[20:23], v[172:175], v[202:205], v[20:23]
	v_mfma_f32_16x16x32_bf16 v[4:7], v[160:163], v[206:209], v[4:7]
	v_mfma_f32_16x16x32_bf16 v[4:7], v[164:167], v[210:213], v[4:7]
	v_mfma_f32_16x16x32_bf16 v[0:3], v[168:171], v[206:209], v[0:3]
	v_mfma_f32_16x16x32_bf16 v[0:3], v[172:175], v[210:213], v[0:3]
	s_setprio 0
	s_barrier
	s_add_i32 s52, 0, 0x18000
	s_add_i32 s53, 0, 0x1c000
	v_add_u32_e32 v156, s52, v181
	v_add_u32_e32 v172, s53, v181
	ds_read_b128 v[128:131], v156
	ds_read_b128 v[132:135], v156 offset:1024
	ds_read_b128 v[152:155], v156 offset:2048
	ds_read_b128 v[156:159], v156 offset:3072
	ds_read_b128 v[160:163], v172
	ds_read_b128 v[164:167], v172 offset:1024
	ds_read_b128 v[168:171], v172 offset:2048
	ds_read_b128 v[172:175], v172 offset:3072
	s_add_u32 s34, s34, 0x200000
	s_addc_u32 s35, s35, 0
	s_mov_b32 m0, s39
	v_lshl_add_u64 v[222:223], s[34:35], 0, v[136:137]
	ds_read_b128 v[176:179], v185 offset:32768
	ds_read_b128 v[186:189], v185 offset:33792
	ds_read_b128 v[190:193], v185 offset:34816
	ds_read_b128 v[194:197], v185 offset:35840
	ds_read_b128 v[198:201], v185 offset:36864
	ds_read_b128 v[202:205], v185 offset:37888
	ds_read_b128 v[206:209], v185 offset:38912
	ds_read_b128 v[210:213], v185 offset:39936
	global_load_lds_dwordx4 v[222:223], off
	v_lshl_add_u64 v[222:223], s[34:35], 0, v[140:141]
	s_mov_b32 m0, s40
	s_nop 0
	global_load_lds_dwordx4 v[222:223], off
	s_waitcnt vmcnt(8)
	s_waitcnt lgkmcnt(0)
	s_barrier
	s_setprio 1
	s_waitcnt lgkmcnt(0)
	v_mfma_f32_16x16x32_bf16 v[120:123], v[128:131], v[176:179], v[120:123]
	v_mfma_f32_16x16x32_bf16 v[120:123], v[132:135], v[186:189], v[120:123]
	v_mfma_f32_16x16x32_bf16 v[124:127], v[152:155], v[176:179], v[124:127]
	v_mfma_f32_16x16x32_bf16 v[124:127], v[156:159], v[186:189], v[124:127]
	v_mfma_f32_16x16x32_bf16 v[104:107], v[128:131], v[190:193], v[104:107]
	v_mfma_f32_16x16x32_bf16 v[104:107], v[132:135], v[194:197], v[104:107]
	v_mfma_f32_16x16x32_bf16 v[108:111], v[152:155], v[190:193], v[108:111]
	v_mfma_f32_16x16x32_bf16 v[108:111], v[156:159], v[194:197], v[108:111]
	v_mfma_f32_16x16x32_bf16 v[88:91], v[128:131], v[198:201], v[88:91]
	v_mfma_f32_16x16x32_bf16 v[88:91], v[132:135], v[202:205], v[88:91]
	v_mfma_f32_16x16x32_bf16 v[92:95], v[152:155], v[198:201], v[92:95]
	v_mfma_f32_16x16x32_bf16 v[92:95], v[156:159], v[202:205], v[92:95]
	v_mfma_f32_16x16x32_bf16 v[72:75], v[128:131], v[206:209], v[72:75]
	v_mfma_f32_16x16x32_bf16 v[72:75], v[132:135], v[210:213], v[72:75]
	v_mfma_f32_16x16x32_bf16 v[76:79], v[152:155], v[206:209], v[76:79]
	v_mfma_f32_16x16x32_bf16 v[76:79], v[156:159], v[210:213], v[76:79]
	s_setprio 0
	s_setprio 1
	v_mfma_f32_16x16x32_bf16 v[112:115], v[160:163], v[176:179], v[112:115]
	v_mfma_f32_16x16x32_bf16 v[112:115], v[164:167], v[186:189], v[112:115]
	v_mfma_f32_16x16x32_bf16 v[116:119], v[168:171], v[176:179], v[116:119]
	v_mfma_f32_16x16x32_bf16 v[116:119], v[172:175], v[186:189], v[116:119]
	v_mfma_f32_16x16x32_bf16 v[96:99], v[160:163], v[190:193], v[96:99]
	v_mfma_f32_16x16x32_bf16 v[96:99], v[164:167], v[194:197], v[96:99]
	v_mfma_f32_16x16x32_bf16 v[100:103], v[168:171], v[190:193], v[100:103]
	v_mfma_f32_16x16x32_bf16 v[100:103], v[172:175], v[194:197], v[100:103]
	v_mfma_f32_16x16x32_bf16 v[80:83], v[160:163], v[198:201], v[80:83]
	v_mfma_f32_16x16x32_bf16 v[80:83], v[164:167], v[202:205], v[80:83]
	v_mfma_f32_16x16x32_bf16 v[84:87], v[168:171], v[198:201], v[84:87]
	v_mfma_f32_16x16x32_bf16 v[84:87], v[172:175], v[202:205], v[84:87]
	v_mfma_f32_16x16x32_bf16 v[64:67], v[160:163], v[206:209], v[64:67]
	v_mfma_f32_16x16x32_bf16 v[64:67], v[164:167], v[210:213], v[64:67]
	v_mfma_f32_16x16x32_bf16 v[68:71], v[168:171], v[206:209], v[68:71]
	v_mfma_f32_16x16x32_bf16 v[68:71], v[172:175], v[210:213], v[68:71]
	s_setprio 0
	s_barrier
; #define PG8_STAGE(bufoff, gbase, voff) do { _Pragma("unroll") for (int _i = 0; _i < 2; ++_i) \
;         __builtin_amdgcn_global_load_lds((const unsigned*)((const char*)(gbase) + (voff)[_i]), (LAS unsigned*)(lds + (bufoff) + ldsw + _i * 8192), 16, 0, 0); } while (0)
; #define PG8_LDA(dst, b, h) do { _Pragma("unroll") for (int m = 0; m < 4; ++m) _Pragma("unroll") for (int k = 0; k < 2; ++k) dst[m][k] = *(const LAS bf16x8*)(lds + PG8_SA(b, h) + aoff + m * 2048 + k * 1024); } while (0)
; #define PG8_MMA(ai, bj, At, Bt) do { __builtin_amdgcn_s_setprio(1); _Pragma("unroll") for (int m = 0; m < 4; ++m) _Pragma("unroll") for (int n = 0; n < 2; ++n) _Pragma("unroll") for (int k = 0; k < 2; ++k) \
;         acc[ai][bj][m][n] = __builtin_amdgcn_mfma_f32_16x16x32_bf16(Bt[n][k], At[m][k], acc[ai][bj][m][n], 0, 0, 0); __builtin_amdgcn_s_setprio(0); } while (0)
; #define PG8_WAIT_V(n) asm volatile("s_waitcnt vmcnt(" #n ")" ::: "memory")
; #define PG8_WAIT_L(n) asm volatile("s_waitcnt lgkmcnt(" #n ")" ::: "memory")
; #define PG8_BAR __builtin_amdgcn_s_barrier()
; #define PG8_SCHED __builtin_amdgcn_sched_barrier(0)
; template <class Epi, bool ALIGN_EPI>
; __device__ __forceinline__ void gemm_phase(LAS unsigned char* lds, const Gemm g, const StaticOrder& S, const Epi& E) {
;     ...
;             PG8_LDA(At, 1, 1); PG8_STAGE(PG8_SB(1, 0), b3, voffB); PG8_STAGE(PG8_SB(1, 1), b3 + hB, voffB); PG8_STAGE(PG8_SA(1, 0), a3, voffA);
;             PG8_WAIT_V(8); PG8_WAIT_L(0); PG8_BAR; PG8_MMA(1, 0, At, B0); PG8_MMA(1, 1, At, B1); PG8_BAR; PG8_SCHED;
;         }
	s_add_i32 s34, s52, s37
	v_lshl_add_u64 v[214:215], v[214:215], 0, s[12:13]
	s_mov_b32 m0, s34
	ds_read_b128 v[176:179], v185 offset:49152
	ds_read_b128 v[186:189], v185 offset:50176
	ds_read_b128 v[190:193], v185 offset:51200
	ds_read_b128 v[194:197], v185 offset:52224
	ds_read_b128 v[198:201], v185 offset:53248
	ds_read_b128 v[202:205], v185 offset:54272
	ds_read_b128 v[206:209], v185 offset:55296
	ds_read_b128 v[210:213], v185 offset:56320
	global_load_lds_dwordx4 v[214:215], off
	s_add_i32 m0, s34, 0x2000
	s_add_u32 s30, s30, 0x200080
	v_lshl_add_u64 v[214:215], v[216:217], 0, s[12:13]
	s_addc_u32 s31, s31, 0
	s_add_i32 s34, s53, s37
	global_load_lds_dwordx4 v[214:215], off
	v_lshl_add_u64 v[214:215], s[30:31], 0, v[138:139]
	s_mov_b32 m0, s34
	s_nop 0
	global_load_lds_dwordx4 v[214:215], off
	v_lshl_add_u64 v[214:215], s[30:31], 0, v[142:143]
	s_add_i32 m0, s34, 0x2000
	s_nop 0
	global_load_lds_dwordx4 v[214:215], off
	v_lshl_add_u64 v[214:215], v[218:219], 0, s[12:13]
	s_mov_b32 m0, s44
	s_nop 0
	global_load_lds_dwordx4 v[214:215], off
	v_lshl_add_u64 v[214:215], v[220:221], 0, s[12:13]
	s_mov_b32 m0, s45
	s_nop 0
	global_load_lds_dwordx4 v[214:215], off
	s_waitcnt vmcnt(8)
	s_waitcnt lgkmcnt(0)
	s_barrier
	s_setprio 1
	s_waitcnt lgkmcnt(0)
	v_mfma_f32_16x16x32_bf16 v[56:59], v[128:131], v[176:179], v[56:59]
	v_mfma_f32_16x16x32_bf16 v[56:59], v[132:135], v[186:189], v[56:59]
	v_mfma_f32_16x16x32_bf16 v[60:63], v[152:155], v[176:179], v[60:63]
	v_mfma_f32_16x16x32_bf16 v[60:63], v[156:159], v[186:189], v[60:63]
	v_mfma_f32_16x16x32_bf16 v[40:43], v[128:131], v[190:193], v[40:43]
	v_mfma_f32_16x16x32_bf16 v[40:43], v[132:135], v[194:197], v[40:43]
	v_mfma_f32_16x16x32_bf16 v[44:47], v[152:155], v[190:193], v[44:47]
	v_mfma_f32_16x16x32_bf16 v[44:47], v[156:159], v[194:197], v[44:47]
	v_mfma_f32_16x16x32_bf16 v[24:27], v[128:131], v[198:201], v[24:27]
	v_mfma_f32_16x16x32_bf16 v[24:27], v[132:135], v[202:205], v[24:27]
	v_mfma_f32_16x16x32_bf16 v[28:31], v[152:155], v[198:201], v[28:31]
	v_mfma_f32_16x16x32_bf16 v[28:31], v[156:159], v[202:205], v[28:31]
	v_mfma_f32_16x16x32_bf16 v[8:11], v[128:131], v[206:209], v[8:11]
	v_mfma_f32_16x16x32_bf16 v[8:11], v[132:135], v[210:213], v[8:11]
	v_mfma_f32_16x16x32_bf16 v[12:15], v[152:155], v[206:209], v[12:15]
	v_mfma_f32_16x16x32_bf16 v[12:15], v[156:159], v[210:213], v[12:15]
	s_setprio 0
	s_setprio 1
	v_mfma_f32_16x16x32_bf16 v[48:51], v[160:163], v[176:179], v[48:51]
	v_mfma_f32_16x16x32_bf16 v[48:51], v[164:167], v[186:189], v[48:51]
	v_mfma_f32_16x16x32_bf16 v[52:55], v[168:171], v[176:179], v[52:55]
	v_mfma_f32_16x16x32_bf16 v[52:55], v[172:175], v[186:189], v[52:55]
	v_mfma_f32_16x16x32_bf16 v[32:35], v[160:163], v[190:193], v[32:35]
	v_mfma_f32_16x16x32_bf16 v[32:35], v[164:167], v[194:197], v[32:35]
	v_mfma_f32_16x16x32_bf16 v[36:39], v[168:171], v[190:193], v[36:39]
	v_mfma_f32_16x16x32_bf16 v[36:39], v[172:175], v[194:197], v[36:39]
	v_mfma_f32_16x16x32_bf16 v[16:19], v[160:163], v[198:201], v[16:19]
	v_mfma_f32_16x16x32_bf16 v[16:19], v[164:167], v[202:205], v[16:19]
	v_mfma_f32_16x16x32_bf16 v[20:23], v[168:171], v[198:201], v[20:23]
	v_mfma_f32_16x16x32_bf16 v[20:23], v[172:175], v[202:205], v[20:23]
	v_mfma_f32_16x16x32_bf16 v[4:7], v[160:163], v[206:209], v[4:7]
	v_mfma_f32_16x16x32_bf16 v[4:7], v[164:167], v[210:213], v[4:7]
	v_mfma_f32_16x16x32_bf16 v[0:3], v[168:171], v[206:209], v[0:3]
	v_mfma_f32_16x16x32_bf16 v[0:3], v[172:175], v[210:213], v[0:3]
	s_setprio 0
	s_barrier
	s_add_i32 s51, s51, 2
	s_add_u32 s28, s28, 0x100
	s_addc_u32 s29, s29, 0
	s_add_u32 s49, s49, 0x100
	s_addc_u32 s50, s50, 0
	s_cmpk_gt_u32 s51, 0x7d
	s_cbranch_scc0 .LBB0_1755
	s_and_b64 vcc, exec, s[14:15]
	s_cbranch_vccz .LBB0_1758
	s_barrier
